# v_cvt_pk_bf16_f32 replaces bit-trick packing; removed chain instrs deleted where no hazard window nearby (else s_nop 0)
# baseline (speedup 1.0000x reference)
; #define LAS __attribute__((address_space(3)))
; __device__ __forceinline__ unsigned pk2(float lo, float hi) { return f2bf(lo) | (f2bf(hi) << 16); }
; __device__ __forceinline__ void phase_prep(const Args& A, const Ctx& C0, int l) {
;     ...
;     bf16x8 wfr[2][4][2];
;     { const int fr = C.lane & 15, fq = C.lane >> 4;
; #pragma unroll
;       for (int mat = 0; mat < 2; ++mat) { const float* W = A.in[mat ? I_AUP : I_WUP] + (size_t)l * 64 * 512 + head * 64 + fr;
; #pragma unroll
;           for (int ct = 0; ct < 4; ++ct)
; #pragma unroll
;               for (int ks = 0; ks < 2; ++ks) { const float* p = W + (size_t)(ks * 32 + 8 * fq) * 512 + ct * 16;
;                   union { bf16x8 v; unsigned w[4]; } f;
; #pragma unroll
;                   for (int e = 0; e < 4; ++e) f.w[e] = pk2(p[(2 * e) * 512], p[(2 * e + 1) * 512]);
;                   wfr[mat][ct][ks] = f.v; } } }
;     LAS bf16* lob = (LAS bf16*)(C.lds + 9 * DSH * 4);
;     LAS float* outw = (LAS float*)(C.lds + 9 * DSH * 4 + 16 * 136 * 2);
;     LAS float* outa = outw + 8 * 512;
;     const float w0 = A.in[I_W0][l * 512 + c], a0 = A.in[I_A0][l * 512 + c], kkc = A.in[I_KK][l * 512 + c], kac = A.in[I_KA][l * 512 + c], rkc = A.in[I_RK][l * 512 + c];
;     const float* mul = A.in[I_MU] + (size_t)l * DSH;
;     const float mu_r = mul[c], mu_k = mul[512 + c], mu_v = mul[1024 + c];
;     v4u px[4];
;     ...
;     if (C.bid < M / 8) PREP_FETCH(C.bid);
.LBB0_43:
	v_and_b32_e32 v166, 63, v94
	s_andn2_b64 vcc, exec, s[40:41]
	s_cbranch_vccnz .LBB0_116
	s_waitcnt vmcnt(0)
	s_nop 0
	s_nop 0
	s_nop 0
	s_nop 0
	s_nop 0
	v_cvt_pk_bf16_f32 v18, v19, v18
	s_nop 0
	s_nop 0
	s_nop 0
	s_nop 0
	s_nop 0
	v_cvt_pk_bf16_f32 v19, v159, v20
	s_nop 0
	s_nop 0
	s_nop 0
	s_nop 0
	v_cvt_pk_bf16_f32 v20, v158, v22
	v_cvt_pk_bf16_f32 v21, v21, v164
	v_cvt_pk_bf16_f32 v22, v161, v162
	v_cvt_pk_bf16_f32 v23, v23, v165
	v_cvt_pk_bf16_f32 v24, v25, v24
	v_cvt_pk_bf16_f32 v25, v160, v163
	v_cvt_pk_bf16_f32 v26, v27, v26
	v_cvt_pk_bf16_f32 v27, v29, v28
	v_cvt_pk_bf16_f32 v28, v31, v30
	v_cvt_pk_bf16_f32 v29, v157, v156
	v_cvt_pk_bf16_f32 v30, v154, v153
	v_cvt_pk_bf16_f32 v31, v151, v155
	v_cvt_pk_bf16_f32 v32, v33, v32
	v_cvt_pk_bf16_f32 v33, v150, v152
	v_cvt_pk_bf16_f32 v34, v35, v34
	v_cvt_pk_bf16_f32 v35, v37, v36
	v_cvt_pk_bf16_f32 v36, v39, v38
	v_cvt_pk_bf16_f32 v37, v133, v129
	v_cvt_pk_bf16_f32 v38, v130, v127
	v_cvt_pk_bf16_f32 v39, v134, v131
	v_cvt_pk_bf16_f32 v40, v40, v126
	v_cvt_pk_bf16_f32 v41, v128, v41
	v_cvt_pk_bf16_f32 v42, v44, v42
	v_cvt_pk_bf16_f32 v43, v45, v43
	v_cvt_pk_bf16_f32 v44, v46, v51
	v_cvt_pk_bf16_f32 v45, v56, v52
	v_cvt_pk_bf16_f32 v46, v55, v47
	v_cvt_pk_bf16_f32 v47, v57, v53
	v_cvt_pk_bf16_f32 v48, v48, v49
	v_cvt_pk_bf16_f32 v49, v54, v50
	v_cvt_pk_bf16_f32 v50, v124, v112
	v_cvt_pk_bf16_f32 v51, v141, v138
	v_cvt_pk_bf16_f32 v52, v140, v139
	v_cvt_pk_bf16_f32 v53, v136, v148
	v_cvt_pk_bf16_f32 v54, v145, v146
	v_cvt_pk_bf16_f32 v55, v137, v149
	v_cvt_pk_bf16_f32 v56, v135, v132
	v_cvt_pk_bf16_f32 v57, v144, v147
	v_cvt_pk_bf16_f32 v58, v59, v58
	v_cvt_pk_bf16_f32 v59, v61, v60
	v_cvt_pk_bf16_f32 v60, v63, v62
	v_cvt_pk_bf16_f32 v61, v125, v115
	v_cvt_pk_bf16_f32 v62, v113, v111
	v_cvt_pk_bf16_f32 v63, v109, v114
	v_cvt_pk_bf16_f32 v64, v65, v64
	v_cvt_pk_bf16_f32 v65, v108, v110
	v_cvt_pk_bf16_f32 v66, v67, v66
	v_cvt_pk_bf16_f32 v67, v69, v68
	v_cvt_pk_bf16_f32 v68, v71, v70
	v_cvt_pk_bf16_f32 v69, v106, v103
	v_cvt_pk_bf16_f32 v70, v104, v96
	v_cvt_pk_bf16_f32 v71, v107, v105
	v_cvt_pk_bf16_f32 v72, v72, v93
	v_cvt_pk_bf16_f32 v73, v102, v73
	v_cvt_pk_bf16_f32 v74, v76, v74
	v_cvt_pk_bf16_f32 v75, v77, v75
	v_cvt_pk_bf16_f32 v76, v78, v86
	v_cvt_pk_bf16_f32 v77, v91, v87
	v_cvt_pk_bf16_f32 v78, v90, v79
	v_cvt_pk_bf16_f32 v79, v92, v88
	v_cvt_pk_bf16_f32 v80, v80, v81
	s_mov_b32 s11, 0x4ec4ec4f
	s_ashr_i32 s1, s9, 6
	v_mul_hi_i32 v92, v84, s11
	s_add_u32 s9, s42, 0x7984000
	s_mul_i32 s2, s1, 0x180
	v_lshrrev_b32_e32 v93, 31, v92
	v_ashrrev_i32_e32 v92, 6, v92
	v_cvt_pk_bf16_f32 v81, v89, v85
	s_addc_u32 s15, s43, 0
	v_and_b32_e32 v85, 0x7f, v94
	s_ashr_i32 s3, s2, 31
	v_add_u32_e32 v126, v92, v93
	v_add_u32_e32 v93, 0x600, v94
	v_lshlrev_b32_e32 v88, 2, v85
	s_lshl_b64 s[2:3], s[2:3], 2
	v_mul_hi_i32 v96, v93, s11
	v_or_b32_e32 v86, 0x1800, v88
	v_mov_b32_e32 v87, v1
	s_movk_i32 s13, 0x110
	s_add_u32 s2, s42, s2
	v_lshrrev_b32_e32 v112, 31, v96
	v_ashrrev_i32_e32 v96, 6, v96
	v_lshl_add_u64 v[102:103], s[38:39], 0, v[86:87]
	v_mad_u32_u24 v86, v83, s13, 0
	v_lshlrev_b32_e32 v89, 13, v82
	s_addc_u32 s3, s43, s3
	v_lshlrev_b32_e32 v82, 2, v166
	v_mov_b32_e32 v83, v1
	s_movk_i32 s12, 0xd0
	v_add_u32_e32 v127, v96, v112
	v_lshl_add_u64 v[82:83], s[2:3], 0, v[82:83]
	s_mov_b64 s[2:3], 0x256d7900
	v_mul_lo_u32 v96, v127, s12
	s_lshl_b32 s0, s0, 2
	v_lshl_add_u64 v[104:105], v[82:83], 0, s[2:3]
	s_movk_i32 s2, 0x680
	s_movk_i32 s14, 0x19f
	s_movk_i32 s3, 0x1a00
	v_sub_u32_e32 v93, v93, v96
	v_add_u32_e32 v96, 0x6cf, v94
	s_add_i32 s0, s0, 0
	v_cmp_gt_i32_e64 s[44:45], s2, v94
	s_movk_i32 s2, 0x74f
	v_cmp_gt_u32_e64 s[68:69], s14, v96
	v_mul_lo_u32 v96, v127, s3
	v_add3_u32 v130, s0, v89, v0
	s_add_i32 s0, s0, 0x13b00
	v_cmp_lt_i32_e64 s[46:47], s2, v94
	s_movk_i32 s2, 0x750
	v_add_u32_e32 v115, 0, v96
	v_ashrrev_i32_e32 v96, 7, v94
	v_add3_u32 v0, s0, v89, v0
	v_max_i32_e32 v89, 0x480, v94
	v_mul_hi_i32 v82, v94, s11
	v_cmp_gt_i32_e64 s[48:49], s2, v94
	v_mul_hi_i32 v90, v97, s11
	s_movk_i32 s2, 0x54f
	v_mul_lo_u32 v114, v96, s3
	v_mul_lo_u32 v139, v96, s13
	v_ashrrev_i32_e32 v96, 7, v97
	v_sub_u32_e32 v89, v89, v94
	v_lshrrev_b32_e32 v83, 31, v82
	v_ashrrev_i32_e32 v82, 6, v82
	v_lshrrev_b32_e32 v91, 31, v90
	v_ashrrev_i32_e32 v90, 6, v90
	v_cmp_lt_i32_e64 s[52:53], s2, v94
	s_movk_i32 s2, 0x550
	v_add3_u32 v128, 0, v114, v88
	v_mul_lo_u32 v114, v96, s3
	v_add_u32_e32 v89, 0x1ff, v89
	v_add_u32_e32 v124, v82, v83
	v_add_u32_e32 v125, v90, v91
	v_cmp_gt_i32_e64 s[54:55], s2, v94
	v_mul_lo_u32 v92, v126, s12
	s_movk_i32 s2, 0x34f
	v_add3_u32 v129, 0, v114, v88
	v_mul_lo_u32 v88, v96, s13
	v_lshrrev_b32_e32 v96, 9, v89
	v_mul_lo_u32 v82, v124, s12
	v_add_u32_e32 v83, 0xcf, v94
	v_mul_lo_u32 v90, v125, s12
	v_add_u32_e32 v91, 0x2cf, v94
	v_sub_u32_e32 v84, v84, v92
	v_cmp_lt_i32_e64 s[58:59], s2, v94
	s_movk_i32 s2, 0x350
	v_add_u32_e32 v92, 0x4cf, v94
	v_add_u32_e32 v133, 1, v96
	s_movk_i32 s0, 0x1ff
	v_sub_u32_e32 v82, v94, v82
	v_cmp_gt_u32_e64 s[50:51], s14, v83
	v_mul_lo_u32 v83, v124, s3
	v_sub_u32_e32 v90, v97, v90
	v_cmp_gt_u32_e64 s[56:57], s14, v91
	v_mul_lo_u32 v91, v125, s3
	v_cmp_gt_i32_e64 s[60:61], s2, v94
	v_cmp_gt_u32_e64 s[62:63], s14, v92
	v_mul_lo_u32 v92, v126, s3
	s_movk_i32 s2, 0x14f
	v_cmp_lt_u32_e64 s[70:71], s0, v89
	v_and_b32_e32 v132, 0xfffffe, v133
	s_lshl_b32 s0, s8, 6
	v_cmp_gt_u32_e64 s[38:39], 64, v85
	v_lshl_add_u32 v85, v85, 1, 0
	v_and_b32_e32 v87, 48, v94
	v_lshlrev_b32_e32 v106, 3, v82
	v_add_u32_e32 v83, 0, v83
	v_lshlrev_b32_e32 v82, 5, v82
	v_lshlrev_b32_e32 v108, 3, v90
	v_add_u32_e32 v91, 0, v91
	v_lshlrev_b32_e32 v90, 5, v90
	v_lshlrev_b32_e32 v110, 3, v84
	v_add_u32_e32 v92, 0, v92
	v_lshlrev_b32_e32 v84, 5, v84
	v_cmp_lt_i32_e64 s[64:65], s2, v94
	s_movk_i32 s2, 0x150
	v_lshlrev_b32_e32 v112, 3, v93
	v_lshlrev_b32_e32 v93, 5, v93
	v_cmp_ne_u32_e64 s[26:27], v133, v132
	v_lshlrev_b32_e32 v133, 2, v94
	s_add_i32 s19, s1, s0
	v_readlane_b32 s0, v254, 60
	v_cmp_gt_u32_e64 s[40:41], 32, v166
	v_cmp_eq_u32_e64 s[42:43], 0, v166
	v_ashrrev_i32_e32 v107, 31, v106
	v_ashrrev_i32_e32 v109, 31, v108
	v_ashrrev_i32_e32 v111, 31, v110
	v_cmp_gt_i32_e64 s[66:67], s2, v94
	v_ashrrev_i32_e32 v113, 31, v112
	v_add_u32_e32 v131, 0xfb00, v130
	v_lshl_add_u32 v114, v132, 9, v94
	v_mov_b32_e32 v96, v94
	s_lshl_b32 s12, s10, 6
	s_lshl_b32 s18, s8, 3
	s_lshl_b32 s14, s10, 3
	v_add_u32_e32 v134, s0, v133
	v_add_u32_e32 v135, v83, v82
	v_add_u32_e32 v136, v91, v90
	v_add_u32_e32 v137, v92, v84
	v_add_u32_e32 v138, v115, v93
	v_add_u32_e32 v139, v85, v139
	v_add_u32_e32 v140, v85, v88
	v_add_u32_e32 v141, v86, v87
	s_mov_b32 s16, s8
	global_load_dword v168, v[102:103], off
	s_waitcnt vmcnt(0)
	s_branch .LBB0_46

; __device__ __forceinline__ unsigned pk2(float lo, float hi) { return f2bf(lo) | (f2bf(hi) << 16); }
; __device__ __forceinline__ void pool_item(const Args& A, const Ctx& C0, int l, int row0, int t0, int pos0, const float* hist, float* outpool) {
;     ...
;         for (int it = 0; it < 6; ++it) { const int idx = C.tid + 512 * it; const int rr = idx >> 6, v = idx & 63;
;             xs[it] = (v4u){0u, 0u, 0u, 0u};
;             if (idx < 47 * 64) {
;                 if (rr < 15 && t0 == 0) { if (hist) { const f32x4 a0 = *(const f32x4*)(hist + rr * 512 + v * 8), a1 = *(const f32x4*)(hist + rr * 512 + v * 8 + 4);
;                         xs[it] = (v4u){pk2(a0.x, a0.y), pk2(a0.z, a0.w), pk2(a1.x, a1.y), pk2(a1.z, a1.w)}; } }
;                 else xs[it] = *(const v4u*)(U + (size_t)(row0 - 15 + rr) * DIN + C_P + v * 8); } }
.LBB0_295:
	s_andn2_saveexec_b64 s[64:65], s[2:3]
	s_cbranch_execz .LBB0_669
	s_andn2_b64 vcc, exec, s[62:63]
	s_cbranch_vccnz .LBB0_668
	s_waitcnt vmcnt(0) lgkmcnt(0)
	v_lshlrev_b32_e32 v22, 9, v38
	v_ashrrev_i32_e32 v23, 31, v22
	v_lshl_add_u64 v[22:23], v[22:23], 2, v[26:27]
	global_load_dwordx4 v[24:27], v[22:23], off offset:16
	global_load_dwordx4 v[40:43], v[22:23], off
	s_waitcnt vmcnt(0)
	s_nop 0
	s_nop 0
	s_nop 0
	s_nop 0
	s_nop 0
	v_cvt_pk_bf16_f32 v22, v40, v41
	s_nop 0
	s_nop 0
	s_nop 0
	v_cvt_pk_bf16_f32 v23, v42, v43
	s_nop 0
	s_nop 0
	s_nop 0
	s_nop 0
	s_nop 0
	v_cvt_pk_bf16_f32 v24, v24, v25
	s_nop 0
	s_nop 0
	s_nop 0
	s_nop 0
	s_nop 0
	v_cvt_pk_bf16_f32 v25, v26, v27
	s_branch .LBB0_669

; __device__ __forceinline__ unsigned pk2(float lo, float hi) { return f2bf(lo) | (f2bf(hi) << 16); }
; __device__ __forceinline__ void attn_unit(const Args& A, const Ctx& C0, int l, int u_qrow0, int u_nq, int u_krow0, int u_krow1, int u_krow2, int u_g, const float* u_ck, const float* u_cv, unsigned u_vmask) {
;     ...
;         for (int it = 0; it < 3; ++it) { const int idx = C.tid + 512 * it; const int j = idx >> 3, part = idx & 7;
;             kx[it] = (v4u){0u, 0u, 0u, 0u}; vx[it] = kx[it];
;             if ((u.vmask >> (j >> 5)) & 1u) {
;                 if (u.ck && j < 128) { const float* pk = u.ck + (size_t)j * 128 + part * 8; const float* pv = u.cv + (size_t)j * 128 + part * 8;
;                     const f32x4 a0 = *(const f32x4*)pk, a1 = *(const f32x4*)(pk + 4), b0 = *(const f32x4*)pv, b1 = *(const f32x4*)(pv + 4);
;                     kx[it] = (v4u){pk2(a0.x, a0.y), pk2(a0.z, a0.w), pk2(a1.x, a1.y), pk2(a1.z, a1.w)}; vx[it] = (v4u){pk2(b0.x, b0.y), pk2(b0.z, b0.w), pk2(b1.x, b1.y), pk2(b1.z, b1.w)}; }
;                 else { const int ch = j >> 6; const int kr = (ch == 0 ? u.krow0 : (ch == 1 ? u.krow1 : u.krow2)) + (j & 63);
;                     kx[it] = *(const v4u*)(U + (size_t)kr * DIN + C_K + u.g * 64 + part * 8); vx[it] = *(const v4u*)(U + (size_t)kr * DIN + C_V + u.g * 64 + part * 8); }
;             } }
.LBB0_304:
	s_andn2_saveexec_b64 s[42:43], s[30:31]
	s_cbranch_execz .LBB0_306
	v_ashrrev_i32_e32 v31, 31, v30
	s_waitcnt vmcnt(0) lgkmcnt(0)
	v_lshlrev_b64 v[2:3], 9, v[30:31]
	v_lshl_add_u64 v[4:5], v[34:35], 0, v[2:3]
	v_lshl_add_u64 v[16:17], v[32:33], 0, v[2:3]
	global_load_dwordx4 v[8:11], v[4:5], off offset:16
	s_nop 0
	global_load_dwordx4 v[2:5], v[4:5], off
	s_nop 0
	global_load_dwordx4 v[12:15], v[16:17], off offset:16
	global_load_dwordx4 v[22:25], v[16:17], off
	s_waitcnt vmcnt(2)
	s_nop 0
	s_nop 0
	s_nop 0
	s_nop 0
	s_nop 0
	v_cvt_pk_bf16_f32 v2, v2, v3
	v_cvt_pk_bf16_f32 v3, v4, v5
	v_cvt_pk_bf16_f32 v4, v8, v9
	v_cvt_pk_bf16_f32 v5, v10, v11
	s_waitcnt vmcnt(0)
	v_cvt_pk_bf16_f32 v10, v22, v23
	s_nop 0
	s_nop 0
	s_nop 0
	s_nop 0
	s_nop 0
	v_cvt_pk_bf16_f32 v11, v24, v25
	s_nop 0
	s_nop 0
	s_nop 0
	s_nop 0
	s_nop 0
	v_cvt_pk_bf16_f32 v12, v12, v13
	s_nop 0
	s_nop 0
	s_nop 0
	s_nop 0
	s_nop 0
	v_cvt_pk_bf16_f32 v13, v14, v15

; __device__ __forceinline__ unsigned pk2(float lo, float hi) { return f2bf(lo) | (f2bf(hi) << 16); }
; __device__ __forceinline__ void attn_unit(const Args& A, const Ctx& C0, int l, int u_qrow0, int u_nq, int u_krow0, int u_krow1, int u_krow2, int u_g, const float* u_ck, const float* u_cv, unsigned u_vmask) {
;     ...
;         for (int it = 0; it < 3; ++it) { const int idx = C.tid + 512 * it; const int j = idx >> 3, part = idx & 7;
;             kx[it] = (v4u){0u, 0u, 0u, 0u}; vx[it] = kx[it];
;             if ((u.vmask >> (j >> 5)) & 1u) {
;                 if (u.ck && j < 128) { const float* pk = u.ck + (size_t)j * 128 + part * 8; const float* pv = u.cv + (size_t)j * 128 + part * 8;
;                     const f32x4 a0 = *(const f32x4*)pk, a1 = *(const f32x4*)(pk + 4), b0 = *(const f32x4*)pv, b1 = *(const f32x4*)(pv + 4);
;                     kx[it] = (v4u){pk2(a0.x, a0.y), pk2(a0.z, a0.w), pk2(a1.x, a1.y), pk2(a1.z, a1.w)}; vx[it] = (v4u){pk2(b0.x, b0.y), pk2(b0.z, b0.w), pk2(b1.x, b1.y), pk2(b1.z, b1.w)}; }
;                 else { const int ch = j >> 6; const int kr = (ch == 0 ? u.krow0 : (ch == 1 ? u.krow1 : u.krow2)) + (j & 63);
;                     kx[it] = *(const v4u*)(U + (size_t)kr * DIN + C_K + u.g * 64 + part * 8); vx[it] = *(const v4u*)(U + (size_t)kr * DIN + C_V + u.g * 64 + part * 8); }
;             } }
.LBB0_310:
	s_andn2_saveexec_b64 s[30:31], s[30:31]
	s_cbranch_execz .LBB0_312
	v_ashrrev_i32_e32 v37, 31, v36
	v_lshlrev_b64 v[8:9], 9, v[36:37]
	s_waitcnt vmcnt(0) lgkmcnt(0)
	v_lshl_add_u64 v[22:23], v[34:35], 0, v[8:9]
	v_lshl_add_u64 v[8:9], v[32:33], 0, v[8:9]
	global_load_dwordx4 v[14:17], v[22:23], off
	s_nop 0
	global_load_dwordx4 v[22:25], v[22:23], off offset:16
	s_nop 0
	global_load_dwordx4 v[26:29], v[8:9], off
	global_load_dwordx4 v[42:45], v[8:9], off offset:16
	s_waitcnt vmcnt(3)
	s_nop 0
	s_nop 0
	s_nop 0
	s_nop 0
	s_waitcnt vmcnt(2)
	s_nop 0
	s_waitcnt vmcnt(1)
	s_waitcnt vmcnt(0)
	v_cvt_pk_bf16_f32 v25, v24, v25
	v_cvt_pk_bf16_f32 v24, v22, v23
	v_cvt_pk_bf16_f32 v22, v14, v15
	v_cvt_pk_bf16_f32 v23, v16, v17
	v_cvt_pk_bf16_f32 v14, v26, v27
	v_cvt_pk_bf16_f32 v15, v28, v29
	v_cvt_pk_bf16_f32 v16, v42, v43
	v_cvt_pk_bf16_f32 v17, v44, v45

; __device__ __forceinline__ unsigned pk2(float lo, float hi) { return f2bf(lo) | (f2bf(hi) << 16); }
; __device__ __forceinline__ void attn_unit(const Args& A, const Ctx& C0, int l, int u_qrow0, int u_nq, int u_krow0, int u_krow1, int u_krow2, int u_g, const float* u_ck, const float* u_cv, unsigned u_vmask) {
;     ...
;         for (int it = 0; it < 3; ++it) { const int idx = C.tid + 512 * it; const int j = idx >> 3, part = idx & 7;
;             kx[it] = (v4u){0u, 0u, 0u, 0u}; vx[it] = kx[it];
;             if ((u.vmask >> (j >> 5)) & 1u) {
;                 if (u.ck && j < 128) { const float* pk = u.ck + (size_t)j * 128 + part * 8; const float* pv = u.cv + (size_t)j * 128 + part * 8;
;                     const f32x4 a0 = *(const f32x4*)pk, a1 = *(const f32x4*)(pk + 4), b0 = *(const f32x4*)pv, b1 = *(const f32x4*)(pv + 4);
;                     kx[it] = (v4u){pk2(a0.x, a0.y), pk2(a0.z, a0.w), pk2(a1.x, a1.y), pk2(a1.z, a1.w)}; vx[it] = (v4u){pk2(b0.x, b0.y), pk2(b0.z, b0.w), pk2(b1.x, b1.y), pk2(b1.z, b1.w)}; }
;                 else { const int ch = j >> 6; const int kr = (ch == 0 ? u.krow0 : (ch == 1 ? u.krow1 : u.krow2)) + (j & 63);
;                     kx[it] = *(const v4u*)(U + (size_t)kr * DIN + C_K + u.g * 64 + part * 8); vx[it] = *(const v4u*)(U + (size_t)kr * DIN + C_V + u.g * 64 + part * 8); }
;             } }
.LBB0_316:
	s_andn2_saveexec_b64 s[24:25], s[30:31]
	s_cbranch_execz .LBB0_318
	v_ashrrev_i32_e32 v39, 31, v38
	v_lshlrev_b64 v[42:43], 9, v[38:39]
	s_waitcnt vmcnt(0) lgkmcnt(0)
	v_lshl_add_u64 v[26:27], v[34:35], 0, v[42:43]
	v_lshl_add_u64 v[42:43], v[32:33], 0, v[42:43]
	global_load_dwordx4 v[6:9], v[26:27], off
	s_nop 0
	global_load_dwordx4 v[26:29], v[26:27], off offset:16
	s_nop 0
	global_load_dwordx4 v[32:35], v[42:43], off
	s_nop 0
	global_load_dwordx4 v[42:45], v[42:43], off offset:16
	s_waitcnt vmcnt(3)
	s_nop 0
	s_nop 0
	s_waitcnt vmcnt(2)
	s_nop 0
	s_nop 0
	s_waitcnt vmcnt(1)
	s_waitcnt vmcnt(0)
	v_cvt_pk_bf16_f32 v6, v6, v7
	v_cvt_pk_bf16_f32 v7, v8, v9
	v_cvt_pk_bf16_f32 v8, v26, v27
	v_cvt_pk_bf16_f32 v9, v28, v29
	v_cvt_pk_bf16_f32 v26, v32, v33
	v_cvt_pk_bf16_f32 v27, v34, v35
	v_cvt_pk_bf16_f32 v28, v42, v43
	v_cvt_pk_bf16_f32 v29, v44, v45

; __device__ __forceinline__ float shflx(float v, int mask, int lane) { return __int_as_float(__builtin_amdgcn_ds_bpermute((lane ^ mask) << 2, __float_as_int(v))); }
; __device__ __forceinline__ void attn_unit(const Args& A, const Ctx& C0, int l, int u_qrow0, int u_nq, int u_krow0, int u_krow1, int u_krow2, int u_g, const float* u_ck, const float* u_cv, unsigned u_vmask) {
;     ...
;         float mx = sink;
; #pragma unroll
;         for (int kt = 0; kt < 6; ++kt) { const bool valid = (u.vmask >> kt) & 1u;
; #pragma unroll
;             for (int r = 0; r < 16; ++r) { const int j = kt * 32 + (r & 3) + 8 * (r >> 2) + 4 * h;
;                 const float lg = valid ? sacc[kt][r] * 0.125f + bL[j - qi + 63] : -1e30f; sacc[kt][r] = lg; mx = fmaxf(mx, lg); }
;             asm volatile("" ::: "memory"); }
;         mx = fmaxf(mx, shflx(mx, 32, C.lane));
;         float sum = 0.f;
; #pragma unroll
;         for (int kt = 0; kt < 6; ++kt)
; #pragma unroll
;             for (int r = 0; r < 16; ++r) { const float e = __expf(sacc[kt][r] - mx); sacc[kt][r] = e; sum += e; }
;         sum += shflx(sum, 32, C.lane); sum += __expf(sink - mx);
.LBB0_404:
	s_waitcnt vmcnt(0)
	v_max3_f32 v18, v186, v123, v122
	v_max3_f32 v18, v18, v83, v82
	v_max3_f32 v18, v18, v85, v84
	v_max3_f32 v18, v18, v87, v86
	v_max3_f32 v18, v18, v89, v88
	v_max3_f32 v18, v18, v91, v90
	v_max3_f32 v18, v18, v93, v92
	v_max3_f32 v18, v18, v95, v94
	v_max3_f32 v18, v18, v97, v96
	v_max3_f32 v18, v18, v67, v66
	v_max3_f32 v18, v18, v69, v68
	v_max3_f32 v18, v18, v71, v70
	v_max3_f32 v18, v18, v73, v72
	v_max3_f32 v18, v18, v75, v74
	v_max3_f32 v18, v18, v77, v76
	v_max3_f32 v18, v18, v79, v78
	v_max3_f32 v18, v18, v81, v80
	v_max3_f32 v18, v18, v119, v118
	v_max3_f32 v18, v18, v53, v52
	v_max3_f32 v18, v18, v55, v54
	v_max3_f32 v18, v18, v57, v56
	v_max3_f32 v18, v18, v59, v58
	v_max3_f32 v18, v18, v61, v60
	v_max3_f32 v18, v18, v63, v62
	v_max3_f32 v18, v18, v65, v64
	v_max3_f32 v18, v18, v121, v120
	v_max3_f32 v18, v18, v125, v124
	v_max3_f32 v18, v18, v127, v126
	v_max3_f32 v18, v18, v194, v192
	v_max3_f32 v18, v18, v197, v196
	v_max3_f32 v18, v18, v201, v199
	v_max3_f32 v18, v18, v205, v204
	s_waitcnt lgkmcnt(7)
	v_fmamk_f32 v48, v2, 0x3e000000, v48
	v_fmac_f32_e32 v49, 0x3e000000, v3
	v_max3_f32 v2, v18, v48, v49
	s_waitcnt lgkmcnt(6)
	v_fmamk_f32 v46, v4, 0x3e000000, v46
	v_fmac_f32_e32 v47, 0x3e000000, v5
	v_max3_f32 v2, v2, v46, v47
	s_waitcnt lgkmcnt(5)
	v_fmamk_f32 v44, v6, 0x3e000000, v44
	v_fmac_f32_e32 v45, 0x3e000000, v7
	v_max3_f32 v2, v2, v44, v45
	s_waitcnt lgkmcnt(4)
	v_fmamk_f32 v42, v8, 0x3e000000, v42
	v_fmac_f32_e32 v43, 0x3e000000, v9
	v_max3_f32 v2, v2, v42, v43
	s_waitcnt lgkmcnt(3)
	v_fmamk_f32 v40, v10, 0x3e000000, v40
	v_fmac_f32_e32 v41, 0x3e000000, v11
	v_max3_f32 v2, v2, v40, v41
	s_waitcnt lgkmcnt(2)
	v_fmamk_f32 v38, v12, 0x3e000000, v38
	v_fmac_f32_e32 v39, 0x3e000000, v13
	v_max3_f32 v2, v2, v38, v39
	s_waitcnt lgkmcnt(1)
	v_fmamk_f32 v36, v14, 0x3e000000, v36
	v_fmac_f32_e32 v37, 0x3e000000, v15
	v_max3_f32 v2, v2, v36, v37
	s_waitcnt lgkmcnt(0)
	v_fmamk_f32 v34, v16, 0x3e000000, v34
	v_fmac_f32_e32 v35, 0x3e000000, v17
	v_max3_f32 v2, v2, v34, v35
	v_max3_f32 v2, v2, v195, v193
	v_max3_f32 v2, v2, v200, v198
	v_max3_f32 v2, v2, v203, v202
	v_max3_f32 v2, v2, v208, v206
	v_max3_f32 v2, v2, v210, v209
	v_max3_f32 v2, v2, v212, v211
	v_max3_f32 v2, v2, v214, v213
	v_xor_b32_e32 v189, 0x80, v164
	v_max3_f32 v2, v2, v216, v215
	ds_bpermute_b32 v3, v189, v2
	s_waitcnt lgkmcnt(0)
	v_max_f32_e32 v3, v3, v3
	v_max_f32_e32 v217, v2, v3
	v_sub_f32_e32 v17, v97, v217
	v_mul_f32_e32 v17, 0x3fb8aa3b, v17
	v_sub_f32_e32 v2, v123, v217
	v_exp_f32_e32 v176, v17
	v_sub_f32_e32 v17, v96, v217
	v_mul_f32_e32 v2, 0x3fb8aa3b, v2
	v_mul_f32_e32 v17, 0x3fb8aa3b, v17
	v_exp_f32_e32 v10, v2
	v_sub_f32_e32 v2, v122, v217
	v_exp_f32_e32 v178, v17
	v_sub_f32_e32 v17, v67, v217
	v_mul_f32_e32 v2, 0x3fb8aa3b, v2
	v_mul_f32_e32 v17, 0x3fb8aa3b, v17
	v_exp_f32_e32 v12, v2
	v_sub_f32_e32 v2, v83, v217
	v_sub_f32_e32 v3, v85, v217
	v_exp_f32_e32 v177, v17
	v_sub_f32_e32 v17, v66, v217
	v_mul_f32_e32 v2, 0x3fb8aa3b, v2
	v_mul_f32_e32 v3, 0x3fb8aa3b, v3
	v_mul_f32_e32 v17, 0x3fb8aa3b, v17
	v_exp_f32_e32 v11, v2
	v_sub_f32_e32 v2, v82, v217
	v_exp_f32_e32 v14, v3
	v_sub_f32_e32 v3, v84, v217
	v_exp_f32_e32 v179, v17
	v_sub_f32_e32 v17, v69, v217
	v_mul_f32_e32 v2, 0x3fb8aa3b, v2
	v_mul_f32_e32 v3, 0x3fb8aa3b, v3
	v_mul_f32_e32 v17, 0x3fb8aa3b, v17
	v_exp_f32_e32 v13, v2
	v_exp_f32_e32 v50, v3
	v_sub_f32_e32 v3, v87, v217
	v_exp_f32_e32 v180, v17
	v_sub_f32_e32 v17, v68, v217
	v_add_f32_e32 v2, 0, v10
	v_mul_f32_e32 v3, 0x3fb8aa3b, v3
	v_mul_f32_e32 v17, 0x3fb8aa3b, v17
	v_add_f32_e32 v2, v12, v2
	v_exp_f32_e32 v15, v3
	v_sub_f32_e32 v3, v86, v217
	v_exp_f32_e32 v182, v17
	v_sub_f32_e32 v17, v71, v217
	v_add_f32_e32 v2, v11, v2
	v_mul_f32_e32 v3, 0x3fb8aa3b, v3
	v_mul_f32_e32 v17, 0x3fb8aa3b, v17
	v_add_f32_e32 v2, v13, v2
	v_exp_f32_e32 v51, v3
	v_exp_f32_e32 v181, v17
	v_sub_f32_e32 v17, v70, v217
	v_add_f32_e32 v2, v14, v2
	v_mul_f32_e32 v17, 0x3fb8aa3b, v17
	v_add_f32_e32 v2, v50, v2
	v_exp_f32_e32 v183, v17
	v_sub_f32_e32 v17, v73, v217
	v_add_f32_e32 v2, v15, v2
	v_mul_f32_e32 v17, 0x3fb8aa3b, v17
	v_add_f32_e32 v6, v51, v2
	v_sub_f32_e32 v2, v89, v217
	v_sub_f32_e32 v3, v88, v217
	v_exp_f32_e32 v168, v17
	v_sub_f32_e32 v17, v72, v217
	v_mul_f32_e32 v2, 0x3fb8aa3b, v2
	v_mul_f32_e32 v3, 0x3fb8aa3b, v3
	v_mul_f32_e32 v17, 0x3fb8aa3b, v17
	v_exp_f32_e32 v2, v2
	v_exp_f32_e32 v4, v3
	v_sub_f32_e32 v3, v91, v217
	v_exp_f32_e32 v170, v17
	v_sub_f32_e32 v17, v75, v217
	v_mul_f32_e32 v3, 0x3fb8aa3b, v3
	v_sub_f32_e32 v5, v90, v217
	v_mul_f32_e32 v17, 0x3fb8aa3b, v17
	v_exp_f32_e32 v3, v3
	v_mul_f32_e32 v5, 0x3fb8aa3b, v5
	v_exp_f32_e32 v169, v17
	v_sub_f32_e32 v17, v74, v217
	v_exp_f32_e32 v5, v5
	v_mul_f32_e32 v17, 0x3fb8aa3b, v17
	v_add_f32_e32 v6, v2, v6
	v_exp_f32_e32 v171, v17
	v_sub_f32_e32 v17, v77, v217
	v_add_f32_e32 v6, v4, v6
	v_mul_f32_e32 v17, 0x3fb8aa3b, v17
	v_add_f32_e32 v6, v3, v6
	v_exp_f32_e32 v172, v17
	v_sub_f32_e32 v17, v76, v217
	v_add_f32_e32 v16, v5, v6
	v_sub_f32_e32 v6, v93, v217
	v_sub_f32_e32 v7, v92, v217
	v_mul_f32_e32 v17, 0x3fb8aa3b, v17
	v_mul_f32_e32 v6, 0x3fb8aa3b, v6
	v_mul_f32_e32 v7, 0x3fb8aa3b, v7
	v_exp_f32_e32 v174, v17
	v_sub_f32_e32 v17, v79, v217
	v_exp_f32_e32 v6, v6
	v_exp_f32_e32 v8, v7
	v_sub_f32_e32 v7, v95, v217
	v_mul_f32_e32 v17, 0x3fb8aa3b, v17
	v_mul_f32_e32 v7, 0x3fb8aa3b, v7
	v_sub_f32_e32 v9, v94, v217
	v_exp_f32_e32 v173, v17
	v_sub_f32_e32 v17, v78, v217
	v_exp_f32_e32 v7, v7
	v_mul_f32_e32 v9, 0x3fb8aa3b, v9
	v_mul_f32_e32 v17, 0x3fb8aa3b, v17
	v_exp_f32_e32 v9, v9
	v_exp_f32_e32 v175, v17
	v_sub_f32_e32 v17, v81, v217
	v_add_f32_e32 v16, v6, v16
; __device__ __forceinline__ float shflx(float v, int mask, int lane) { return __int_as_float(__builtin_amdgcn_ds_bpermute((lane ^ mask) << 2, __float_as_int(v))); }
; __device__ __forceinline__ void attn_unit(const Args& A, const Ctx& C0, int l, int u_qrow0, int u_nq, int u_krow0, int u_krow1, int u_krow2, int u_g, const float* u_ck, const float* u_cv, unsigned u_vmask) {
;     ...
;         float sum = 0.f;
; #pragma unroll
;         for (int kt = 0; kt < 6; ++kt)
; #pragma unroll
;             for (int r = 0; r < 16; ++r) { const float e = __expf(sacc[kt][r] - mx); sacc[kt][r] = e; sum += e; }
;         sum += shflx(sum, 32, C.lane); sum += __expf(sink - mx);
	v_mul_f32_e32 v17, 0x3fb8aa3b, v17
	v_add_f32_e32 v16, v8, v16
	v_exp_f32_e32 v32, v17
	v_sub_f32_e32 v17, v80, v217
	v_add_f32_e32 v16, v7, v16
	v_mul_f32_e32 v17, 0x3fb8aa3b, v17
	v_add_f32_e32 v16, v9, v16
	v_exp_f32_e32 v128, v17
	v_sub_f32_e32 v17, v119, v217
	v_add_f32_e32 v16, v176, v16
	v_mul_f32_e32 v17, 0x3fb8aa3b, v17
	v_add_f32_e32 v16, v178, v16
	v_exp_f32_e32 v33, v17
	v_sub_f32_e32 v17, v118, v217
	v_add_f32_e32 v16, v177, v16
	v_mul_f32_e32 v17, 0x3fb8aa3b, v17
	v_add_f32_e32 v16, v179, v16
	v_exp_f32_e32 v129, v17
	v_sub_f32_e32 v17, v53, v217
	v_add_f32_e32 v16, v180, v16
	v_mul_f32_e32 v17, 0x3fb8aa3b, v17
	v_add_f32_e32 v16, v182, v16
	v_exp_f32_e32 v164, v17
	v_sub_f32_e32 v17, v52, v217
	v_add_f32_e32 v16, v181, v16
	v_mul_f32_e32 v17, 0x3fb8aa3b, v17
	v_add_f32_e32 v16, v183, v16
	v_exp_f32_e32 v166, v17
	v_sub_f32_e32 v17, v55, v217
	v_add_f32_e32 v16, v168, v16
	v_mul_f32_e32 v17, 0x3fb8aa3b, v17
	v_add_f32_e32 v16, v170, v16
	v_exp_f32_e32 v165, v17
	v_sub_f32_e32 v17, v54, v217
	v_add_f32_e32 v16, v169, v16
	v_mul_f32_e32 v17, 0x3fb8aa3b, v17
	v_add_f32_e32 v16, v171, v16
	v_exp_f32_e32 v167, v17
	v_sub_f32_e32 v17, v57, v217
	v_add_f32_e32 v16, v172, v16
	v_mul_f32_e32 v17, 0x3fb8aa3b, v17
	v_add_f32_e32 v16, v174, v16
	v_exp_f32_e32 v24, v17
	v_sub_f32_e32 v17, v56, v217
	v_add_f32_e32 v16, v173, v16
	v_mul_f32_e32 v17, 0x3fb8aa3b, v17
	v_add_f32_e32 v16, v175, v16
	v_exp_f32_e32 v26, v17
	v_sub_f32_e32 v17, v59, v217
	v_add_f32_e32 v16, v32, v16
	v_mul_f32_e32 v17, 0x3fb8aa3b, v17
	v_add_f32_e32 v16, v128, v16
	v_exp_f32_e32 v25, v17
	v_sub_f32_e32 v17, v58, v217
	v_add_f32_e32 v16, v33, v16
	v_mul_f32_e32 v17, 0x3fb8aa3b, v17
	v_add_f32_e32 v16, v129, v16
	v_exp_f32_e32 v27, v17
	v_sub_f32_e32 v17, v61, v217
	v_add_f32_e32 v16, v164, v16
	v_mul_f32_e32 v17, 0x3fb8aa3b, v17
	v_add_f32_e32 v16, v166, v16
	v_exp_f32_e32 v28, v17
	v_sub_f32_e32 v17, v60, v217
	v_add_f32_e32 v16, v165, v16
	v_mul_f32_e32 v17, 0x3fb8aa3b, v17
	v_add_f32_e32 v16, v167, v16
	v_exp_f32_e32 v30, v17
	v_sub_f32_e32 v17, v63, v217
	v_add_f32_e32 v16, v24, v16
	v_mul_f32_e32 v17, 0x3fb8aa3b, v17
	v_add_f32_e32 v16, v26, v16
	v_exp_f32_e32 v29, v17
	v_sub_f32_e32 v17, v62, v217
	v_add_f32_e32 v16, v25, v16
	v_mul_f32_e32 v17, 0x3fb8aa3b, v17
	v_add_f32_e32 v16, v27, v16
	v_exp_f32_e32 v31, v17
	v_add_f32_e32 v16, v28, v16
	v_add_f32_e32 v16, v30, v16
	v_add_f32_e32 v16, v29, v16
	v_add_f32_e32 v20, v31, v16
	v_sub_f32_e32 v16, v65, v217
	v_sub_f32_e32 v17, v64, v217
	v_mul_f32_e32 v16, 0x3fb8aa3b, v16
	v_mul_f32_e32 v17, 0x3fb8aa3b, v17
	v_exp_f32_e32 v16, v16
	v_exp_f32_e32 v18, v17
	v_sub_f32_e32 v17, v121, v217
	v_mul_f32_e32 v17, 0x3fb8aa3b, v17
	v_sub_f32_e32 v19, v120, v217
	v_exp_f32_e32 v17, v17
	v_mul_f32_e32 v19, 0x3fb8aa3b, v19
	v_exp_f32_e32 v19, v19
	v_add_f32_e32 v20, v16, v20
	v_sub_f32_e32 v53, v194, v217
	v_add_f32_e32 v20, v18, v20
	v_mul_f32_e32 v53, 0x3fb8aa3b, v53
	v_add_f32_e32 v20, v17, v20
	v_exp_f32_e32 v120, v53
	v_sub_f32_e32 v53, v192, v217
	v_add_f32_e32 v52, v19, v20
	v_sub_f32_e32 v20, v125, v217
	v_sub_f32_e32 v21, v124, v217
	v_mul_f32_e32 v53, 0x3fb8aa3b, v53
	v_mul_f32_e32 v20, 0x3fb8aa3b, v20
	v_mul_f32_e32 v21, 0x3fb8aa3b, v21
	v_exp_f32_e32 v122, v53
	v_sub_f32_e32 v53, v197, v217
	v_exp_f32_e32 v20, v20
	v_exp_f32_e32 v22, v21
	v_sub_f32_e32 v21, v127, v217
	v_mul_f32_e32 v53, 0x3fb8aa3b, v53
	v_mul_f32_e32 v21, 0x3fb8aa3b, v21
	v_sub_f32_e32 v23, v126, v217
	v_exp_f32_e32 v121, v53
	v_sub_f32_e32 v53, v196, v217
	v_exp_f32_e32 v21, v21
	v_mul_f32_e32 v23, 0x3fb8aa3b, v23
	v_mul_f32_e32 v53, 0x3fb8aa3b, v53
	v_exp_f32_e32 v23, v23
	v_exp_f32_e32 v123, v53
	v_sub_f32_e32 v53, v201, v217
	v_add_f32_e32 v52, v20, v52
	v_mul_f32_e32 v53, 0x3fb8aa3b, v53
	v_add_f32_e32 v52, v22, v52
	v_exp_f32_e32 v124, v53
	v_sub_f32_e32 v53, v199, v217
	v_add_f32_e32 v52, v21, v52
	v_mul_f32_e32 v53, 0x3fb8aa3b, v53
	v_add_f32_e32 v52, v23, v52
	v_exp_f32_e32 v126, v53
	v_sub_f32_e32 v53, v205, v217
	v_add_f32_e32 v52, v120, v52
	v_mul_f32_e32 v53, 0x3fb8aa3b, v53
	v_add_f32_e32 v52, v122, v52
	v_exp_f32_e32 v125, v53
	v_sub_f32_e32 v53, v204, v217
	v_sub_f32_e32 v48, v48, v217
	v_sub_f32_e32 v34, v34, v217
	v_add_f32_e32 v52, v121, v52
	v_mul_f32_e32 v53, 0x3fb8aa3b, v53
	v_mul_f32_e32 v48, 0x3fb8aa3b, v48
	v_mul_f32_e32 v34, 0x3fb8aa3b, v34
	v_add_f32_e32 v52, v123, v52
	v_exp_f32_e32 v127, v53
	v_exp_f32_e32 v92, v48
	v_sub_f32_e32 v48, v49, v217
	v_sub_f32_e32 v46, v46, v217
	v_exp_f32_e32 v89, v34
	v_sub_f32_e32 v34, v35, v217
	v_sub_f32_e32 v35, v195, v217
	v_add_f32_e32 v52, v124, v52
	v_mul_f32_e32 v48, 0x3fb8aa3b, v48
	v_mul_f32_e32 v46, 0x3fb8aa3b, v46
	v_mul_f32_e32 v35, 0x3fb8aa3b, v35
	v_add_f32_e32 v52, v126, v52
	v_exp_f32_e32 v94, v48
	v_exp_f32_e32 v93, v46
	v_sub_f32_e32 v46, v47, v217
	v_sub_f32_e32 v44, v44, v217
	v_exp_f32_e32 v74, v35
	v_sub_f32_e32 v35, v193, v217
	v_add_f32_e32 v52, v125, v52
	v_mul_f32_e32 v46, 0x3fb8aa3b, v46
	v_mul_f32_e32 v44, 0x3fb8aa3b, v44
	v_mul_f32_e32 v35, 0x3fb8aa3b, v35
	v_add_f32_e32 v52, v127, v52
	v_exp_f32_e32 v95, v46
	v_exp_f32_e32 v96, v44
	v_sub_f32_e32 v44, v45, v217
	v_sub_f32_e32 v42, v42, v217
	v_exp_f32_e32 v76, v35
	v_sub_f32_e32 v35, v200, v217
	v_add_f32_e32 v46, v92, v52
; #define LAS __attribute__((address_space(3)))
; __device__ __forceinline__ unsigned pk2(float lo, float hi) { return f2bf(lo) | (f2bf(hi) << 16); }
; __device__ __forceinline__ float shflx(float v, int mask, int lane) { return __int_as_float(__builtin_amdgcn_ds_bpermute((lane ^ mask) << 2, __float_as_int(v))); }
; __device__ __forceinline__ void attn_unit(const Args& A, const Ctx& C0, int l, int u_qrow0, int u_nq, int u_krow0, int u_krow1, int u_krow2, int u_g, const float* u_ck, const float* u_cv, unsigned u_vmask) {
;     ...
;         mx = fmaxf(mx, shflx(mx, 32, C.lane));
;         float sum = 0.f;
; #pragma unroll
;         for (int kt = 0; kt < 6; ++kt)
; #pragma unroll
;             for (int r = 0; r < 16; ++r) { const float e = __expf(sacc[kt][r] - mx); sacc[kt][r] = e; sum += e; }
;         sum += shflx(sum, 32, C.lane); sum += __expf(sink - mx);
;         const float inv = 1.f / sum;
;         f32x16 oacc[2];
; #pragma unroll
;         for (int dt = 0; dt < 2; ++dt)
; #pragma unroll
;             for (int r = 0; r < 16; ++r) oacc[dt][r] = 0.f;
; #pragma unroll
;         for (int kt = 0; kt < 6; ++kt) {
;             if ((u.vmask >> kt) & 1u) {
; #pragma unroll
;                 for (int s = 0; s < 2; ++s) {
;                     union { bf16x8 v; unsigned w[4]; } pf;
; #pragma unroll
;                     for (int e = 0; e < 4; ++e) pf.w[e] = pk2(sacc[kt][8 * s + 2 * e] * inv, sacc[kt][8 * s + 2 * e + 1] * inv);
; #pragma unroll
;                     for (int dt = 0; dt < 2; ++dt) { const LAS bf16* vp = Vt + (dt * 32 + li) * VP + kt * 32 + 16 * s + 4 * h;
;                         union { bf16x8 v; v2u w[2]; } vf; vf.w[0] = *(const LAS v2u*)vp; vf.w[1] = *(const LAS v2u*)(vp + 8);
;                         oacc[dt] = __builtin_amdgcn_mfma_f32_32x32x16_bf16(vf.v, pf.v, oacc[dt], 0, 0, 0); }
	v_mul_f32_e32 v44, 0x3fb8aa3b, v44
	v_mul_f32_e32 v42, 0x3fb8aa3b, v42
	v_mul_f32_e32 v35, 0x3fb8aa3b, v35
	v_add_f32_e32 v46, v94, v46
	v_exp_f32_e32 v118, v44
	v_exp_f32_e32 v97, v42
	v_sub_f32_e32 v42, v43, v217
	v_sub_f32_e32 v40, v40, v217
	v_exp_f32_e32 v75, v35
	v_sub_f32_e32 v35, v198, v217
	v_add_f32_e32 v46, v93, v46
	v_mul_f32_e32 v42, 0x3fb8aa3b, v42
	v_mul_f32_e32 v40, 0x3fb8aa3b, v40
	v_mul_f32_e32 v35, 0x3fb8aa3b, v35
	v_add_f32_e32 v46, v95, v46
	v_exp_f32_e32 v119, v42
	v_exp_f32_e32 v84, v40
	v_sub_f32_e32 v40, v41, v217
	v_sub_f32_e32 v38, v38, v217
	v_exp_f32_e32 v77, v35
	v_sub_f32_e32 v35, v203, v217
	v_add_f32_e32 v42, v96, v46
	v_mul_f32_e32 v40, 0x3fb8aa3b, v40
	v_mul_f32_e32 v38, 0x3fb8aa3b, v38
	v_mul_f32_e32 v35, 0x3fb8aa3b, v35
	v_add_f32_e32 v42, v118, v42
	v_exp_f32_e32 v86, v40
	v_exp_f32_e32 v85, v38
	v_sub_f32_e32 v38, v39, v217
	v_sub_f32_e32 v36, v36, v217
	v_exp_f32_e32 v78, v35
	v_sub_f32_e32 v35, v202, v217
	v_add_f32_e32 v42, v97, v42
	v_mul_f32_e32 v38, 0x3fb8aa3b, v38
	v_mul_f32_e32 v36, 0x3fb8aa3b, v36
	v_mul_f32_e32 v35, 0x3fb8aa3b, v35
	v_add_f32_e32 v42, v119, v42
	v_exp_f32_e32 v87, v38
	v_exp_f32_e32 v88, v36
	v_sub_f32_e32 v36, v37, v217
	v_exp_f32_e32 v80, v35
	v_sub_f32_e32 v35, v208, v217
	v_add_f32_e32 v38, v84, v42
	v_mul_f32_e32 v36, 0x3fb8aa3b, v36
	v_mul_f32_e32 v35, 0x3fb8aa3b, v35
	v_add_f32_e32 v38, v86, v38
	v_exp_f32_e32 v90, v36
	v_exp_f32_e32 v79, v35
	v_sub_f32_e32 v35, v206, v217
	v_add_f32_e32 v38, v85, v38
	v_mul_f32_e32 v34, 0x3fb8aa3b, v34
	v_mul_f32_e32 v35, 0x3fb8aa3b, v35
	v_add_f32_e32 v38, v87, v38
	v_exp_f32_e32 v91, v34
	v_exp_f32_e32 v81, v35
	v_sub_f32_e32 v35, v210, v217
	v_add_f32_e32 v34, v88, v38
	v_mul_f32_e32 v35, 0x3fb8aa3b, v35
	v_add_f32_e32 v34, v90, v34
	v_exp_f32_e32 v66, v35
	v_sub_f32_e32 v35, v209, v217
	v_add_f32_e32 v34, v89, v34
	v_mul_f32_e32 v35, 0x3fb8aa3b, v35
	v_add_f32_e32 v34, v91, v34
	v_exp_f32_e32 v68, v35
	v_sub_f32_e32 v35, v212, v217
	v_add_f32_e32 v34, v74, v34
	v_mul_f32_e32 v35, 0x3fb8aa3b, v35
	v_add_f32_e32 v34, v76, v34
	v_exp_f32_e32 v67, v35
	v_sub_f32_e32 v35, v211, v217
	v_add_f32_e32 v34, v75, v34
	v_mul_f32_e32 v35, 0x3fb8aa3b, v35
	v_add_f32_e32 v34, v77, v34
	v_exp_f32_e32 v69, v35
	v_sub_f32_e32 v35, v214, v217
	v_add_f32_e32 v34, v78, v34
	v_mul_f32_e32 v35, 0x3fb8aa3b, v35
	v_add_f32_e32 v34, v80, v34
	v_exp_f32_e32 v70, v35
	v_sub_f32_e32 v35, v213, v217
	v_add_f32_e32 v34, v79, v34
	v_mul_f32_e32 v35, 0x3fb8aa3b, v35
	v_add_f32_e32 v34, v81, v34
	v_exp_f32_e32 v72, v35
	v_sub_f32_e32 v35, v216, v217
	v_add_f32_e32 v34, v66, v34
	v_mul_f32_e32 v35, 0x3fb8aa3b, v35
	v_add_f32_e32 v34, v68, v34
	v_exp_f32_e32 v71, v35
	v_sub_f32_e32 v35, v215, v217
	v_add_f32_e32 v34, v67, v34
	v_mul_f32_e32 v35, 0x3fb8aa3b, v35
	v_add_f32_e32 v34, v69, v34
	v_exp_f32_e32 v73, v35
	v_add_f32_e32 v34, v70, v34
	v_add_f32_e32 v34, v72, v34
	v_add_f32_e32 v34, v71, v34
	v_add_f32_e32 v34, v73, v34
	ds_bpermute_b32 v35, v189, v34
	v_sub_f32_e32 v36, v186, v217
	v_mul_f32_e32 v36, 0x3fb8aa3b, v36
	v_exp_f32_e32 v36, v36
	v_sub_u32_e32 v192, v190, v0
	s_waitcnt lgkmcnt(0)
	v_add_f32_e32 v34, v34, v35
	v_add_f32_e32 v34, v36, v34
	v_div_scale_f32 v35, s[2:3], v34, v34, 1.0
	v_rcp_f32_e32 v36, v35
	s_movk_i32 s2, 0x188
	v_fma_f32 v0, -v35, v36, 1.0
	v_fmac_f32_e32 v36, v0, v36
	v_div_scale_f32 v0, vcc, 1.0, v34, 1.0
	v_mul_f32_e32 v37, v0, v36
	v_fma_f32 v38, -v35, v37, v0
	v_fmac_f32_e32 v37, v38, v36
	v_fma_f32 v0, -v35, v37, v0
	v_div_fmas_f32 v0, v0, v36, v37
	v_div_fixup_f32 v82, v0, v34, 1.0
	v_mad_u32_u24 v0, v187, s2, v192
	s_and_b64 vcc, exec, s[38:39]
	v_add_u32_e32 v83, 0x6800, v0
	v_add_u32_e32 v193, 0x9800, v0
	s_cbranch_vccnz .LBB0_481
	v_pk_mul_f32 v[12:13], v[12:13], v[82:83] op_sel_hi:[1,0]
	v_pk_mul_f32 v[34:35], v[50:51], v[82:83] op_sel_hi:[1,0]
	v_pk_mul_f32 v[10:11], v[10:11], v[82:83] op_sel_hi:[1,0]
	v_pk_mul_f32 v[14:15], v[14:15], v[82:83] op_sel_hi:[1,0]
	s_nop 0
	s_nop 0
	v_cvt_pk_bf16_f32 v53, v15, v35
	v_cvt_pk_bf16_f32 v51, v11, v13
	v_cvt_pk_bf16_f32 v50, v10, v12
	ds_read2_b64 v[10:13], v83 offset0:128 offset1:130
	v_cvt_pk_bf16_f32 v52, v14, v34
	s_nop 0
	s_nop 0
	v_pk_mul_f32 v[8:9], v[8:9], v[82:83] op_sel_hi:[1,0]
	v_pk_mul_f32 v[4:5], v[4:5], v[82:83] op_sel_hi:[1,0]
	s_waitcnt lgkmcnt(0)
	v_mfma_f32_32x32x16_bf16 v[34:49], v[10:13], v[50:53], 0
	ds_read2_b64 v[10:13], v193 offset0:160 offset1:162
	ds_read2_b64 v[194:197], v83 offset0:132 offset1:134
	v_mul_f32_e64 v6, v6, v82
	v_mul_f32_e64 v7, v7, v82
	s_nop 0
	s_nop 0
	s_nop 0
	v_pk_mul_f32 v[2:3], v[2:3], v[82:83] op_sel_hi:[1,0]
	s_nop 0
	s_waitcnt lgkmcnt(1)
	v_mfma_f32_32x32x16_bf16 v[50:65], v[10:13], v[50:53], 0
	s_nop 0
	s_nop 0
	s_nop 0
	s_nop 0
	s_nop 0
	s_nop 0
	s_nop 0
	s_nop 0
	v_cvt_pk_bf16_f32 v2, v2, v4
	v_cvt_pk_bf16_f32 v4, v6, v8
	s_nop 0
	s_nop 0
	s_nop 0
	s_nop 0
	s_nop 0
	s_nop 0
	s_nop 0
	v_cvt_pk_bf16_f32 v3, v3, v5
	v_cvt_pk_bf16_f32 v5, v7, v9
	ds_read2_b64 v[6:9], v193 offset0:164 offset1:166
	s_nop 0
	s_nop 0
	s_nop 0
	s_nop 0
	s_nop 0
	s_waitcnt lgkmcnt(1)
	s_nop 0
	v_mfma_f32_32x32x16_bf16 v[34:49], v[194:197], v[2:5], v[34:49]
	s_waitcnt lgkmcnt(0)
	v_mfma_f32_32x32x16_bf16 v[50:65], v[6:9], v[2:5], v[50:65]
	s_branch .LBB0_482

; #define LAS __attribute__((address_space(3)))
; __device__ __forceinline__ unsigned pk2(float lo, float hi) { return f2bf(lo) | (f2bf(hi) << 16); }
; __device__ __forceinline__ void attn_unit(const Args& A, const Ctx& C0, int l, int u_qrow0, int u_nq, int u_krow0, int u_krow1, int u_krow2, int u_g, const float* u_ck, const float* u_cv, unsigned u_vmask) {
;     ...
;         for (int kt = 0; kt < 6; ++kt) {
;             if ((u.vmask >> kt) & 1u) {
; #pragma unroll
;                 for (int s = 0; s < 2; ++s) {
;                     union { bf16x8 v; unsigned w[4]; } pf;
; #pragma unroll
;                     for (int e = 0; e < 4; ++e) pf.w[e] = pk2(sacc[kt][8 * s + 2 * e] * inv, sacc[kt][8 * s + 2 * e + 1] * inv);
; #pragma unroll
;                     for (int dt = 0; dt < 2; ++dt) { const LAS bf16* vp = Vt + (dt * 32 + li) * VP + kt * 32 + 16 * s + 4 * h;
;                         union { bf16x8 v; v2u w[2]; } vf; vf.w[0] = *(const LAS v2u*)vp; vf.w[1] = *(const LAS v2u*)(vp + 8);
;                         oacc[dt] = __builtin_amdgcn_mfma_f32_32x32x16_bf16(vf.v, pf.v, oacc[dt], 0, 0, 0); }
;                 }
;             }
.LBB0_482:
	s_and_b64 vcc, exec, s[40:41]
	s_cbranch_vccnz .LBB0_484
	v_pk_mul_f32 v[4:5], v[178:179], v[82:83] op_sel_hi:[1,0]
	v_pk_mul_f32 v[8:9], v[182:183], v[82:83] op_sel_hi:[1,0]
	v_pk_mul_f32 v[2:3], v[176:177], v[82:83] op_sel_hi:[1,0]
	v_pk_mul_f32 v[6:7], v[180:181], v[82:83] op_sel_hi:[1,0]
	v_bfe_u32 v0, v9, 16, 1
	s_nop 0
	v_bfe_u32 v11, v5, 16, 1
	v_bfe_u32 v12, v4, 16, 1
	v_add3_u32 v12, v4, v12, s33
	v_add3_u32 v11, v5, v11, s33
	s_nop 0
	v_add3_u32 v0, v9, v0, s33
	v_bfe_u32 v4, v2, 16, 1
	v_bfe_u32 v5, v3, 16, 1
	s_nop 0
	v_bfe_u32 v10, v7, 16, 1
	v_add3_u32 v7, v7, v10, s33
	s_nop 0
	v_add3_u32 v9, v3, v5, s33
	v_add3_u32 v10, v2, v4, s33
	ds_read2_b64 v[2:5], v83 offset0:136 offset1:138
	v_lshrrev_b32_e32 v10, 16, v10
	v_lshrrev_b32_e32 v13, 16, v9
	v_lshrrev_b32_e32 v7, 16, v7
	v_and_or_b32 v9, v0, s96, v7
	v_cvt_pk_bf16_f32 v8, v6, v8
	v_and_or_b32 v7, v11, s96, v13
	v_and_or_b32 v6, v12, s96, v10
	s_waitcnt lgkmcnt(0)
	s_nop 0
	v_mfma_f32_32x32x16_bf16 v[34:49], v[2:5], v[6:9], v[34:49]
	ds_read2_b64 v[2:5], v193 offset0:168 offset1:170
	ds_read2_b64 v[10:13], v83 offset0:140 offset1:142
	s_waitcnt lgkmcnt(1)
	v_mfma_f32_32x32x16_bf16 v[50:65], v[2:5], v[6:9], v[50:65]
	v_mul_f32_e64 v8, v174, v82
	v_mul_f32_e64 v9, v175, v82
	v_mul_f32_e64 v4, v170, v82
	v_mul_f32_e64 v5, v171, v82
	v_mul_f32_e64 v6, v172, v82
	v_mul_f32_e64 v7, v173, v82
	s_nop 0
	v_pk_mul_f32 v[2:3], v[168:169], v[82:83] op_sel_hi:[1,0]
	s_nop 0
	s_nop 0
	s_nop 0
	s_nop 0
	s_nop 0
	s_nop 0
	s_nop 0
	s_nop 0
	s_nop 0
	s_nop 0
	s_nop 0
	v_cvt_pk_bf16_f32 v2, v2, v4
	v_cvt_pk_bf16_f32 v4, v6, v8
	s_nop 0
	s_nop 0
	s_nop 0
	s_nop 0
	s_nop 0
	s_nop 0
	s_nop 0
	v_cvt_pk_bf16_f32 v3, v3, v5
	v_cvt_pk_bf16_f32 v5, v7, v9
	ds_read2_b64 v[6:9], v193 offset0:172 offset1:174
	s_nop 0
	s_nop 0
	s_nop 0
	s_nop 0
	s_nop 0
	s_waitcnt lgkmcnt(1)
	s_nop 0
	v_mfma_f32_32x32x16_bf16 v[34:49], v[10:13], v[2:5], v[34:49]
	s_waitcnt lgkmcnt(0)
	v_mfma_f32_32x32x16_bf16 v[50:65], v[6:9], v[2:5], v[50:65]
.LBB0_484:
	s_and_b64 vcc, exec, s[44:45]
	s_cbranch_vccnz .LBB0_486
	v_pk_mul_f32 v[4:5], v[128:129], v[82:83] op_sel_hi:[1,0]
	v_pk_mul_f32 v[8:9], v[166:167], v[82:83] op_sel_hi:[1,0]
	v_pk_mul_f32 v[2:3], v[32:33], v[82:83] op_sel_hi:[1,0]
	v_pk_mul_f32 v[6:7], v[164:165], v[82:83] op_sel_hi:[1,0]
	v_bfe_u32 v0, v9, 16, 1
	s_nop 0
	v_bfe_u32 v11, v5, 16, 1
	v_bfe_u32 v12, v4, 16, 1
	v_add3_u32 v12, v4, v12, s33
	v_add3_u32 v11, v5, v11, s33
	s_nop 0
	v_add3_u32 v0, v9, v0, s33
	v_bfe_u32 v4, v2, 16, 1
	v_bfe_u32 v5, v3, 16, 1
	s_nop 0
	v_bfe_u32 v10, v7, 16, 1
	v_add3_u32 v7, v7, v10, s33
	s_nop 0
	v_add3_u32 v9, v3, v5, s33
	v_add3_u32 v10, v2, v4, s33
	ds_read2_b64 v[2:5], v83 offset0:144 offset1:146
	v_lshrrev_b32_e32 v10, 16, v10
	v_lshrrev_b32_e32 v13, 16, v9
	v_lshrrev_b32_e32 v7, 16, v7
	v_and_or_b32 v9, v0, s96, v7
	v_cvt_pk_bf16_f32 v8, v6, v8
	v_and_or_b32 v7, v11, s96, v13
	v_and_or_b32 v6, v12, s96, v10
	s_waitcnt lgkmcnt(0)
	s_nop 0
	v_mfma_f32_32x32x16_bf16 v[34:49], v[2:5], v[6:9], v[34:49]
	ds_read2_b64 v[2:5], v193 offset0:176 offset1:178
	ds_read2_b64 v[10:13], v83 offset0:148 offset1:150
	s_waitcnt lgkmcnt(1)
	v_mfma_f32_32x32x16_bf16 v[50:65], v[2:5], v[6:9], v[50:65]
	v_mul_f32_e64 v8, v30, v82
	v_mul_f32_e64 v9, v31, v82
	v_mul_f32_e64 v4, v26, v82
	v_mul_f32_e64 v5, v27, v82
	v_mul_f32_e64 v6, v28, v82
	v_mul_f32_e64 v7, v29, v82
	s_nop 0
	v_pk_mul_f32 v[2:3], v[24:25], v[82:83] op_sel_hi:[1,0]
	s_nop 0
	s_nop 0
	s_nop 0
	s_nop 0
	s_nop 0
	s_nop 0
	s_nop 0
	s_nop 0
	s_nop 0
	s_nop 0
	s_nop 0
	v_cvt_pk_bf16_f32 v2, v2, v4
	v_cvt_pk_bf16_f32 v4, v6, v8
	s_nop 0
	s_nop 0
	s_nop 0
	s_nop 0
	s_nop 0
	s_nop 0
	s_nop 0
	v_cvt_pk_bf16_f32 v3, v3, v5
	v_cvt_pk_bf16_f32 v5, v7, v9
	ds_read2_b64 v[6:9], v193 offset0:180 offset1:182
	s_nop 0
	s_nop 0
	s_nop 0
	s_nop 0
	s_nop 0
	s_waitcnt lgkmcnt(1)
	s_nop 0
	v_mfma_f32_32x32x16_bf16 v[34:49], v[10:13], v[2:5], v[34:49]
	s_waitcnt lgkmcnt(0)
	v_mfma_f32_32x32x16_bf16 v[50:65], v[6:9], v[2:5], v[50:65]
.LBB0_486:
	v_mov_b32_e32 v14, 0x3100
	s_and_b64 vcc, exec, s[60:61]
	v_mul_u32_u24_e32 v0, 0x188, v187
	v_mad_u32_u24 v128, v187, s2, v14
	s_cbranch_vccz .LBB0_488
	v_pk_mul_f32 v[4:5], v[18:19], v[82:83] op_sel_hi:[1,0]
	v_pk_mul_f32 v[8:9], v[22:23], v[82:83] op_sel_hi:[1,0]
	v_pk_mul_f32 v[2:3], v[16:17], v[82:83] op_sel_hi:[1,0]
	v_pk_mul_f32 v[6:7], v[20:21], v[82:83] op_sel_hi:[1,0]
	s_nop 0
	s_nop 0
	s_nop 0
	s_nop 0
	s_nop 0
	s_nop 0
	s_nop 0
	s_nop 0
	s_nop 0
	s_nop 0
	s_nop 0
	v_cvt_pk_bf16_f32 v167, v3, v5
	v_cvt_pk_bf16_f32 v166, v2, v4
	ds_read2_b64 v[2:5], v83 offset0:152 offset1:154
	v_cvt_pk_bf16_f32 v169, v7, v9
	v_cvt_pk_bf16_f32 v168, v6, v8
	s_nop 0
	s_nop 0
	v_mad_u32_u24 v164, v187, s2, v14
	v_pk_mul_f32 v[122:123], v[122:123], v[82:83] op_sel_hi:[1,0]
	s_waitcnt lgkmcnt(0)
	v_mfma_f32_32x32x16_bf16 v[18:33], v[2:5], v[166:169], v[34:49]
	v_add_u32_e32 v2, v192, v164
	v_add_u32_e32 v129, 0x6800, v2
	ds_read2_b64 v[170:173], v129 offset0:152 offset1:154
	ds_read2_b64 v[174:177], v83 offset0:156 offset1:158
	v_mul_f32_e64 v124, v124, v82
	v_mul_f32_e64 v125, v125, v82
	v_pk_mul_f32 v[126:127], v[126:127], v[82:83] op_sel_hi:[1,0]
	v_pk_mul_f32 v[120:121], v[120:121], v[82:83] op_sel_hi:[1,0]
	s_nop 0
	s_waitcnt lgkmcnt(1)
	v_mfma_f32_32x32x16_bf16 v[2:17], v[170:173], v[166:169], v[50:65]
	s_nop 0
	s_nop 0
	s_nop 0
	s_nop 0
	s_nop 0
	s_nop 0
	s_nop 0
	s_nop 0
	ds_read2_b64 v[166:169], v129 offset0:156 offset1:158
	s_nop 0
	s_nop 0
	s_nop 0
	v_cvt_pk_bf16_f32 v125, v125, v127
	s_nop 0
	s_nop 0
	s_nop 0
	s_nop 0
	s_nop 0
	s_nop 0
	s_nop 0
	v_cvt_pk_bf16_f32 v124, v124, v126
	v_cvt_pk_bf16_f32 v123, v121, v123
	v_cvt_pk_bf16_f32 v122, v120, v122
	v_mul_u32_u24_e32 v120, 0x188, v187
	s_waitcnt lgkmcnt(1)
	v_mfma_f32_32x32x16_bf16 v[18:33], v[174:177], v[122:125], v[18:33]
	s_waitcnt lgkmcnt(0)
	v_mfma_f32_32x32x16_bf16 v[2:17], v[166:169], v[122:125], v[2:17]
	s_cbranch_execz .LBB0_489
	s_branch .LBB0_490

; #define LAS __attribute__((address_space(3)))
; __device__ __forceinline__ unsigned pk2(float lo, float hi) { return f2bf(lo) | (f2bf(hi) << 16); }
; __device__ __forceinline__ void attn_unit(const Args& A, const Ctx& C0, int l, int u_qrow0, int u_nq, int u_krow0, int u_krow1, int u_krow2, int u_g, const float* u_ck, const float* u_cv, unsigned u_vmask) {
;     ...
;         for (int kt = 0; kt < 6; ++kt) {
;             if ((u.vmask >> kt) & 1u) {
; #pragma unroll
;                 for (int s = 0; s < 2; ++s) {
;                     union { bf16x8 v; unsigned w[4]; } pf;
; #pragma unroll
;                     for (int e = 0; e < 4; ++e) pf.w[e] = pk2(sacc[kt][8 * s + 2 * e] * inv, sacc[kt][8 * s + 2 * e + 1] * inv);
; #pragma unroll
;                     for (int dt = 0; dt < 2; ++dt) { const LAS bf16* vp = Vt + (dt * 32 + li) * VP + kt * 32 + 16 * s + 4 * h;
;                         union { bf16x8 v; v2u w[2]; } vf; vf.w[0] = *(const LAS v2u*)vp; vf.w[1] = *(const LAS v2u*)(vp + 8);
;                         oacc[dt] = __builtin_amdgcn_mfma_f32_32x32x16_bf16(vf.v, pf.v, oacc[dt], 0, 0, 0); }
;                 }
;             }
.LBB0_490:
	v_mov_b32_e32 v83, v82
	v_pk_mul_f32 v[36:37], v[94:95], v[82:83]
	v_pk_mul_f32 v[40:41], v[118:119], v[82:83]
	v_pk_mul_f32 v[34:35], v[92:93], v[82:83]
	v_pk_mul_f32 v[38:39], v[96:97], v[82:83]
	s_nop 0
	v_bfe_u32 v44, v36, 16, 1
	v_add3_u32 v44, v36, v44, s33
	s_nop 0
	v_bfe_u32 v36, v34, 16, 1
	v_bfe_u32 v42, v39, 16, 1
	v_bfe_u32 v0, v41, 16, 1
	v_bfe_u32 v43, v37, 16, 1
	v_add3_u32 v39, v39, v42, s33
	v_add3_u32 v42, v34, v36, s33
	v_add_u32_e32 v34, v192, v120
	v_add3_u32 v43, v37, v43, s33
	v_add3_u32 v0, v41, v0, s33
	v_bfe_u32 v37, v35, 16, 1
	s_nop 0
	v_add_u32_e32 v129, 0x6800, v34
	v_add3_u32 v41, v35, v37, s33
	ds_read2_b64 v[34:37], v129 offset0:160 offset1:162
	v_lshrrev_b32_e32 v39, 16, v39
	v_lshrrev_b32_e32 v42, 16, v42
	v_lshrrev_b32_e32 v45, 16, v41
	v_and_or_b32 v41, v0, s96, v39
	v_add_u32_e32 v0, v192, v164
	v_cvt_pk_bf16_f32 v40, v38, v40
	v_and_or_b32 v39, v43, s96, v45
	v_and_or_b32 v38, v44, s96, v42
	v_add_u32_e32 v128, 0x6800, v0
	s_and_b64 vcc, exec, s[42:43]
	s_waitcnt lgkmcnt(0)
	v_mfma_f32_32x32x16_bf16 v[18:33], v[34:37], v[38:41], v[18:33]
	ds_read2_b64 v[34:37], v128 offset0:160 offset1:162
	ds_read2_b64 v[42:45], v129 offset0:164 offset1:166
	s_waitcnt lgkmcnt(1)
	v_mfma_f32_32x32x16_bf16 v[2:17], v[34:37], v[38:41], v[2:17]
	v_mul_f32_e64 v40, v90, v82
	v_mul_f32_e64 v41, v91, v83
	v_mul_f32_e64 v36, v86, v82
	v_mul_f32_e64 v37, v87, v83
	v_mul_f32_e64 v38, v88, v82
	v_mul_f32_e64 v39, v89, v83
	s_nop 0
	s_nop 0
	s_nop 0
	s_nop 0
	s_nop 0
	v_pk_mul_f32 v[34:35], v[84:85], v[82:83]
	s_nop 0
	s_nop 0
	s_nop 0
	s_nop 0
	s_nop 0
	s_nop 0
	s_nop 0
	v_cvt_pk_bf16_f32 v34, v34, v36
	v_cvt_pk_bf16_f32 v36, v38, v40
	s_nop 0
	s_nop 0
	s_nop 0
	s_nop 0
	s_nop 0
	s_nop 0
	s_nop 0
	v_cvt_pk_bf16_f32 v35, v35, v37
	v_cvt_pk_bf16_f32 v37, v39, v41
	ds_read2_b64 v[38:41], v128 offset0:164 offset1:166
	s_nop 0
	s_nop 0
	s_nop 0
	s_nop 0
	s_nop 0
	s_waitcnt lgkmcnt(1)
	s_nop 0
	v_mfma_f32_32x32x16_bf16 v[18:33], v[42:45], v[34:37], v[18:33]
	s_waitcnt lgkmcnt(0)
	v_mfma_f32_32x32x16_bf16 v[2:17], v[38:41], v[34:37], v[2:17]
	s_cbranch_vccnz .LBB0_492
	v_pk_mul_f32 v[36:37], v[76:77], v[82:83]
	v_pk_mul_f32 v[40:41], v[80:81], v[82:83]
	v_pk_mul_f32 v[34:35], v[74:75], v[82:83]
	v_pk_mul_f32 v[38:39], v[78:79], v[82:83]
	v_bfe_u32 v0, v41, 16, 1
	s_nop 0
	v_bfe_u32 v43, v37, 16, 1
	v_bfe_u32 v44, v36, 16, 1
	v_add3_u32 v44, v36, v44, s33
	v_add3_u32 v43, v37, v43, s33
	s_nop 0
	v_add3_u32 v0, v41, v0, s33
	v_bfe_u32 v36, v34, 16, 1
	v_bfe_u32 v37, v35, 16, 1
	s_nop 0
	v_bfe_u32 v42, v39, 16, 1
	v_add3_u32 v39, v39, v42, s33
	s_nop 0
	v_add3_u32 v41, v35, v37, s33
	v_add3_u32 v42, v34, v36, s33
	ds_read2_b64 v[34:37], v129 offset0:168 offset1:170
	v_lshrrev_b32_e32 v42, 16, v42
	v_lshrrev_b32_e32 v45, 16, v41
	v_lshrrev_b32_e32 v39, 16, v39
	v_and_or_b32 v41, v0, s96, v39
	v_cvt_pk_bf16_f32 v40, v38, v40
	v_and_or_b32 v39, v43, s96, v45
	v_and_or_b32 v38, v44, s96, v42
	s_waitcnt lgkmcnt(0)
	s_nop 0
	v_mfma_f32_32x32x16_bf16 v[18:33], v[34:37], v[38:41], v[18:33]
	ds_read2_b64 v[34:37], v128 offset0:168 offset1:170
	ds_read2_b64 v[42:45], v129 offset0:172 offset1:174
	s_waitcnt lgkmcnt(1)
	v_mfma_f32_32x32x16_bf16 v[2:17], v[34:37], v[38:41], v[2:17]
	v_mul_f32_e64 v40, v72, v82
	v_mul_f32_e64 v41, v73, v83
	v_mul_f32_e64 v36, v68, v82
	v_mul_f32_e64 v37, v69, v83
	v_mul_f32_e64 v38, v70, v82
	v_mul_f32_e64 v39, v71, v83
	s_nop 0
	s_nop 0
	s_nop 0
	s_nop 0
	s_nop 0
	v_pk_mul_f32 v[34:35], v[66:67], v[82:83]
	s_nop 0
	s_nop 0
	s_nop 0
	s_nop 0
	s_nop 0
	s_nop 0
	s_nop 0
	v_cvt_pk_bf16_f32 v34, v34, v36
	v_cvt_pk_bf16_f32 v36, v38, v40
	s_nop 0
	s_nop 0
	s_nop 0
	s_nop 0
	s_nop 0
	s_nop 0
	s_nop 0
	v_cvt_pk_bf16_f32 v35, v35, v37
	v_cvt_pk_bf16_f32 v37, v39, v41
	ds_read2_b64 v[38:41], v128 offset0:172 offset1:174
	s_nop 0
	s_nop 0
	s_nop 0
	s_nop 0
	s_nop 0
	s_waitcnt lgkmcnt(1)
	s_nop 0
	v_mfma_f32_32x32x16_bf16 v[18:33], v[42:45], v[34:37], v[18:33]
	s_waitcnt lgkmcnt(0)
	v_mfma_f32_32x32x16_bf16 v[2:17], v[38:41], v[34:37], v[2:17]

; __device__ __forceinline__ float shflx(float v, int mask, int lane) { return __int_as_float(__builtin_amdgcn_ds_bpermute((lane ^ mask) << 2, __float_as_int(v))); }
; __device__ __forceinline__ void attn_unit(const Args& A, const Ctx& C0, int l, int u_qrow0, int u_nq, int u_krow0, int u_krow1, int u_krow2, int u_g, const float* u_ck, const float* u_cv, unsigned u_vmask) {
;     ...
;         float mx = sink;
; #pragma unroll
;         for (int kt = 0; kt < 6; ++kt) { const bool valid = (u.vmask >> kt) & 1u;
; #pragma unroll
;             for (int r = 0; r < 16; ++r) { const int j = kt * 32 + (r & 3) + 8 * (r >> 2) + 4 * h;
;                 const float lg = valid ? sacc[kt][r] * 0.125f + bL[j - qi + 63] : -1e30f; sacc[kt][r] = lg; mx = fmaxf(mx, lg); }
;             asm volatile("" ::: "memory"); }
;         mx = fmaxf(mx, shflx(mx, 32, C.lane));
;         float sum = 0.f;
; #pragma unroll
;         for (int kt = 0; kt < 6; ++kt)
; #pragma unroll
;             for (int r = 0; r < 16; ++r) { const float e = __expf(sacc[kt][r] - mx); sacc[kt][r] = e; sum += e; }
;         sum += shflx(sum, 32, C.lane); sum += __expf(sink - mx);
.LBB0_578:
	v_max3_f32 v18, v186, v107, v106
	v_max3_f32 v18, v18, v83, v82
	v_max3_f32 v18, v18, v85, v84
	v_max3_f32 v18, v18, v87, v86
	v_max3_f32 v18, v18, v89, v88
	v_max3_f32 v18, v18, v91, v90
	v_max3_f32 v18, v18, v93, v92
	v_max3_f32 v18, v18, v95, v94
	v_max3_f32 v18, v18, v97, v96
	v_max3_f32 v18, v18, v67, v66
	v_max3_f32 v18, v18, v69, v68
	v_max3_f32 v18, v18, v71, v70
	v_max3_f32 v18, v18, v73, v72
	v_max3_f32 v18, v18, v75, v74
	v_max3_f32 v18, v18, v77, v76
	v_max3_f32 v18, v18, v79, v78
	v_max3_f32 v18, v18, v81, v80
	v_max3_f32 v18, v18, v103, v102
	v_max3_f32 v18, v18, v105, v104
	v_max3_f32 v18, v18, v109, v108
	v_max3_f32 v18, v18, v111, v110
	v_max3_f32 v18, v18, v59, v58
	v_max3_f32 v18, v18, v61, v60
	v_max3_f32 v18, v18, v63, v62
	v_max3_f32 v18, v18, v65, v64
	v_max3_f32 v18, v18, v149, v148
	v_max3_f32 v18, v18, v151, v150
	v_max3_f32 v18, v18, v153, v152
	v_max3_f32 v18, v18, v156, v154
	v_max3_f32 v18, v18, v160, v158
	v_max3_f32 v18, v18, v164, v162
	v_max3_f32 v18, v18, v168, v166
	s_waitcnt lgkmcnt(0)
	v_fmamk_f32 v48, v2, 0x3e000000, v48
	v_fmac_f32_e32 v49, 0x3e000000, v3
	v_max3_f32 v2, v18, v48, v49
	v_fmamk_f32 v46, v4, 0x3e000000, v46
	v_fmac_f32_e32 v47, 0x3e000000, v5
	v_max3_f32 v2, v2, v46, v47
	v_fmamk_f32 v44, v6, 0x3e000000, v44
	v_fmac_f32_e32 v45, 0x3e000000, v7
	v_max3_f32 v2, v2, v44, v45
	v_fmamk_f32 v42, v8, 0x3e000000, v42
	v_fmac_f32_e32 v43, 0x3e000000, v9
	v_max3_f32 v2, v2, v42, v43
	v_fmamk_f32 v40, v10, 0x3e000000, v40
	v_fmac_f32_e32 v41, 0x3e000000, v11
	v_max3_f32 v2, v2, v40, v41
	v_fmamk_f32 v38, v12, 0x3e000000, v38
	v_fmac_f32_e32 v39, 0x3e000000, v13
	v_max3_f32 v2, v2, v38, v39
	v_fmamk_f32 v36, v14, 0x3e000000, v36
	v_fmac_f32_e32 v37, 0x3e000000, v15
	v_max3_f32 v2, v2, v36, v37
	v_fmamk_f32 v34, v16, 0x3e000000, v34
	v_fmac_f32_e32 v35, 0x3e000000, v17
	v_max3_f32 v2, v2, v34, v35
	v_max3_f32 v2, v2, v157, v155
	v_max3_f32 v2, v2, v161, v159
	v_max3_f32 v2, v2, v165, v163
	v_max3_f32 v2, v2, v169, v167
	v_max3_f32 v2, v2, v171, v170
	v_max3_f32 v2, v2, v173, v172
	v_max3_f32 v2, v2, v175, v174
	v_max3_f32 v2, v2, v177, v176
	ds_bpermute_b32 v3, v189, v2
	s_waitcnt lgkmcnt(0)
	v_max_f32_e32 v3, v3, v3
	v_max_f32_e32 v178, v2, v3
	v_sub_f32_e32 v3, v85, v178
	v_mul_f32_e32 v3, 0x3fb8aa3b, v3
	v_exp_f32_e32 v54, v3
	v_sub_f32_e32 v3, v84, v178
	v_mul_f32_e32 v3, 0x3fb8aa3b, v3
	v_exp_f32_e32 v56, v3
	v_sub_f32_e32 v3, v87, v178
	v_mul_f32_e32 v3, 0x3fb8aa3b, v3
	v_exp_f32_e32 v55, v3
	v_sub_f32_e32 v3, v86, v178
	v_mul_f32_e32 v3, 0x3fb8aa3b, v3
	v_exp_f32_e32 v57, v3
	v_sub_f32_e32 v3, v89, v178
	v_mul_f32_e32 v3, 0x3fb8aa3b, v3
	v_exp_f32_e32 v120, v3
	v_sub_f32_e32 v3, v88, v178
	v_mul_f32_e32 v3, 0x3fb8aa3b, v3
	v_exp_f32_e32 v122, v3
	v_sub_f32_e32 v3, v91, v178
	v_mul_f32_e32 v3, 0x3fb8aa3b, v3
	v_exp_f32_e32 v121, v3
	v_sub_f32_e32 v3, v90, v178
	v_mul_f32_e32 v3, 0x3fb8aa3b, v3
	v_exp_f32_e32 v123, v3
	v_sub_f32_e32 v3, v93, v178
	v_mul_f32_e32 v3, 0x3fb8aa3b, v3
	v_exp_f32_e32 v124, v3
	v_sub_f32_e32 v3, v92, v178
	v_mul_f32_e32 v3, 0x3fb8aa3b, v3
	v_exp_f32_e32 v126, v3
	v_sub_f32_e32 v3, v95, v178
	v_mul_f32_e32 v3, 0x3fb8aa3b, v3
	v_exp_f32_e32 v125, v3
	v_sub_f32_e32 v3, v94, v178
	v_mul_f32_e32 v3, 0x3fb8aa3b, v3
	v_exp_f32_e32 v127, v3
	v_sub_f32_e32 v3, v97, v178
	v_mul_f32_e32 v3, 0x3fb8aa3b, v3
	v_exp_f32_e32 v112, v3
	v_sub_f32_e32 v3, v96, v178
	v_mul_f32_e32 v3, 0x3fb8aa3b, v3
	v_exp_f32_e32 v114, v3
	v_sub_f32_e32 v3, v67, v178
	v_mul_f32_e32 v3, 0x3fb8aa3b, v3
	v_exp_f32_e32 v113, v3
	v_sub_f32_e32 v3, v66, v178
	v_mul_f32_e32 v3, 0x3fb8aa3b, v3
	v_exp_f32_e32 v115, v3
	v_sub_f32_e32 v3, v69, v178
	v_mul_f32_e32 v3, 0x3fb8aa3b, v3
	v_exp_f32_e32 v116, v3
	v_sub_f32_e32 v3, v68, v178
	v_mul_f32_e32 v3, 0x3fb8aa3b, v3
	v_sub_f32_e32 v2, v107, v178
	v_exp_f32_e32 v118, v3
	v_sub_f32_e32 v3, v71, v178
	v_mul_f32_e32 v2, 0x3fb8aa3b, v2
	v_mul_f32_e32 v3, 0x3fb8aa3b, v3
	v_exp_f32_e32 v50, v2
	v_sub_f32_e32 v2, v106, v178
	v_exp_f32_e32 v117, v3
	v_sub_f32_e32 v3, v70, v178
	v_mul_f32_e32 v2, 0x3fb8aa3b, v2
	v_mul_f32_e32 v3, 0x3fb8aa3b, v3
	v_exp_f32_e32 v52, v2
	v_sub_f32_e32 v2, v83, v178
	v_exp_f32_e32 v119, v3
	v_sub_f32_e32 v3, v73, v178
	v_mul_f32_e32 v2, 0x3fb8aa3b, v2
	v_mul_f32_e32 v3, 0x3fb8aa3b, v3
	v_exp_f32_e32 v51, v2
	v_sub_f32_e32 v2, v82, v178
	v_exp_f32_e32 v26, v3
	v_sub_f32_e32 v3, v72, v178
	v_mul_f32_e32 v2, 0x3fb8aa3b, v2
	v_mul_f32_e32 v3, 0x3fb8aa3b, v3
	v_exp_f32_e32 v53, v2
	v_exp_f32_e32 v28, v3
	v_sub_f32_e32 v3, v75, v178
	v_add_f32_e32 v2, 0, v50
	v_mul_f32_e32 v3, 0x3fb8aa3b, v3
	v_add_f32_e32 v2, v52, v2
	v_exp_f32_e32 v27, v3
	v_sub_f32_e32 v3, v74, v178
	v_add_f32_e32 v2, v51, v2
	v_mul_f32_e32 v3, 0x3fb8aa3b, v3
	v_add_f32_e32 v2, v53, v2
	v_exp_f32_e32 v29, v3
	v_sub_f32_e32 v3, v77, v178
	v_add_f32_e32 v2, v54, v2
	v_mul_f32_e32 v3, 0x3fb8aa3b, v3
	v_add_f32_e32 v2, v56, v2
	v_exp_f32_e32 v30, v3
	v_sub_f32_e32 v3, v76, v178
	v_add_f32_e32 v2, v55, v2
	v_mul_f32_e32 v3, 0x3fb8aa3b, v3
	v_add_f32_e32 v2, v57, v2
	v_exp_f32_e32 v32, v3
	v_sub_f32_e32 v3, v79, v178
	v_add_f32_e32 v2, v120, v2
	v_mul_f32_e32 v3, 0x3fb8aa3b, v3
	v_add_f32_e32 v2, v122, v2
	v_exp_f32_e32 v31, v3
	v_sub_f32_e32 v3, v78, v178
	v_add_f32_e32 v2, v121, v2
	v_mul_f32_e32 v3, 0x3fb8aa3b, v3
	v_add_f32_e32 v2, v123, v2
	v_exp_f32_e32 v33, v3
	v_sub_f32_e32 v3, v81, v178
	v_add_f32_e32 v2, v124, v2
	v_mul_f32_e32 v3, 0x3fb8aa3b, v3
	v_add_f32_e32 v2, v126, v2
	v_exp_f32_e32 v18, v3
	v_sub_f32_e32 v3, v80, v178
	v_add_f32_e32 v2, v125, v2
	v_mul_f32_e32 v3, 0x3fb8aa3b, v3
	v_add_f32_e32 v2, v127, v2
	v_exp_f32_e32 v20, v3
	v_sub_f32_e32 v3, v103, v178
; __device__ __forceinline__ float shflx(float v, int mask, int lane) { return __int_as_float(__builtin_amdgcn_ds_bpermute((lane ^ mask) << 2, __float_as_int(v))); }
; __device__ __forceinline__ void attn_unit(const Args& A, const Ctx& C0, int l, int u_qrow0, int u_nq, int u_krow0, int u_krow1, int u_krow2, int u_g, const float* u_ck, const float* u_cv, unsigned u_vmask) {
;     ...
;         float sum = 0.f;
; #pragma unroll
;         for (int kt = 0; kt < 6; ++kt)
; #pragma unroll
;             for (int r = 0; r < 16; ++r) { const float e = __expf(sacc[kt][r] - mx); sacc[kt][r] = e; sum += e; }
;         sum += shflx(sum, 32, C.lane); sum += __expf(sink - mx);
	v_add_f32_e32 v2, v112, v2
	v_mul_f32_e32 v3, 0x3fb8aa3b, v3
	v_add_f32_e32 v2, v114, v2
	v_exp_f32_e32 v19, v3
	v_sub_f32_e32 v3, v102, v178
	v_add_f32_e32 v2, v113, v2
	v_mul_f32_e32 v3, 0x3fb8aa3b, v3
	v_add_f32_e32 v2, v115, v2
	v_exp_f32_e32 v21, v3
	v_sub_f32_e32 v3, v105, v178
	v_add_f32_e32 v2, v116, v2
	v_mul_f32_e32 v3, 0x3fb8aa3b, v3
	v_add_f32_e32 v2, v118, v2
	v_exp_f32_e32 v22, v3
	v_sub_f32_e32 v3, v104, v178
	v_add_f32_e32 v2, v117, v2
	v_mul_f32_e32 v3, 0x3fb8aa3b, v3
	v_add_f32_e32 v2, v119, v2
	v_exp_f32_e32 v24, v3
	v_sub_f32_e32 v3, v109, v178
	v_add_f32_e32 v2, v26, v2
	v_mul_f32_e32 v3, 0x3fb8aa3b, v3
	v_add_f32_e32 v2, v28, v2
	v_exp_f32_e32 v23, v3
	v_sub_f32_e32 v3, v108, v178
	v_add_f32_e32 v2, v27, v2
	v_mul_f32_e32 v3, 0x3fb8aa3b, v3
	v_add_f32_e32 v2, v29, v2
	v_exp_f32_e32 v25, v3
	v_sub_f32_e32 v3, v111, v178
	v_add_f32_e32 v2, v30, v2
	v_mul_f32_e32 v3, 0x3fb8aa3b, v3
	v_add_f32_e32 v2, v32, v2
	v_exp_f32_e32 v10, v3
	v_sub_f32_e32 v3, v110, v178
	v_add_f32_e32 v2, v31, v2
	v_mul_f32_e32 v3, 0x3fb8aa3b, v3
	v_add_f32_e32 v2, v33, v2
	v_exp_f32_e32 v12, v3
	v_sub_f32_e32 v3, v59, v178
	v_add_f32_e32 v2, v18, v2
	v_mul_f32_e32 v3, 0x3fb8aa3b, v3
	v_add_f32_e32 v2, v20, v2
	v_exp_f32_e32 v11, v3
	v_sub_f32_e32 v3, v58, v178
	v_add_f32_e32 v2, v19, v2
	v_mul_f32_e32 v3, 0x3fb8aa3b, v3
	v_add_f32_e32 v2, v21, v2
	v_exp_f32_e32 v13, v3
	v_sub_f32_e32 v3, v61, v178
	v_add_f32_e32 v2, v22, v2
	v_mul_f32_e32 v3, 0x3fb8aa3b, v3
	v_add_f32_e32 v2, v24, v2
	v_exp_f32_e32 v14, v3
	v_sub_f32_e32 v3, v60, v178
	v_add_f32_e32 v2, v23, v2
	v_mul_f32_e32 v3, 0x3fb8aa3b, v3
	v_add_f32_e32 v2, v25, v2
	v_exp_f32_e32 v16, v3
	v_sub_f32_e32 v3, v63, v178
	v_add_f32_e32 v2, v10, v2
	v_mul_f32_e32 v3, 0x3fb8aa3b, v3
	v_add_f32_e32 v2, v12, v2
	v_exp_f32_e32 v15, v3
	v_sub_f32_e32 v3, v62, v178
	v_add_f32_e32 v2, v11, v2
	v_mul_f32_e32 v3, 0x3fb8aa3b, v3
	v_add_f32_e32 v2, v13, v2
	v_exp_f32_e32 v17, v3
	v_add_f32_e32 v2, v14, v2
	v_add_f32_e32 v2, v16, v2
	v_add_f32_e32 v2, v15, v2
	v_add_f32_e32 v6, v17, v2
	v_sub_f32_e32 v2, v65, v178
	v_sub_f32_e32 v3, v64, v178
	v_mul_f32_e32 v2, 0x3fb8aa3b, v2
	v_mul_f32_e32 v3, 0x3fb8aa3b, v3
	v_exp_f32_e32 v2, v2
	v_exp_f32_e32 v4, v3
	v_sub_f32_e32 v3, v149, v178
	v_mul_f32_e32 v3, 0x3fb8aa3b, v3
	v_sub_f32_e32 v5, v148, v178
	v_exp_f32_e32 v3, v3
	v_mul_f32_e32 v5, 0x3fb8aa3b, v5
	v_exp_f32_e32 v5, v5
	v_add_f32_e32 v6, v2, v6
	v_sub_f32_e32 v59, v156, v178
	v_add_f32_e32 v6, v4, v6
	v_mul_f32_e32 v59, 0x3fb8aa3b, v59
	v_add_f32_e32 v6, v3, v6
	v_exp_f32_e32 v104, v59
	v_sub_f32_e32 v59, v154, v178
	v_add_f32_e32 v58, v5, v6
	v_sub_f32_e32 v6, v151, v178
	v_sub_f32_e32 v7, v150, v178
	v_mul_f32_e32 v59, 0x3fb8aa3b, v59
	v_mul_f32_e32 v6, 0x3fb8aa3b, v6
	v_mul_f32_e32 v7, 0x3fb8aa3b, v7
	v_exp_f32_e32 v106, v59
	v_sub_f32_e32 v59, v160, v178
	v_exp_f32_e32 v6, v6
	v_exp_f32_e32 v8, v7
	v_sub_f32_e32 v7, v153, v178
	v_mul_f32_e32 v59, 0x3fb8aa3b, v59
	v_mul_f32_e32 v7, 0x3fb8aa3b, v7
	v_sub_f32_e32 v9, v152, v178
	v_exp_f32_e32 v105, v59
	v_sub_f32_e32 v59, v158, v178
	v_exp_f32_e32 v7, v7
	v_mul_f32_e32 v9, 0x3fb8aa3b, v9
	v_mul_f32_e32 v59, 0x3fb8aa3b, v59
	v_exp_f32_e32 v9, v9
	v_exp_f32_e32 v107, v59
	v_sub_f32_e32 v59, v164, v178
	v_add_f32_e32 v58, v6, v58
	v_mul_f32_e32 v59, 0x3fb8aa3b, v59
	v_add_f32_e32 v58, v8, v58
	v_exp_f32_e32 v108, v59
	v_sub_f32_e32 v59, v162, v178
	v_add_f32_e32 v58, v7, v58
	v_mul_f32_e32 v59, 0x3fb8aa3b, v59
	v_add_f32_e32 v58, v9, v58
	v_exp_f32_e32 v110, v59
	v_sub_f32_e32 v59, v168, v178
	v_add_f32_e32 v58, v104, v58
	v_mul_f32_e32 v59, 0x3fb8aa3b, v59
	v_add_f32_e32 v58, v106, v58
	v_exp_f32_e32 v109, v59
	v_sub_f32_e32 v59, v166, v178
	v_sub_f32_e32 v48, v48, v178
	v_sub_f32_e32 v34, v34, v178
	v_add_f32_e32 v58, v105, v58
	v_mul_f32_e32 v59, 0x3fb8aa3b, v59
	v_mul_f32_e32 v48, 0x3fb8aa3b, v48
	v_mul_f32_e32 v34, 0x3fb8aa3b, v34
	v_add_f32_e32 v58, v107, v58
	v_exp_f32_e32 v111, v59
	v_exp_f32_e32 v92, v48
	v_sub_f32_e32 v48, v49, v178
	v_sub_f32_e32 v46, v46, v178
	v_exp_f32_e32 v89, v34
	v_sub_f32_e32 v34, v35, v178
	v_sub_f32_e32 v35, v157, v178
	v_add_f32_e32 v58, v108, v58
	v_mul_f32_e32 v48, 0x3fb8aa3b, v48
	v_mul_f32_e32 v46, 0x3fb8aa3b, v46
	v_mul_f32_e32 v35, 0x3fb8aa3b, v35
	v_add_f32_e32 v58, v110, v58
	v_exp_f32_e32 v94, v48
	v_exp_f32_e32 v93, v46
	v_sub_f32_e32 v46, v47, v178
	v_sub_f32_e32 v44, v44, v178
	v_exp_f32_e32 v74, v35
	v_sub_f32_e32 v35, v155, v178
	v_add_f32_e32 v58, v109, v58
	v_mul_f32_e32 v46, 0x3fb8aa3b, v46
	v_mul_f32_e32 v44, 0x3fb8aa3b, v44
	v_mul_f32_e32 v35, 0x3fb8aa3b, v35
	v_add_f32_e32 v58, v111, v58
	v_exp_f32_e32 v95, v46
	v_exp_f32_e32 v96, v44
	v_sub_f32_e32 v44, v45, v178
	v_sub_f32_e32 v42, v42, v178
	v_exp_f32_e32 v76, v35
	v_sub_f32_e32 v35, v161, v178
	v_add_f32_e32 v46, v92, v58
	v_mul_f32_e32 v44, 0x3fb8aa3b, v44
	v_mul_f32_e32 v42, 0x3fb8aa3b, v42
	v_mul_f32_e32 v35, 0x3fb8aa3b, v35
	v_add_f32_e32 v46, v94, v46
	v_exp_f32_e32 v102, v44
	v_exp_f32_e32 v97, v42
	v_sub_f32_e32 v42, v43, v178
	v_sub_f32_e32 v40, v40, v178
	v_exp_f32_e32 v75, v35
	v_sub_f32_e32 v35, v159, v178
; #define LAS __attribute__((address_space(3)))
; __device__ __forceinline__ unsigned pk2(float lo, float hi) { return f2bf(lo) | (f2bf(hi) << 16); }
; __device__ __forceinline__ float shflx(float v, int mask, int lane) { return __int_as_float(__builtin_amdgcn_ds_bpermute((lane ^ mask) << 2, __float_as_int(v))); }
; __device__ __forceinline__ void attn_unit(const Args& A, const Ctx& C0, int l, int u_qrow0, int u_nq, int u_krow0, int u_krow1, int u_krow2, int u_g, const float* u_ck, const float* u_cv, unsigned u_vmask) {
;     ...
;         mx = fmaxf(mx, shflx(mx, 32, C.lane));
;         float sum = 0.f;
; #pragma unroll
;         for (int kt = 0; kt < 6; ++kt)
; #pragma unroll
;             for (int r = 0; r < 16; ++r) { const float e = __expf(sacc[kt][r] - mx); sacc[kt][r] = e; sum += e; }
;         sum += shflx(sum, 32, C.lane); sum += __expf(sink - mx);
;         const float inv = 1.f / sum;
;         f32x16 oacc[2];
; #pragma unroll
;         for (int dt = 0; dt < 2; ++dt)
; #pragma unroll
;             for (int r = 0; r < 16; ++r) oacc[dt][r] = 0.f;
; #pragma unroll
;         for (int kt = 0; kt < 6; ++kt) {
;             if ((u.vmask >> kt) & 1u) {
; #pragma unroll
;                 for (int s = 0; s < 2; ++s) {
;                     union { bf16x8 v; unsigned w[4]; } pf;
; #pragma unroll
;                     for (int e = 0; e < 4; ++e) pf.w[e] = pk2(sacc[kt][8 * s + 2 * e] * inv, sacc[kt][8 * s + 2 * e + 1] * inv);
; #pragma unroll
;                     for (int dt = 0; dt < 2; ++dt) { const LAS bf16* vp = Vt + (dt * 32 + li) * VP + kt * 32 + 16 * s + 4 * h;
;                         union { bf16x8 v; v2u w[2]; } vf; vf.w[0] = *(const LAS v2u*)vp; vf.w[1] = *(const LAS v2u*)(vp + 8);
;                         oacc[dt] = __builtin_amdgcn_mfma_f32_32x32x16_bf16(vf.v, pf.v, oacc[dt], 0, 0, 0); }
	v_add_f32_e32 v46, v93, v46
	v_mul_f32_e32 v42, 0x3fb8aa3b, v42
	v_mul_f32_e32 v40, 0x3fb8aa3b, v40
	v_mul_f32_e32 v35, 0x3fb8aa3b, v35
	v_add_f32_e32 v46, v95, v46
	v_exp_f32_e32 v103, v42
	v_exp_f32_e32 v84, v40
	v_sub_f32_e32 v40, v41, v178
	v_sub_f32_e32 v38, v38, v178
	v_exp_f32_e32 v77, v35
	v_sub_f32_e32 v35, v165, v178
	v_add_f32_e32 v42, v96, v46
	v_mul_f32_e32 v40, 0x3fb8aa3b, v40
	v_mul_f32_e32 v38, 0x3fb8aa3b, v38
	v_mul_f32_e32 v35, 0x3fb8aa3b, v35
	v_add_f32_e32 v42, v102, v42
	v_exp_f32_e32 v86, v40
	v_exp_f32_e32 v85, v38
	v_sub_f32_e32 v38, v39, v178
	v_sub_f32_e32 v36, v36, v178
	v_exp_f32_e32 v78, v35
	v_sub_f32_e32 v35, v163, v178
	v_add_f32_e32 v42, v97, v42
	v_mul_f32_e32 v38, 0x3fb8aa3b, v38
	v_mul_f32_e32 v36, 0x3fb8aa3b, v36
	v_mul_f32_e32 v35, 0x3fb8aa3b, v35
	v_add_f32_e32 v42, v103, v42
	v_exp_f32_e32 v87, v38
	v_exp_f32_e32 v88, v36
	v_sub_f32_e32 v36, v37, v178
	v_exp_f32_e32 v80, v35
	v_sub_f32_e32 v35, v169, v178
	v_add_f32_e32 v38, v84, v42
	v_mul_f32_e32 v36, 0x3fb8aa3b, v36
	v_mul_f32_e32 v35, 0x3fb8aa3b, v35
	v_add_f32_e32 v38, v86, v38
	v_exp_f32_e32 v90, v36
	v_exp_f32_e32 v79, v35
	v_sub_f32_e32 v35, v167, v178
	v_add_f32_e32 v38, v85, v38
	v_mul_f32_e32 v34, 0x3fb8aa3b, v34
	v_mul_f32_e32 v35, 0x3fb8aa3b, v35
	v_add_f32_e32 v38, v87, v38
	v_exp_f32_e32 v91, v34
	v_exp_f32_e32 v81, v35
	v_sub_f32_e32 v35, v171, v178
	v_add_f32_e32 v34, v88, v38
	v_mul_f32_e32 v35, 0x3fb8aa3b, v35
	v_add_f32_e32 v34, v90, v34
	v_exp_f32_e32 v66, v35
	v_sub_f32_e32 v35, v170, v178
	v_add_f32_e32 v34, v89, v34
	v_mul_f32_e32 v35, 0x3fb8aa3b, v35
	v_add_f32_e32 v34, v91, v34
	v_exp_f32_e32 v68, v35
	v_sub_f32_e32 v35, v173, v178
	v_add_f32_e32 v34, v74, v34
	v_mul_f32_e32 v35, 0x3fb8aa3b, v35
	v_add_f32_e32 v34, v76, v34
	v_exp_f32_e32 v67, v35
	v_sub_f32_e32 v35, v172, v178
	v_add_f32_e32 v34, v75, v34
	v_mul_f32_e32 v35, 0x3fb8aa3b, v35
	v_add_f32_e32 v34, v77, v34
	v_exp_f32_e32 v69, v35
	v_sub_f32_e32 v35, v175, v178
	v_add_f32_e32 v34, v78, v34
	v_mul_f32_e32 v35, 0x3fb8aa3b, v35
	v_add_f32_e32 v34, v80, v34
	v_exp_f32_e32 v70, v35
	v_sub_f32_e32 v35, v174, v178
	v_add_f32_e32 v34, v79, v34
	v_mul_f32_e32 v35, 0x3fb8aa3b, v35
	v_add_f32_e32 v34, v81, v34
	v_exp_f32_e32 v72, v35
	v_sub_f32_e32 v35, v177, v178
	v_add_f32_e32 v34, v66, v34
	v_mul_f32_e32 v35, 0x3fb8aa3b, v35
	v_add_f32_e32 v34, v68, v34
	v_exp_f32_e32 v71, v35
	v_sub_f32_e32 v35, v176, v178
	v_add_f32_e32 v34, v67, v34
	v_mul_f32_e32 v35, 0x3fb8aa3b, v35
	v_add_f32_e32 v34, v69, v34
	v_exp_f32_e32 v73, v35
	v_add_f32_e32 v34, v70, v34
	v_add_f32_e32 v34, v72, v34
	v_add_f32_e32 v34, v71, v34
	v_add_f32_e32 v34, v73, v34
	ds_bpermute_b32 v35, v189, v34
	v_sub_f32_e32 v36, v186, v178
	v_mul_f32_e32 v36, 0x3fb8aa3b, v36
	v_exp_f32_e32 v36, v36
	s_waitcnt lgkmcnt(0)
	v_add_f32_e32 v34, v34, v35
	v_add_f32_e32 v34, v36, v34
	v_div_scale_f32 v35, s[2:3], v34, v34, 1.0
	v_rcp_f32_e32 v36, v35
	s_nop 0
	v_fma_f32 v37, -v35, v36, 1.0
	v_fmac_f32_e32 v36, v37, v36
	v_div_scale_f32 v37, vcc, 1.0, v34, 1.0
	v_mul_f32_e32 v38, v37, v36
	v_fma_f32 v39, -v35, v38, v37
	v_fmac_f32_e32 v38, v39, v36
	v_fma_f32 v35, -v35, v38, v37
	v_div_fmas_f32 v35, v35, v36, v38
	s_and_b64 vcc, exec, s[38:39]
	v_div_fixup_f32 v82, v35, v34, 1.0
	s_cbranch_vccnz .LBB0_655
	v_pk_mul_f32 v[36:37], v[52:53], v[82:83] op_sel_hi:[1,0]
	v_pk_mul_f32 v[40:41], v[56:57], v[82:83] op_sel_hi:[1,0]
	v_pk_mul_f32 v[34:35], v[50:51], v[82:83] op_sel_hi:[1,0]
	v_pk_mul_f32 v[38:39], v[54:55], v[82:83] op_sel_hi:[1,0]
	s_nop 0
	s_nop 0
	v_bfe_u32 v44, v37, 16, 1
	v_bfe_u32 v45, v36, 16, 1
	v_add3_u32 v45, v36, v45, s33
	v_add3_u32 v44, v37, v44, s33
	v_bfe_u32 v36, v34, 16, 1
	v_bfe_u32 v37, v35, 16, 1
	v_add3_u32 v42, v35, v37, s33
	v_add3_u32 v43, v34, v36, s33
	ds_read2_b64 v[34:37], v129 offset0:128 offset1:130
	v_lshrrev_b32_e32 v43, 16, v43
	v_lshrrev_b32_e32 v42, 16, v42
	v_pk_mul_f32 v[126:127], v[126:127], v[82:83] op_sel_hi:[1,0]
	v_cvt_pk_bf16_f32 v41, v39, v41
	v_cvt_pk_bf16_f32 v40, v38, v40
	v_and_or_b32 v39, v44, s96, v42
	v_and_or_b32 v38, v45, s96, v43
	v_pk_mul_f32 v[120:121], v[120:121], v[82:83] op_sel_hi:[1,0]
	v_pk_mul_f32 v[122:123], v[122:123], v[82:83] op_sel_hi:[1,0]
	v_pk_mul_f32 v[124:125], v[124:125], v[82:83] op_sel_hi:[1,0]
	s_nop 0
	s_waitcnt lgkmcnt(0)
	v_mfma_f32_32x32x16_bf16 v[50:65], v[34:37], v[38:41], 0
	ds_read2_b64 v[34:37], v128 offset0:128 offset1:130
	ds_read2_b64 v[148:151], v129 offset0:132 offset1:134
	s_nop 0
	s_nop 0
	s_nop 0
	s_nop 0
	s_nop 0
	s_nop 0
	s_nop 0
	s_nop 0
	s_nop 0
	s_nop 0
	s_nop 0
	v_cvt_pk_bf16_f32 v120, v120, v122
	v_cvt_pk_bf16_f32 v122, v124, v126
	s_nop 0
	s_nop 0
	s_nop 0
	s_nop 0
	s_nop 0
	s_nop 0
	s_nop 0
	v_cvt_pk_bf16_f32 v121, v121, v123
	v_cvt_pk_bf16_f32 v123, v125, v127
	ds_read2_b64 v[124:127], v128 offset0:132 offset1:134
	s_waitcnt lgkmcnt(0)
	v_mfma_f32_32x32x16_bf16 v[34:49], v[34:37], v[38:41], 0
	s_nop 0
	s_nop 0
	s_nop 0
	s_nop 0
	s_nop 0
	s_nop 1
	v_mfma_f32_32x32x16_bf16 v[50:65], v[148:151], v[120:123], v[50:65]
	v_mfma_f32_32x32x16_bf16 v[34:49], v[124:127], v[120:123], v[34:49]
	s_branch .LBB0_656

; #define LAS __attribute__((address_space(3)))
; __device__ __forceinline__ unsigned pk2(float lo, float hi) { return f2bf(lo) | (f2bf(hi) << 16); }
; __device__ __forceinline__ void attn_unit(const Args& A, const Ctx& C0, int l, int u_qrow0, int u_nq, int u_krow0, int u_krow1, int u_krow2, int u_g, const float* u_ck, const float* u_cv, unsigned u_vmask) {
;     ...
;         for (int kt = 0; kt < 6; ++kt) {
;             if ((u.vmask >> kt) & 1u) {
; #pragma unroll
;                 for (int s = 0; s < 2; ++s) {
;                     union { bf16x8 v; unsigned w[4]; } pf;
; #pragma unroll
;                     for (int e = 0; e < 4; ++e) pf.w[e] = pk2(sacc[kt][8 * s + 2 * e] * inv, sacc[kt][8 * s + 2 * e + 1] * inv);
; #pragma unroll
;                     for (int dt = 0; dt < 2; ++dt) { const LAS bf16* vp = Vt + (dt * 32 + li) * VP + kt * 32 + 16 * s + 4 * h;
;                         union { bf16x8 v; v2u w[2]; } vf; vf.w[0] = *(const LAS v2u*)vp; vf.w[1] = *(const LAS v2u*)(vp + 8);
;                         oacc[dt] = __builtin_amdgcn_mfma_f32_32x32x16_bf16(vf.v, pf.v, oacc[dt], 0, 0, 0); }
;                 }
;             }
.LBB0_656:
	s_and_b64 vcc, exec, s[40:41]
	s_cbranch_vccnz .LBB0_658
	v_pk_mul_f32 v[114:115], v[114:115], v[82:83] op_sel_hi:[1,0]
	v_pk_mul_f32 v[118:119], v[118:119], v[82:83] op_sel_hi:[1,0]
	v_pk_mul_f32 v[112:113], v[112:113], v[82:83] op_sel_hi:[1,0]
	v_pk_mul_f32 v[116:117], v[116:117], v[82:83] op_sel_hi:[1,0]
	v_bfe_u32 v83, v119, 16, 1
	s_nop 0
	v_bfe_u32 v121, v115, 16, 1
	v_bfe_u32 v122, v114, 16, 1
	v_add3_u32 v122, v114, v122, s33
	v_add3_u32 v121, v115, v121, s33
	s_nop 0
	v_add3_u32 v83, v119, v83, s33
	v_bfe_u32 v114, v112, 16, 1
	v_bfe_u32 v115, v113, 16, 1
	s_nop 0
	v_bfe_u32 v120, v117, 16, 1
	v_add3_u32 v117, v117, v120, s33
	s_nop 0
	v_add3_u32 v119, v113, v115, s33
	v_add3_u32 v120, v112, v114, s33
	ds_read2_b64 v[112:115], v129 offset0:136 offset1:138
	v_lshrrev_b32_e32 v120, 16, v120
	v_lshrrev_b32_e32 v123, 16, v119
	v_lshrrev_b32_e32 v117, 16, v117
	v_and_or_b32 v119, v83, s96, v117
	v_cvt_pk_bf16_f32 v118, v116, v118
	v_and_or_b32 v117, v121, s96, v123
	v_and_or_b32 v116, v122, s96, v120
	v_pk_mul_f32 v[28:29], v[28:29], v[82:83] op_sel_hi:[1,0]
	v_pk_mul_f32 v[32:33], v[32:33], v[82:83] op_sel_hi:[1,0]
	s_waitcnt lgkmcnt(0)
	v_mfma_f32_32x32x16_bf16 v[50:65], v[112:115], v[116:119], v[50:65]
	ds_read2_b64 v[112:115], v128 offset0:136 offset1:138
	ds_read2_b64 v[120:123], v129 offset0:140 offset1:142
	v_mul_f32_e64 v26, v26, v82
	v_mul_f32_e64 v27, v27, v82
	v_mul_f32_e64 v30, v30, v82
	v_mul_f32_e64 v31, v31, v82
	s_nop 0
	s_waitcnt lgkmcnt(0)
	v_mfma_f32_32x32x16_bf16 v[34:49], v[112:115], v[116:119], v[34:49]
	s_nop 0
	v_bfe_u32 v113, v29, 16, 1
	v_bfe_u32 v114, v28, 16, 1
	v_add3_u32 v114, v28, v114, s33
	v_add3_u32 v113, v29, v113, s33
	s_nop 0
	s_nop 0
	s_nop 0
	s_nop 0
	s_nop 0
	s_nop 0
	v_cvt_pk_bf16_f32 v28, v30, v32
	v_bfe_u32 v32, v26, 16, 1
	v_cvt_pk_bf16_f32 v29, v31, v33
	v_bfe_u32 v33, v27, 16, 1
	s_nop 0
	s_nop 0
	v_add3_u32 v27, v27, v33, s33
	v_add3_u32 v26, v26, v32, s33
	s_nop 0
	ds_read2_b64 v[30:33], v128 offset0:140 offset1:142
	v_lshrrev_b32_e32 v26, 16, v26
	v_lshrrev_b32_e32 v27, 16, v27
	v_and_or_b32 v27, v113, s96, v27
	v_and_or_b32 v26, v114, s96, v26
	s_nop 1
	v_mfma_f32_32x32x16_bf16 v[50:65], v[120:123], v[26:29], v[50:65]
	s_waitcnt lgkmcnt(0)
	v_mfma_f32_32x32x16_bf16 v[34:49], v[30:33], v[26:29], v[34:49]
.LBB0_658:
	s_and_b64 vcc, exec, s[44:45]
	s_cbranch_vccnz .LBB0_660
	v_pk_mul_f32 v[20:21], v[20:21], v[82:83] op_sel_hi:[1,0]
	v_pk_mul_f32 v[24:25], v[24:25], v[82:83] op_sel_hi:[1,0]
	v_pk_mul_f32 v[18:19], v[18:19], v[82:83] op_sel_hi:[1,0]
	v_pk_mul_f32 v[22:23], v[22:23], v[82:83] op_sel_hi:[1,0]
	s_nop 0
	s_nop 0
	v_bfe_u32 v28, v21, 16, 1
	v_bfe_u32 v29, v20, 16, 1
	v_add3_u32 v29, v20, v29, s33
	v_add3_u32 v28, v21, v28, s33
	s_nop 0
	s_nop 0
	v_bfe_u32 v20, v18, 16, 1
	v_bfe_u32 v21, v19, 16, 1
	s_nop 0
	s_nop 0
	s_nop 0
	s_nop 0
	v_add3_u32 v26, v19, v21, s33
	v_add3_u32 v27, v18, v20, s33
	ds_read2_b64 v[18:21], v129 offset0:144 offset1:146
	v_lshrrev_b32_e32 v27, 16, v27
	v_lshrrev_b32_e32 v26, 16, v26
	v_cvt_pk_bf16_f32 v25, v23, v25
	v_cvt_pk_bf16_f32 v24, v22, v24
	v_and_or_b32 v23, v28, s96, v26
	v_and_or_b32 v22, v29, s96, v27
	v_pk_mul_f32 v[12:13], v[12:13], v[82:83] op_sel_hi:[1,0]
	v_pk_mul_f32 v[16:17], v[16:17], v[82:83] op_sel_hi:[1,0]
	s_waitcnt lgkmcnt(0)
	v_mfma_f32_32x32x16_bf16 v[50:65], v[18:21], v[22:25], v[50:65]
	ds_read2_b64 v[18:21], v128 offset0:144 offset1:146
	ds_read2_b64 v[26:29], v129 offset0:148 offset1:150
	v_mul_f32_e64 v14, v14, v82
	v_mul_f32_e64 v15, v15, v82
	v_mul_f32_e64 v10, v10, v82
	v_mul_f32_e64 v11, v11, v82
	s_waitcnt lgkmcnt(0)
	v_mfma_f32_32x32x16_bf16 v[34:49], v[18:21], v[22:25], v[34:49]
	s_nop 0
	s_nop 0
	v_bfe_u32 v20, v13, 16, 1
	v_bfe_u32 v21, v12, 16, 1
	v_add3_u32 v21, v12, v21, s33
	v_add3_u32 v20, v13, v20, s33
	s_nop 0
	s_nop 0
	s_nop 0
	s_nop 0
	s_nop 0
	s_nop 0
	v_cvt_pk_bf16_f32 v12, v14, v16
	v_bfe_u32 v16, v10, 16, 1
	v_cvt_pk_bf16_f32 v13, v15, v17
	v_bfe_u32 v17, v11, 16, 1
	s_nop 0
	s_nop 0
	v_add3_u32 v11, v11, v17, s33
	v_add3_u32 v10, v10, v16, s33
	ds_read2_b64 v[14:17], v128 offset0:148 offset1:150
	v_lshrrev_b32_e32 v10, 16, v10
	v_lshrrev_b32_e32 v11, 16, v11
	v_and_or_b32 v11, v20, s96, v11
	v_and_or_b32 v10, v21, s96, v10
	s_nop 1
	v_mfma_f32_32x32x16_bf16 v[50:65], v[26:29], v[10:13], v[50:65]
	s_waitcnt lgkmcnt(0)
	v_mfma_f32_32x32x16_bf16 v[34:49], v[14:17], v[10:13], v[34:49]
.LBB0_660:
	s_and_b64 vcc, exec, s[60:61]
	s_cbranch_vccz .LBB0_662
	v_pk_mul_f32 v[4:5], v[4:5], v[82:83] op_sel_hi:[1,0]
	v_pk_mul_f32 v[8:9], v[8:9], v[82:83] op_sel_hi:[1,0]
	v_pk_mul_f32 v[2:3], v[2:3], v[82:83] op_sel_hi:[1,0]
	v_pk_mul_f32 v[6:7], v[6:7], v[82:83] op_sel_hi:[1,0]
	s_nop 0
	s_nop 0
	s_nop 0
	s_nop 0
	s_nop 0
	s_nop 0
	s_nop 0
	s_nop 0
	s_nop 0
	s_nop 0
	s_nop 0
	s_nop 0
	s_nop 0
	s_nop 0
	v_cvt_pk_bf16_f32 v113, v3, v5
	v_cvt_pk_bf16_f32 v112, v2, v4
	ds_read2_b64 v[2:5], v129 offset0:152 offset1:154
	ds_read2_b64 v[116:119], v128 offset0:152 offset1:154
	ds_read2_b64 v[120:123], v129 offset0:156 offset1:158
	v_pk_mul_f32 v[110:111], v[110:111], v[82:83] op_sel_hi:[1,0]
	v_cvt_pk_bf16_f32 v115, v7, v9
	v_cvt_pk_bf16_f32 v114, v6, v8
	v_pk_mul_f32 v[104:105], v[104:105], v[82:83] op_sel_hi:[1,0]
	v_pk_mul_f32 v[106:107], v[106:107], v[82:83] op_sel_hi:[1,0]
	v_pk_mul_f32 v[108:109], v[108:109], v[82:83] op_sel_hi:[1,0]
	s_nop 0
	s_waitcnt lgkmcnt(0)
	v_mfma_f32_32x32x16_bf16 v[18:33], v[2:5], v[112:115], v[50:65]
	s_nop 0
	s_nop 0
	s_nop 0
	s_nop 0
	v_mfma_f32_32x32x16_bf16 v[2:17], v[116:119], v[112:115], v[34:49]
	s_nop 0
	s_nop 0
	s_nop 0
	s_nop 0
	s_nop 0
	s_nop 0
	s_nop 0
	s_nop 0
	v_cvt_pk_bf16_f32 v104, v104, v106
	v_cvt_pk_bf16_f32 v106, v108, v110
	s_nop 0
	s_nop 0
	s_nop 0
	s_nop 0
	s_nop 0
	s_nop 0
	v_cvt_pk_bf16_f32 v105, v105, v107
	v_cvt_pk_bf16_f32 v107, v109, v111
	ds_read2_b64 v[108:111], v128 offset0:156 offset1:158
	s_nop 0
	s_nop 0
	s_nop 0
	s_nop 0
	s_nop 0
	s_nop 1
	v_mfma_f32_32x32x16_bf16 v[18:33], v[120:123], v[104:107], v[18:33]
	s_waitcnt lgkmcnt(0)
	v_mfma_f32_32x32x16_bf16 v[2:17], v[108:111], v[104:107], v[2:17]
	s_cbranch_execz .LBB0_663
	s_branch .LBB0_664

; #define LAS __attribute__((address_space(3)))
; __device__ __forceinline__ unsigned pk2(float lo, float hi) { return f2bf(lo) | (f2bf(hi) << 16); }
; __device__ __forceinline__ void attn_unit(const Args& A, const Ctx& C0, int l, int u_qrow0, int u_nq, int u_krow0, int u_krow1, int u_krow2, int u_g, const float* u_ck, const float* u_cv, unsigned u_vmask) {
;     ...
;         for (int kt = 0; kt < 6; ++kt) {
;             if ((u.vmask >> kt) & 1u) {
; #pragma unroll
;                 for (int s = 0; s < 2; ++s) {
;                     union { bf16x8 v; unsigned w[4]; } pf;
; #pragma unroll
;                     for (int e = 0; e < 4; ++e) pf.w[e] = pk2(sacc[kt][8 * s + 2 * e] * inv, sacc[kt][8 * s + 2 * e + 1] * inv);
; #pragma unroll
;                     for (int dt = 0; dt < 2; ++dt) { const LAS bf16* vp = Vt + (dt * 32 + li) * VP + kt * 32 + 16 * s + 4 * h;
;                         union { bf16x8 v; v2u w[2]; } vf; vf.w[0] = *(const LAS v2u*)vp; vf.w[1] = *(const LAS v2u*)(vp + 8);
;                         oacc[dt] = __builtin_amdgcn_mfma_f32_32x32x16_bf16(vf.v, pf.v, oacc[dt], 0, 0, 0); }
;                 }
;             }
.LBB0_664:
	v_mov_b32_e32 v83, v82
	v_pk_mul_f32 v[36:37], v[94:95], v[82:83]
	v_pk_mul_f32 v[40:41], v[102:103], v[82:83]
	v_pk_mul_f32 v[34:35], v[92:93], v[82:83]
	v_pk_mul_f32 v[38:39], v[96:97], v[82:83]
	s_nop 0
	s_nop 0
	v_bfe_u32 v44, v37, 16, 1
	v_bfe_u32 v45, v36, 16, 1
	v_add3_u32 v45, v36, v45, s33
	v_add3_u32 v44, v37, v44, s33
	s_nop 0
	s_nop 0
	v_bfe_u32 v36, v34, 16, 1
	v_bfe_u32 v37, v35, 16, 1
	s_nop 0
	s_nop 0
	s_nop 0
	s_nop 0
	v_add3_u32 v42, v35, v37, s33
	v_add3_u32 v43, v34, v36, s33
	ds_read2_b64 v[34:37], v129 offset0:160 offset1:162
	v_lshrrev_b32_e32 v43, 16, v43
	v_lshrrev_b32_e32 v42, 16, v42
	v_cvt_pk_bf16_f32 v41, v39, v41
	v_cvt_pk_bf16_f32 v40, v38, v40
	v_and_or_b32 v39, v44, s96, v42
	v_and_or_b32 v38, v45, s96, v43
	s_and_b64 vcc, exec, s[42:43]
	s_waitcnt lgkmcnt(0)
	v_mfma_f32_32x32x16_bf16 v[18:33], v[34:37], v[38:41], v[18:33]
	ds_read2_b64 v[34:37], v128 offset0:160 offset1:162
	ds_read2_b64 v[42:45], v129 offset0:164 offset1:166
	s_waitcnt lgkmcnt(0)
	v_mfma_f32_32x32x16_bf16 v[2:17], v[34:37], v[38:41], v[2:17]
	v_mul_f32_e64 v36, v86, v82
	v_mul_f32_e64 v37, v87, v83
	v_mul_f32_e64 v40, v90, v82
	v_mul_f32_e64 v41, v91, v83
	v_mul_f32_e64 v38, v88, v82
	v_mul_f32_e64 v39, v89, v83
	s_nop 0
	s_nop 0
	v_bfe_u32 v48, v37, 16, 1
	v_bfe_u32 v49, v36, 16, 1
	v_add3_u32 v49, v36, v49, s33
	v_add3_u32 v48, v37, v48, s33
	s_nop 0
	s_nop 0
	s_nop 0
	s_nop 0
	v_pk_mul_f32 v[34:35], v[84:85], v[82:83]
	s_nop 0
	s_nop 0
	v_cvt_pk_bf16_f32 v36, v38, v40
	v_bfe_u32 v40, v34, 16, 1
	v_cvt_pk_bf16_f32 v37, v39, v41
	v_bfe_u32 v41, v35, 16, 1
	v_add3_u32 v35, v35, v41, s33
	v_add3_u32 v34, v34, v40, s33
	ds_read2_b64 v[38:41], v128 offset0:164 offset1:166
	v_lshrrev_b32_e32 v34, 16, v34
	v_lshrrev_b32_e32 v35, 16, v35
	v_and_or_b32 v35, v48, s96, v35
	v_and_or_b32 v34, v49, s96, v34
	s_nop 1
	v_mfma_f32_32x32x16_bf16 v[18:33], v[42:45], v[34:37], v[18:33]
	s_waitcnt lgkmcnt(0)
	v_mfma_f32_32x32x16_bf16 v[2:17], v[38:41], v[34:37], v[2:17]
	s_cbranch_vccnz .LBB0_666
	v_pk_mul_f32 v[36:37], v[76:77], v[82:83]
	v_pk_mul_f32 v[40:41], v[80:81], v[82:83]
	v_pk_mul_f32 v[34:35], v[74:75], v[82:83]
	v_pk_mul_f32 v[38:39], v[78:79], v[82:83]
	s_nop 0
	s_nop 0
	v_bfe_u32 v44, v37, 16, 1
	v_bfe_u32 v45, v36, 16, 1
	v_add3_u32 v45, v36, v45, s33
	v_add3_u32 v44, v37, v44, s33
	s_nop 0
	s_nop 0
	v_bfe_u32 v36, v34, 16, 1
	v_bfe_u32 v37, v35, 16, 1
	s_nop 0
	s_nop 0
	s_nop 0
	s_nop 0
	v_add3_u32 v42, v35, v37, s33
	v_add3_u32 v43, v34, v36, s33
	ds_read2_b64 v[34:37], v129 offset0:168 offset1:170
	v_lshrrev_b32_e32 v43, 16, v43
	v_lshrrev_b32_e32 v42, 16, v42
	v_cvt_pk_bf16_f32 v41, v39, v41
	v_cvt_pk_bf16_f32 v40, v38, v40
	v_and_or_b32 v39, v44, s96, v42
	v_and_or_b32 v38, v45, s96, v43
	s_waitcnt lgkmcnt(0)
	s_nop 0
	v_mfma_f32_32x32x16_bf16 v[18:33], v[34:37], v[38:41], v[18:33]
	ds_read2_b64 v[34:37], v128 offset0:168 offset1:170
	ds_read2_b64 v[42:45], v129 offset0:172 offset1:174
	s_waitcnt lgkmcnt(0)
	v_mfma_f32_32x32x16_bf16 v[2:17], v[34:37], v[38:41], v[2:17]
	v_mul_f32_e64 v36, v68, v82
	v_mul_f32_e64 v37, v69, v83
	v_mul_f32_e64 v40, v72, v82
	v_mul_f32_e64 v41, v73, v83
	v_mul_f32_e64 v38, v70, v82
	v_mul_f32_e64 v39, v71, v83
	s_nop 0
	s_nop 0
	v_bfe_u32 v48, v37, 16, 1
	v_bfe_u32 v49, v36, 16, 1
	v_add3_u32 v49, v36, v49, s33
	v_add3_u32 v48, v37, v48, s33
	s_nop 0
	s_nop 0
	s_nop 0
	s_nop 0
	v_pk_mul_f32 v[34:35], v[66:67], v[82:83]
	s_nop 0
	s_nop 0
	v_cvt_pk_bf16_f32 v36, v38, v40
	v_bfe_u32 v40, v34, 16, 1
	v_cvt_pk_bf16_f32 v37, v39, v41
	v_bfe_u32 v41, v35, 16, 1
	v_add3_u32 v35, v35, v41, s33
	v_add3_u32 v34, v34, v40, s33
	ds_read2_b64 v[38:41], v128 offset0:172 offset1:174
	v_lshrrev_b32_e32 v34, 16, v34
	v_lshrrev_b32_e32 v35, 16, v35
	v_and_or_b32 v35, v48, s96, v35
	v_and_or_b32 v34, v49, s96, v34
	s_nop 1
	v_mfma_f32_32x32x16_bf16 v[18:33], v[42:45], v[34:37], v[18:33]
	s_waitcnt lgkmcnt(0)
	v_mfma_f32_32x32x16_bf16 v[2:17], v[38:41], v[34:37], v[2:17]

; __device__ __forceinline__ unsigned pk2(float lo, float hi) { return f2bf(lo) | (f2bf(hi) << 16); }
; __device__ __forceinline__ void pool_item(const Args& A, const Ctx& C0, int l, int row0, int t0, int pos0, const float* hist, float* outpool) {
;     ...
;         for (int it = 0; it < 6; ++it) { const int idx = C.tid + 512 * it; const int rr = idx >> 6, v = idx & 63;
;             xs[it] = (v4u){0u, 0u, 0u, 0u};
;             if (idx < 47 * 64) {
;                 if (rr < 15 && t0 == 0) { if (hist) { const f32x4 a0 = *(const f32x4*)(hist + rr * 512 + v * 8), a1 = *(const f32x4*)(hist + rr * 512 + v * 8 + 4);
;                         xs[it] = (v4u){pk2(a0.x, a0.y), pk2(a0.z, a0.w), pk2(a1.x, a1.y), pk2(a1.z, a1.w)}; } }
;                 else xs[it] = *(const v4u*)(U + (size_t)(row0 - 15 + rr) * DIN + C_P + v * 8); } }
.LBB0_705:
	s_andn2_saveexec_b64 s[30:31], s[2:3]
	s_cbranch_execz .LBB0_709
	s_andn2_b64 vcc, exec, s[64:65]
	s_cbranch_vccnz .LBB0_708
	v_lshlrev_b32_e32 v4, 9, v30
	v_ashrrev_i32_e32 v5, 31, v4
	s_waitcnt vmcnt(0) lgkmcnt(0)
	v_lshl_add_u64 v[8:9], v[4:5], 2, v[26:27]
	global_load_dwordx4 v[4:7], v[8:9], off
	s_nop 0
	global_load_dwordx4 v[8:11], v[8:9], off offset:16
	s_waitcnt vmcnt(1)
	s_nop 0
	s_nop 0
	s_nop 0
	s_nop 0
	s_waitcnt vmcnt(0)
	s_nop 0
	s_nop 0
	s_nop 0
	v_cvt_pk_bf16_f32 v241, v4, v5
	v_cvt_pk_bf16_f32 v242, v6, v7
	v_cvt_pk_bf16_f32 v8, v8, v9
	v_mov_b32_e32 v6, v241
	v_mov_b32_e32 v7, v242
	s_nop 0
	v_cvt_pk_bf16_f32 v9, v10, v11
	s_branch .LBB0_709

; __device__ __forceinline__ unsigned pk2(float lo, float hi) { return f2bf(lo) | (f2bf(hi) << 16); }
; __device__ __forceinline__ void pool_item(const Args& A, const Ctx& C0, int l, int row0, int t0, int pos0, const float* hist, float* outpool) {
;     ...
;         for (int it = 0; it < 6; ++it) { const int idx = C.tid + 512 * it; const int rr = idx >> 6, v = idx & 63;
;             xs[it] = (v4u){0u, 0u, 0u, 0u};
;             if (idx < 47 * 64) {
;                 if (rr < 15 && t0 == 0) { if (hist) { const f32x4 a0 = *(const f32x4*)(hist + rr * 512 + v * 8), a1 = *(const f32x4*)(hist + rr * 512 + v * 8 + 4);
;                         xs[it] = (v4u){pk2(a0.x, a0.y), pk2(a0.z, a0.w), pk2(a1.x, a1.y), pk2(a1.z, a1.w)}; } }
;                 else xs[it] = *(const v4u*)(U + (size_t)(row0 - 15 + rr) * DIN + C_P + v * 8); } }
.LBB0_713:
	s_andn2_saveexec_b64 s[30:31], s[2:3]
	s_cbranch_execz .LBB0_717
	s_andn2_b64 vcc, exec, s[64:65]
	s_cbranch_vccnz .LBB0_716
	v_lshlrev_b32_e32 v4, 9, v32
	v_ashrrev_i32_e32 v5, 31, v4
	v_lshl_add_u64 v[4:5], v[4:5], 2, v[26:27]
	s_waitcnt lgkmcnt(0)
	global_load_dwordx4 v[10:13], v[4:5], off
	global_load_dwordx4 v[14:17], v[4:5], off offset:16
	s_waitcnt vmcnt(0)
	s_nop 0
	s_nop 0
	s_nop 0
	s_nop 0
	s_nop 0
	s_nop 0
	s_nop 0
	s_nop 0
	s_nop 0
	v_cvt_pk_bf16_f32 v241, v10, v11
	v_cvt_pk_bf16_f32 v242, v12, v13
	v_cvt_pk_bf16_f32 v12, v14, v15
	v_mov_b32_e32 v10, v241
	v_mov_b32_e32 v11, v242
	s_nop 0
	v_cvt_pk_bf16_f32 v13, v16, v17
	s_branch .LBB0_717

; __device__ __forceinline__ unsigned pk2(float lo, float hi) { return f2bf(lo) | (f2bf(hi) << 16); }
; __device__ __forceinline__ void pool_item(const Args& A, const Ctx& C0, int l, int row0, int t0, int pos0, const float* hist, float* outpool) {
;     ...
;         for (int it = 0; it < 6; ++it) { const int idx = C.tid + 512 * it; const int rr = idx >> 6, v = idx & 63;
;             xs[it] = (v4u){0u, 0u, 0u, 0u};
;             if (idx < 47 * 64) {
;                 if (rr < 15 && t0 == 0) { if (hist) { const f32x4 a0 = *(const f32x4*)(hist + rr * 512 + v * 8), a1 = *(const f32x4*)(hist + rr * 512 + v * 8 + 4);
;                         xs[it] = (v4u){pk2(a0.x, a0.y), pk2(a0.z, a0.w), pk2(a1.x, a1.y), pk2(a1.z, a1.w)}; } }
;                 else xs[it] = *(const v4u*)(U + (size_t)(row0 - 15 + rr) * DIN + C_P + v * 8); } }
.LBB0_729:
	s_andn2_saveexec_b64 s[36:37], s[2:3]
	s_cbranch_execz .LBB0_733
	s_andn2_b64 vcc, exec, s[64:65]
	s_cbranch_vccnz .LBB0_732
	v_lshlrev_b32_e32 v16, 9, v36
	v_ashrrev_i32_e32 v17, 31, v16
	s_waitcnt vmcnt(0) lgkmcnt(0)
	v_lshl_add_u64 v[20:21], v[16:17], 2, v[26:27]
	global_load_dwordx4 v[16:19], v[20:21], off
	s_nop 0
	global_load_dwordx4 v[20:23], v[20:21], off offset:16
	s_waitcnt vmcnt(1)
	s_nop 0
	s_nop 0
	s_nop 0
	s_nop 0
	s_waitcnt vmcnt(0)
	s_nop 0
	s_nop 0
	s_nop 0
	v_cvt_pk_bf16_f32 v241, v16, v17
	v_cvt_pk_bf16_f32 v242, v18, v19
	v_cvt_pk_bf16_f32 v20, v20, v21
	v_mov_b32_e32 v18, v241
	v_mov_b32_e32 v19, v242
	s_nop 0
	v_cvt_pk_bf16_f32 v21, v22, v23
	s_branch .LBB0_733

; __device__ __forceinline__ unsigned pk2(float lo, float hi) { return f2bf(lo) | (f2bf(hi) << 16); }
; __device__ __forceinline__ void pool_item(const Args& A, const Ctx& C0, int l, int row0, int t0, int pos0, const float* hist, float* outpool) {
;     ...
;         for (int it = 0; it < 6; ++it) { const int idx = C.tid + 512 * it; const int rr = idx >> 6, v = idx & 63;
;             xs[it] = (v4u){0u, 0u, 0u, 0u};
;             if (idx < 47 * 64) {
;                 if (rr < 15 && t0 == 0) { if (hist) { const f32x4 a0 = *(const f32x4*)(hist + rr * 512 + v * 8), a1 = *(const f32x4*)(hist + rr * 512 + v * 8 + 4);
;                         xs[it] = (v4u){pk2(a0.x, a0.y), pk2(a0.z, a0.w), pk2(a1.x, a1.y), pk2(a1.z, a1.w)}; } }
;                 else xs[it] = *(const v4u*)(U + (size_t)(row0 - 15 + rr) * DIN + C_P + v * 8); } }
.LBB0_783:
	s_andn2_saveexec_b64 s[66:67], s[2:3]
	s_cbranch_execz .LBB0_1157
	s_andn2_b64 vcc, exec, s[64:65]
	s_cbranch_vccnz .LBB0_1156
	s_waitcnt vmcnt(0) lgkmcnt(0)
	v_lshlrev_b32_e32 v22, 9, v38
	v_ashrrev_i32_e32 v23, 31, v22
	v_lshl_add_u64 v[22:23], v[22:23], 2, v[26:27]
	global_load_dwordx4 v[24:27], v[22:23], off offset:16
	global_load_dwordx4 v[40:43], v[22:23], off
	s_waitcnt vmcnt(0)
	s_nop 0
	s_nop 0
	s_nop 0
	s_nop 0
	s_nop 0
	v_cvt_pk_bf16_f32 v22, v40, v41
	s_nop 0
	s_nop 0
	s_nop 0
	v_cvt_pk_bf16_f32 v23, v42, v43
	s_nop 0
	s_nop 0
	s_nop 0
	s_nop 0
	s_nop 0
	v_cvt_pk_bf16_f32 v24, v24, v25
	s_nop 0
	s_nop 0
	s_nop 0
	s_nop 0
	s_nop 0
	v_cvt_pk_bf16_f32 v25, v26, v27
	s_branch .LBB0_1157

; __device__ __forceinline__ unsigned pk2(float lo, float hi) { return f2bf(lo) | (f2bf(hi) << 16); }
; __device__ __forceinline__ void attn_unit(const Args& A, const Ctx& C0, int l, int u_qrow0, int u_nq, int u_krow0, int u_krow1, int u_krow2, int u_g, const float* u_ck, const float* u_cv, unsigned u_vmask) {
;     ...
;         for (int it = 0; it < 3; ++it) { const int idx = C.tid + 512 * it; const int j = idx >> 3, part = idx & 7;
;             kx[it] = (v4u){0u, 0u, 0u, 0u}; vx[it] = kx[it];
;             if ((u.vmask >> (j >> 5)) & 1u) {
;                 if (u.ck && j < 128) { const float* pk = u.ck + (size_t)j * 128 + part * 8; const float* pv = u.cv + (size_t)j * 128 + part * 8;
;                     const f32x4 a0 = *(const f32x4*)pk, a1 = *(const f32x4*)(pk + 4), b0 = *(const f32x4*)pv, b1 = *(const f32x4*)(pv + 4);
;                     kx[it] = (v4u){pk2(a0.x, a0.y), pk2(a0.z, a0.w), pk2(a1.x, a1.y), pk2(a1.z, a1.w)}; vx[it] = (v4u){pk2(b0.x, b0.y), pk2(b0.z, b0.w), pk2(b1.x, b1.y), pk2(b1.z, b1.w)}; }
;                 else { const int ch = j >> 6; const int kr = (ch == 0 ? u.krow0 : (ch == 1 ? u.krow1 : u.krow2)) + (j & 63);
;                     kx[it] = *(const v4u*)(U + (size_t)kr * DIN + C_K + u.g * 64 + part * 8); vx[it] = *(const v4u*)(U + (size_t)kr * DIN + C_V + u.g * 64 + part * 8); }
;             } }
.LBB0_798:
	s_andn2_saveexec_b64 s[30:31], s[30:31]
	s_cbranch_execz .LBB0_800
	v_ashrrev_i32_e32 v37, 31, v36
	v_lshlrev_b64 v[8:9], 9, v[36:37]
	s_waitcnt vmcnt(0) lgkmcnt(0)
	v_lshl_add_u64 v[22:23], v[34:35], 0, v[8:9]
	v_lshl_add_u64 v[8:9], v[32:33], 0, v[8:9]
	global_load_dwordx4 v[14:17], v[22:23], off
	s_nop 0
	global_load_dwordx4 v[22:25], v[22:23], off offset:16
	s_nop 0
	global_load_dwordx4 v[26:29], v[8:9], off
	global_load_dwordx4 v[42:45], v[8:9], off offset:16
	s_waitcnt vmcnt(3)
	s_nop 0
	s_nop 0
	s_nop 0
	s_nop 0
	s_waitcnt vmcnt(2)
	s_nop 0
	s_waitcnt vmcnt(1)
	s_waitcnt vmcnt(0)
	v_cvt_pk_bf16_f32 v241, v14, v15
	v_cvt_pk_bf16_f32 v242, v16, v17
	v_cvt_pk_bf16_f32 v243, v22, v23
	v_cvt_pk_bf16_f32 v25, v24, v25
	v_cvt_pk_bf16_f32 v15, v28, v29
	v_cvt_pk_bf16_f32 v14, v26, v27
	v_mov_b32_e32 v22, v241
	v_mov_b32_e32 v23, v242
	v_mov_b32_e32 v24, v243
	s_nop 0
	s_nop 0
	s_nop 0
	v_cvt_pk_bf16_f32 v16, v42, v43
	v_cvt_pk_bf16_f32 v17, v44, v45

; __device__ __forceinline__ unsigned pk2(float lo, float hi) { return f2bf(lo) | (f2bf(hi) << 16); }
; __device__ __forceinline__ void attn_unit(const Args& A, const Ctx& C0, int l, int u_qrow0, int u_nq, int u_krow0, int u_krow1, int u_krow2, int u_g, const float* u_ck, const float* u_cv, unsigned u_vmask) {
;     ...
;         for (int it = 0; it < 3; ++it) { const int idx = C.tid + 512 * it; const int j = idx >> 3, part = idx & 7;
;             kx[it] = (v4u){0u, 0u, 0u, 0u}; vx[it] = kx[it];
;             if ((u.vmask >> (j >> 5)) & 1u) {
;                 if (u.ck && j < 128) { const float* pk = u.ck + (size_t)j * 128 + part * 8; const float* pv = u.cv + (size_t)j * 128 + part * 8;
;                     const f32x4 a0 = *(const f32x4*)pk, a1 = *(const f32x4*)(pk + 4), b0 = *(const f32x4*)pv, b1 = *(const f32x4*)(pv + 4);
;                     kx[it] = (v4u){pk2(a0.x, a0.y), pk2(a0.z, a0.w), pk2(a1.x, a1.y), pk2(a1.z, a1.w)}; vx[it] = (v4u){pk2(b0.x, b0.y), pk2(b0.z, b0.w), pk2(b1.x, b1.y), pk2(b1.z, b1.w)}; }
;                 else { const int ch = j >> 6; const int kr = (ch == 0 ? u.krow0 : (ch == 1 ? u.krow1 : u.krow2)) + (j & 63);
;                     kx[it] = *(const v4u*)(U + (size_t)kr * DIN + C_K + u.g * 64 + part * 8); vx[it] = *(const v4u*)(U + (size_t)kr * DIN + C_V + u.g * 64 + part * 8); }
;             } }
.LBB0_804:
	s_andn2_saveexec_b64 s[24:25], s[30:31]
	s_cbranch_execz .LBB0_806
	v_ashrrev_i32_e32 v39, 31, v38
	v_lshlrev_b64 v[42:43], 9, v[38:39]
	s_waitcnt vmcnt(0) lgkmcnt(0)
	v_lshl_add_u64 v[26:27], v[34:35], 0, v[42:43]
	v_lshl_add_u64 v[42:43], v[32:33], 0, v[42:43]
	global_load_dwordx4 v[6:9], v[26:27], off
	s_nop 0
	global_load_dwordx4 v[26:29], v[26:27], off offset:16
	s_nop 0
	global_load_dwordx4 v[32:35], v[42:43], off
	s_nop 0
	global_load_dwordx4 v[42:45], v[42:43], off offset:16
	s_waitcnt vmcnt(3)
	s_nop 0
	s_nop 0
	s_waitcnt vmcnt(2)
	s_nop 0
	s_nop 0
	s_waitcnt vmcnt(1)
	s_waitcnt vmcnt(0)
	v_cvt_pk_bf16_f32 v241, v32, v33
	v_cvt_pk_bf16_f32 v242, v34, v35
	v_cvt_pk_bf16_f32 v6, v6, v7
	v_cvt_pk_bf16_f32 v7, v8, v9
	v_cvt_pk_bf16_f32 v8, v26, v27
	v_cvt_pk_bf16_f32 v9, v28, v29
	v_mov_b32_e32 v26, v241
	v_mov_b32_e32 v27, v242
	v_cvt_pk_bf16_f32 v28, v42, v43
	v_cvt_pk_bf16_f32 v29, v44, v45

; #define LAS __attribute__((address_space(3)))
; __device__ __forceinline__ unsigned pk2(float lo, float hi) { return f2bf(lo) | (f2bf(hi) << 16); }
; __device__ __forceinline__ void attn_unit(const Args& A, const Ctx& C0, int l, int u_qrow0, int u_nq, int u_krow0, int u_krow1, int u_krow2, int u_g, const float* u_ck, const float* u_cv, unsigned u_vmask) {
;     ...
;         for (int kt = 0; kt < 6; ++kt) {
;             if ((u.vmask >> kt) & 1u) {
; #pragma unroll
;                 for (int s = 0; s < 2; ++s) {
;                     union { bf16x8 v; unsigned w[4]; } pf;
; #pragma unroll
;                     for (int e = 0; e < 4; ++e) pf.w[e] = pk2(sacc[kt][8 * s + 2 * e] * inv, sacc[kt][8 * s + 2 * e + 1] * inv);
; #pragma unroll
;                     for (int dt = 0; dt < 2; ++dt) { const LAS bf16* vp = Vt + (dt * 32 + li) * VP + kt * 32 + 16 * s + 4 * h;
;                         union { bf16x8 v; v2u w[2]; } vf; vf.w[0] = *(const LAS v2u*)vp; vf.w[1] = *(const LAS v2u*)(vp + 8);
;                         oacc[dt] = __builtin_amdgcn_mfma_f32_32x32x16_bf16(vf.v, pf.v, oacc[dt], 0, 0, 0); }
;                 }
;             }
.LBB0_970:
	s_and_b64 vcc, exec, s[40:41]
	s_cbranch_vccnz .LBB0_972
	v_pk_mul_f32 v[4:5], v[178:179], v[82:83] op_sel_hi:[1,0]
	v_pk_mul_f32 v[8:9], v[182:183], v[82:83] op_sel_hi:[1,0]
	v_pk_mul_f32 v[2:3], v[176:177], v[82:83] op_sel_hi:[1,0]
	v_pk_mul_f32 v[6:7], v[180:181], v[82:83] op_sel_hi:[1,0]
	s_nop 0
	s_nop 0
	s_nop 0
	s_nop 0
	s_nop 0
	s_nop 0
	s_nop 0
	s_nop 0
	s_nop 0
	s_nop 0
	s_nop 0
	s_nop 0
	s_nop 0
	s_nop 0
	v_cvt_pk_bf16_f32 v241, v7, v9
	v_cvt_pk_bf16_f32 v7, v3, v5
	v_cvt_pk_bf16_f32 v242, v2, v4
	ds_read2_b64 v[2:5], v83 offset0:136 offset1:138
	v_mov_b32_e32 v9, v241
	v_cvt_pk_bf16_f32 v8, v6, v8
	s_nop 0
	v_mov_b32_e32 v6, v242
	s_waitcnt lgkmcnt(0)
	s_nop 0
	v_mfma_f32_32x32x16_bf16 v[34:49], v[2:5], v[6:9], v[34:49]
	ds_read2_b64 v[2:5], v193 offset0:168 offset1:170
	ds_read2_b64 v[10:13], v83 offset0:140 offset1:142
	s_waitcnt lgkmcnt(1)
	v_mfma_f32_32x32x16_bf16 v[50:65], v[2:5], v[6:9], v[50:65]
	v_mul_f32_e64 v8, v174, v82
	v_mul_f32_e64 v9, v175, v82
	v_mul_f32_e64 v4, v170, v82
	v_mul_f32_e64 v5, v171, v82
	v_mul_f32_e64 v6, v172, v82
	v_mul_f32_e64 v7, v173, v82
	s_nop 0
	v_pk_mul_f32 v[2:3], v[168:169], v[82:83] op_sel_hi:[1,0]
	s_nop 0
	s_nop 0
	s_nop 0
	s_nop 0
	s_nop 0
	s_nop 0
	s_nop 0
	s_nop 0
	s_nop 0
	s_nop 0
	s_nop 0
	v_cvt_pk_bf16_f32 v2, v2, v4
	v_cvt_pk_bf16_f32 v4, v6, v8
	s_nop 0
	s_nop 0
	s_nop 0
	s_nop 0
	s_nop 0
	s_nop 0
	s_nop 0
	v_cvt_pk_bf16_f32 v3, v3, v5
	v_cvt_pk_bf16_f32 v5, v7, v9
	ds_read2_b64 v[6:9], v193 offset0:172 offset1:174
	s_nop 0
	s_nop 0
	s_nop 0
	s_nop 0
	s_nop 0
	s_waitcnt lgkmcnt(1)
	s_nop 0
	v_mfma_f32_32x32x16_bf16 v[34:49], v[10:13], v[2:5], v[34:49]
	s_waitcnt lgkmcnt(0)
	v_mfma_f32_32x32x16_bf16 v[50:65], v[6:9], v[2:5], v[50:65]
.LBB0_972:
	s_and_b64 vcc, exec, s[44:45]
	s_cbranch_vccnz .LBB0_974
	v_pk_mul_f32 v[4:5], v[128:129], v[82:83] op_sel_hi:[1,0]
	v_pk_mul_f32 v[8:9], v[166:167], v[82:83] op_sel_hi:[1,0]
	v_pk_mul_f32 v[2:3], v[32:33], v[82:83] op_sel_hi:[1,0]
	v_pk_mul_f32 v[6:7], v[164:165], v[82:83] op_sel_hi:[1,0]
	s_nop 0
	s_nop 0
	s_nop 0
	s_nop 0
	s_nop 0
	s_nop 0
	s_nop 0
	s_nop 0
	s_nop 0
	s_nop 0
	s_nop 0
	s_nop 0
	s_nop 0
	s_nop 0
	v_cvt_pk_bf16_f32 v241, v7, v9
	v_cvt_pk_bf16_f32 v7, v3, v5
	v_cvt_pk_bf16_f32 v242, v2, v4
	ds_read2_b64 v[2:5], v83 offset0:144 offset1:146
	v_mov_b32_e32 v9, v241
	v_cvt_pk_bf16_f32 v8, v6, v8
	s_nop 0
	v_mov_b32_e32 v6, v242
	s_waitcnt lgkmcnt(0)
	s_nop 0
	v_mfma_f32_32x32x16_bf16 v[34:49], v[2:5], v[6:9], v[34:49]
	ds_read2_b64 v[2:5], v193 offset0:176 offset1:178
	ds_read2_b64 v[10:13], v83 offset0:148 offset1:150
	s_waitcnt lgkmcnt(1)
	v_mfma_f32_32x32x16_bf16 v[50:65], v[2:5], v[6:9], v[50:65]
	v_mul_f32_e64 v8, v30, v82
	v_mul_f32_e64 v9, v31, v82
	v_mul_f32_e64 v4, v26, v82
	v_mul_f32_e64 v5, v27, v82
	v_mul_f32_e64 v6, v28, v82
	v_mul_f32_e64 v7, v29, v82
	s_nop 0
	v_pk_mul_f32 v[2:3], v[24:25], v[82:83] op_sel_hi:[1,0]
	s_nop 0
	s_nop 0
	s_nop 0
	s_nop 0
	s_nop 0
	s_nop 0
	s_nop 0
	s_nop 0
	s_nop 0
	s_nop 0
	s_nop 0
	v_cvt_pk_bf16_f32 v2, v2, v4
	v_cvt_pk_bf16_f32 v4, v6, v8
	s_nop 0
	s_nop 0
	s_nop 0
	s_nop 0
	s_nop 0
	s_nop 0
	s_nop 0
	v_cvt_pk_bf16_f32 v3, v3, v5
	v_cvt_pk_bf16_f32 v5, v7, v9
	ds_read2_b64 v[6:9], v193 offset0:180 offset1:182
	s_nop 0
	s_nop 0
	s_nop 0
	s_nop 0
	s_nop 0
	s_waitcnt lgkmcnt(1)
	s_nop 0
	v_mfma_f32_32x32x16_bf16 v[34:49], v[10:13], v[2:5], v[34:49]
	s_waitcnt lgkmcnt(0)
	v_mfma_f32_32x32x16_bf16 v[50:65], v[6:9], v[2:5], v[50:65]
.LBB0_974:
	v_mov_b32_e32 v14, 0x3100
	s_and_b64 vcc, exec, s[62:63]
	v_mul_u32_u24_e32 v0, 0x188, v187
	v_mad_u32_u24 v128, v187, s2, v14
	s_cbranch_vccz .LBB0_976
	v_pk_mul_f32 v[4:5], v[18:19], v[82:83] op_sel_hi:[1,0]
	v_pk_mul_f32 v[8:9], v[22:23], v[82:83] op_sel_hi:[1,0]
	v_pk_mul_f32 v[2:3], v[16:17], v[82:83] op_sel_hi:[1,0]
	v_pk_mul_f32 v[6:7], v[20:21], v[82:83] op_sel_hi:[1,0]
	s_nop 0
	s_nop 0
	s_nop 0
	s_nop 0
	s_nop 0
	s_nop 0
	s_nop 0
	s_nop 0
	s_nop 0
	s_nop 0
	s_nop 0
	v_cvt_pk_bf16_f32 v167, v3, v5
	v_cvt_pk_bf16_f32 v166, v2, v4
	ds_read2_b64 v[2:5], v83 offset0:152 offset1:154
	v_cvt_pk_bf16_f32 v169, v7, v9
	v_cvt_pk_bf16_f32 v168, v6, v8
	s_nop 0
	s_nop 0
	v_mad_u32_u24 v164, v187, s2, v14
	v_pk_mul_f32 v[122:123], v[122:123], v[82:83] op_sel_hi:[1,0]
	s_waitcnt lgkmcnt(0)
	v_mfma_f32_32x32x16_bf16 v[18:33], v[2:5], v[166:169], v[34:49]
	v_add_u32_e32 v2, v192, v164
	v_add_u32_e32 v129, 0x6800, v2
	ds_read2_b64 v[170:173], v129 offset0:152 offset1:154
	ds_read2_b64 v[174:177], v83 offset0:156 offset1:158
	v_mul_f32_e64 v124, v124, v82
	v_mul_f32_e64 v125, v125, v82
	v_pk_mul_f32 v[126:127], v[126:127], v[82:83] op_sel_hi:[1,0]
	v_pk_mul_f32 v[120:121], v[120:121], v[82:83] op_sel_hi:[1,0]
	s_nop 0
	s_waitcnt lgkmcnt(1)
	v_mfma_f32_32x32x16_bf16 v[2:17], v[170:173], v[166:169], v[50:65]
	s_nop 0
	s_nop 0
	s_nop 0
	s_nop 0
	s_nop 0
	s_nop 0
	s_nop 0
	s_nop 0
	ds_read2_b64 v[166:169], v129 offset0:156 offset1:158
	s_nop 0
	s_nop 0
	s_nop 0
	v_cvt_pk_bf16_f32 v125, v125, v127
	s_nop 0
	s_nop 0
	s_nop 0
	s_nop 0
	s_nop 0
	s_nop 0
	s_nop 0
	v_cvt_pk_bf16_f32 v124, v124, v126
	v_cvt_pk_bf16_f32 v123, v121, v123
	v_cvt_pk_bf16_f32 v122, v120, v122
	v_mul_u32_u24_e32 v120, 0x188, v187
	s_waitcnt lgkmcnt(1)
	v_mfma_f32_32x32x16_bf16 v[18:33], v[174:177], v[122:125], v[18:33]
	s_waitcnt lgkmcnt(0)
	v_mfma_f32_32x32x16_bf16 v[2:17], v[166:169], v[122:125], v[2:17]
	s_cbranch_execz .LBB0_977
	s_branch .LBB0_978

; #define LAS __attribute__((address_space(3)))
; __device__ __forceinline__ unsigned pk2(float lo, float hi) { return f2bf(lo) | (f2bf(hi) << 16); }
; __device__ __forceinline__ void attn_unit(const Args& A, const Ctx& C0, int l, int u_qrow0, int u_nq, int u_krow0, int u_krow1, int u_krow2, int u_g, const float* u_ck, const float* u_cv, unsigned u_vmask) {
;     ...
;         for (int kt = 0; kt < 6; ++kt) {
;             if ((u.vmask >> kt) & 1u) {
; #pragma unroll
;                 for (int s = 0; s < 2; ++s) {
;                     union { bf16x8 v; unsigned w[4]; } pf;
; #pragma unroll
;                     for (int e = 0; e < 4; ++e) pf.w[e] = pk2(sacc[kt][8 * s + 2 * e] * inv, sacc[kt][8 * s + 2 * e + 1] * inv);
; #pragma unroll
;                     for (int dt = 0; dt < 2; ++dt) { const LAS bf16* vp = Vt + (dt * 32 + li) * VP + kt * 32 + 16 * s + 4 * h;
;                         union { bf16x8 v; v2u w[2]; } vf; vf.w[0] = *(const LAS v2u*)vp; vf.w[1] = *(const LAS v2u*)(vp + 8);
;                         oacc[dt] = __builtin_amdgcn_mfma_f32_32x32x16_bf16(vf.v, pf.v, oacc[dt], 0, 0, 0); }
;                 }
;             }
.LBB0_978:
	v_mov_b32_e32 v83, v82
	v_pk_mul_f32 v[36:37], v[94:95], v[82:83]
	v_pk_mul_f32 v[40:41], v[118:119], v[82:83]
	v_pk_mul_f32 v[34:35], v[92:93], v[82:83]
	v_pk_mul_f32 v[38:39], v[96:97], v[82:83]
	s_nop 0
	s_nop 0
	s_nop 0
	s_nop 0
	s_nop 0
	s_nop 0
	s_nop 0
	s_nop 0
	s_nop 0
	s_nop 0
	v_cvt_pk_bf16_f32 v242, v34, v36
	v_add_u32_e32 v34, v192, v120
	s_nop 0
	s_nop 0
	s_nop 0
	v_cvt_pk_bf16_f32 v241, v39, v41
	v_add_u32_e32 v129, 0x6800, v34
	v_cvt_pk_bf16_f32 v39, v35, v37
	ds_read2_b64 v[34:37], v129 offset0:160 offset1:162
	v_mov_b32_e32 v41, v241
	v_add_u32_e32 v0, v192, v164
	v_cvt_pk_bf16_f32 v40, v38, v40
	v_mov_b32_e32 v38, v242
	v_add_u32_e32 v128, 0x6800, v0
	s_and_b64 vcc, exec, s[42:43]
	s_waitcnt lgkmcnt(0)
	v_mfma_f32_32x32x16_bf16 v[18:33], v[34:37], v[38:41], v[18:33]
	ds_read2_b64 v[34:37], v128 offset0:160 offset1:162
	ds_read2_b64 v[42:45], v129 offset0:164 offset1:166
	s_waitcnt lgkmcnt(1)
	v_mfma_f32_32x32x16_bf16 v[2:17], v[34:37], v[38:41], v[2:17]
	v_mul_f32_e64 v40, v90, v82
	v_mul_f32_e64 v41, v91, v83
	v_mul_f32_e64 v36, v86, v82
	v_mul_f32_e64 v37, v87, v83
	v_mul_f32_e64 v38, v88, v82
	v_mul_f32_e64 v39, v89, v83
	s_nop 0
	s_nop 0
	s_nop 0
	s_nop 0
	s_nop 0
	v_pk_mul_f32 v[34:35], v[84:85], v[82:83]
	s_nop 0
	s_nop 0
	s_nop 0
	s_nop 0
	s_nop 0
	s_nop 0
	s_nop 0
	v_cvt_pk_bf16_f32 v34, v34, v36
	v_cvt_pk_bf16_f32 v36, v38, v40
	s_nop 0
	s_nop 0
	s_nop 0
	s_nop 0
	s_nop 0
	s_nop 0
	s_nop 0
	v_cvt_pk_bf16_f32 v35, v35, v37
	v_cvt_pk_bf16_f32 v37, v39, v41
	ds_read2_b64 v[38:41], v128 offset0:164 offset1:166
	s_nop 0
	s_nop 0
	s_nop 0
	s_nop 0
	s_nop 0
	s_waitcnt lgkmcnt(1)
	s_nop 0
	v_mfma_f32_32x32x16_bf16 v[18:33], v[42:45], v[34:37], v[18:33]
	s_waitcnt lgkmcnt(0)
	v_mfma_f32_32x32x16_bf16 v[2:17], v[38:41], v[34:37], v[2:17]
	s_cbranch_vccnz .LBB0_980
	v_pk_mul_f32 v[36:37], v[76:77], v[82:83]
	v_pk_mul_f32 v[40:41], v[80:81], v[82:83]
	v_pk_mul_f32 v[34:35], v[74:75], v[82:83]
	v_pk_mul_f32 v[38:39], v[78:79], v[82:83]
	s_nop 0
	s_nop 0
	s_nop 0
	s_nop 0
	s_nop 0
	s_nop 0
	s_nop 0
	s_nop 0
	s_nop 0
	s_nop 0
	s_nop 0
	s_nop 0
	s_nop 0
	s_nop 0
	v_cvt_pk_bf16_f32 v241, v39, v41
	v_cvt_pk_bf16_f32 v39, v35, v37
	v_cvt_pk_bf16_f32 v242, v34, v36
	ds_read2_b64 v[34:37], v129 offset0:168 offset1:170
	v_mov_b32_e32 v41, v241
	v_cvt_pk_bf16_f32 v40, v38, v40
	s_nop 0
	v_mov_b32_e32 v38, v242
	s_waitcnt lgkmcnt(0)
	s_nop 0
	v_mfma_f32_32x32x16_bf16 v[18:33], v[34:37], v[38:41], v[18:33]
	ds_read2_b64 v[34:37], v128 offset0:168 offset1:170
	ds_read2_b64 v[42:45], v129 offset0:172 offset1:174
	s_waitcnt lgkmcnt(1)
	v_mfma_f32_32x32x16_bf16 v[2:17], v[34:37], v[38:41], v[2:17]
	v_mul_f32_e64 v40, v72, v82
	v_mul_f32_e64 v41, v73, v83
	v_mul_f32_e64 v36, v68, v82
	v_mul_f32_e64 v37, v69, v83
	v_mul_f32_e64 v38, v70, v82
	v_mul_f32_e64 v39, v71, v83
	s_nop 0
	s_nop 0
	s_nop 0
	s_nop 0
	s_nop 0
	v_pk_mul_f32 v[34:35], v[66:67], v[82:83]
	s_nop 0
	s_nop 0
	s_nop 0
	s_nop 0
	s_nop 0
	s_nop 0
	s_nop 0
	v_cvt_pk_bf16_f32 v34, v34, v36
	v_cvt_pk_bf16_f32 v36, v38, v40
	s_nop 0
	s_nop 0
	s_nop 0
	s_nop 0
	s_nop 0
	s_nop 0
	s_nop 0
	v_cvt_pk_bf16_f32 v35, v35, v37
	v_cvt_pk_bf16_f32 v37, v39, v41
	ds_read2_b64 v[38:41], v128 offset0:172 offset1:174
	s_nop 0
	s_nop 0
	s_nop 0
	s_nop 0
	s_nop 0
	s_waitcnt lgkmcnt(1)
	s_nop 0
	v_mfma_f32_32x32x16_bf16 v[18:33], v[42:45], v[34:37], v[18:33]
	s_waitcnt lgkmcnt(0)
	v_mfma_f32_32x32x16_bf16 v[2:17], v[38:41], v[34:37], v[2:17]

; __device__ __forceinline__ float shflx(float v, int mask, int lane) { return __int_as_float(__builtin_amdgcn_ds_bpermute((lane ^ mask) << 2, __float_as_int(v))); }
; __device__ __forceinline__ void attn_unit(const Args& A, const Ctx& C0, int l, int u_qrow0, int u_nq, int u_krow0, int u_krow1, int u_krow2, int u_g, const float* u_ck, const float* u_cv, unsigned u_vmask) {
;     ...
;         float mx = sink;
; #pragma unroll
;         for (int kt = 0; kt < 6; ++kt) { const bool valid = (u.vmask >> kt) & 1u;
; #pragma unroll
;             for (int r = 0; r < 16; ++r) { const int j = kt * 32 + (r & 3) + 8 * (r >> 2) + 4 * h;
;                 const float lg = valid ? sacc[kt][r] * 0.125f + bL[j - qi + 63] : -1e30f; sacc[kt][r] = lg; mx = fmaxf(mx, lg); }
;             asm volatile("" ::: "memory"); }
;         mx = fmaxf(mx, shflx(mx, 32, C.lane));
;         float sum = 0.f;
; #pragma unroll
;         for (int kt = 0; kt < 6; ++kt)
; #pragma unroll
;             for (int r = 0; r < 16; ++r) { const float e = __expf(sacc[kt][r] - mx); sacc[kt][r] = e; sum += e; }
;         sum += shflx(sum, 32, C.lane); sum += __expf(sink - mx);
.LBB0_1066:
	v_max3_f32 v18, v186, v107, v106
	v_max3_f32 v18, v18, v83, v82
	v_max3_f32 v18, v18, v85, v84
	v_max3_f32 v18, v18, v87, v86
	v_max3_f32 v18, v18, v89, v88
	v_max3_f32 v18, v18, v91, v90
	v_max3_f32 v18, v18, v93, v92
	v_max3_f32 v18, v18, v95, v94
	v_max3_f32 v18, v18, v97, v96
	v_max3_f32 v18, v18, v67, v66
	v_max3_f32 v18, v18, v69, v68
	v_max3_f32 v18, v18, v71, v70
	v_max3_f32 v18, v18, v73, v72
	v_max3_f32 v18, v18, v75, v74
	v_max3_f32 v18, v18, v77, v76
	v_max3_f32 v18, v18, v79, v78
	v_max3_f32 v18, v18, v81, v80
	v_max3_f32 v18, v18, v103, v102
	v_max3_f32 v18, v18, v105, v104
	v_max3_f32 v18, v18, v109, v108
	v_max3_f32 v18, v18, v111, v110
	v_max3_f32 v18, v18, v59, v58
	v_max3_f32 v18, v18, v61, v60
	v_max3_f32 v18, v18, v63, v62
	v_max3_f32 v18, v18, v65, v64
	v_max3_f32 v18, v18, v149, v148
	v_max3_f32 v18, v18, v151, v150
	v_max3_f32 v18, v18, v153, v152
	v_max3_f32 v18, v18, v156, v154
	v_max3_f32 v18, v18, v160, v158
	v_max3_f32 v18, v18, v164, v162
	v_max3_f32 v18, v18, v168, v166
	s_waitcnt lgkmcnt(0)
	v_fmamk_f32 v48, v2, 0x3e000000, v48
	v_fmac_f32_e32 v49, 0x3e000000, v3
	v_max3_f32 v2, v18, v48, v49
	v_fmamk_f32 v46, v4, 0x3e000000, v46
	v_fmac_f32_e32 v47, 0x3e000000, v5
	v_max3_f32 v2, v2, v46, v47
	v_fmamk_f32 v44, v6, 0x3e000000, v44
	v_fmac_f32_e32 v45, 0x3e000000, v7
	v_max3_f32 v2, v2, v44, v45
	v_fmamk_f32 v42, v8, 0x3e000000, v42
	v_fmac_f32_e32 v43, 0x3e000000, v9
	v_max3_f32 v2, v2, v42, v43
	v_fmamk_f32 v40, v10, 0x3e000000, v40
	v_fmac_f32_e32 v41, 0x3e000000, v11
	v_max3_f32 v2, v2, v40, v41
	v_fmamk_f32 v38, v12, 0x3e000000, v38
	v_fmac_f32_e32 v39, 0x3e000000, v13
	v_max3_f32 v2, v2, v38, v39
	v_fmamk_f32 v36, v14, 0x3e000000, v36
	v_fmac_f32_e32 v37, 0x3e000000, v15
	v_max3_f32 v2, v2, v36, v37
	v_fmamk_f32 v34, v16, 0x3e000000, v34
	v_fmac_f32_e32 v35, 0x3e000000, v17
	v_max3_f32 v2, v2, v34, v35
	v_max3_f32 v2, v2, v157, v155
	v_max3_f32 v2, v2, v161, v159
	v_max3_f32 v2, v2, v165, v163
	v_max3_f32 v2, v2, v169, v167
	v_max3_f32 v2, v2, v171, v170
	v_max3_f32 v2, v2, v173, v172
	v_max3_f32 v2, v2, v175, v174
	v_max3_f32 v2, v2, v177, v176
	ds_bpermute_b32 v3, v189, v2
	s_waitcnt lgkmcnt(0)
	v_max_f32_e32 v3, v3, v3
	v_max_f32_e32 v178, v2, v3
	v_sub_f32_e32 v3, v85, v178
	v_mul_f32_e32 v3, 0x3fb8aa3b, v3
	v_exp_f32_e32 v54, v3
	v_sub_f32_e32 v3, v84, v178
	v_mul_f32_e32 v3, 0x3fb8aa3b, v3
	v_exp_f32_e32 v56, v3
	v_sub_f32_e32 v3, v87, v178
	v_mul_f32_e32 v3, 0x3fb8aa3b, v3
	v_exp_f32_e32 v55, v3
	v_sub_f32_e32 v3, v86, v178
	v_mul_f32_e32 v3, 0x3fb8aa3b, v3
	v_exp_f32_e32 v57, v3
	v_sub_f32_e32 v3, v89, v178
	v_mul_f32_e32 v3, 0x3fb8aa3b, v3
	v_exp_f32_e32 v120, v3
	v_sub_f32_e32 v3, v88, v178
	v_mul_f32_e32 v3, 0x3fb8aa3b, v3
	v_exp_f32_e32 v122, v3
	v_sub_f32_e32 v3, v91, v178
	v_mul_f32_e32 v3, 0x3fb8aa3b, v3
	v_exp_f32_e32 v121, v3
	v_sub_f32_e32 v3, v90, v178
	v_mul_f32_e32 v3, 0x3fb8aa3b, v3
	v_exp_f32_e32 v123, v3
	v_sub_f32_e32 v3, v93, v178
	v_mul_f32_e32 v3, 0x3fb8aa3b, v3
	v_exp_f32_e32 v124, v3
	v_sub_f32_e32 v3, v92, v178
	v_mul_f32_e32 v3, 0x3fb8aa3b, v3
	v_exp_f32_e32 v126, v3
	v_sub_f32_e32 v3, v95, v178
	v_mul_f32_e32 v3, 0x3fb8aa3b, v3
	v_exp_f32_e32 v125, v3
	v_sub_f32_e32 v3, v94, v178
	v_mul_f32_e32 v3, 0x3fb8aa3b, v3
	v_exp_f32_e32 v127, v3
	v_sub_f32_e32 v3, v97, v178
	v_mul_f32_e32 v3, 0x3fb8aa3b, v3
	v_exp_f32_e32 v112, v3
	v_sub_f32_e32 v3, v96, v178
	v_mul_f32_e32 v3, 0x3fb8aa3b, v3
	v_exp_f32_e32 v114, v3
	v_sub_f32_e32 v3, v67, v178
	v_mul_f32_e32 v3, 0x3fb8aa3b, v3
	v_exp_f32_e32 v113, v3
	v_sub_f32_e32 v3, v66, v178
	v_mul_f32_e32 v3, 0x3fb8aa3b, v3
	v_exp_f32_e32 v115, v3
	v_sub_f32_e32 v3, v69, v178
	v_mul_f32_e32 v3, 0x3fb8aa3b, v3
	v_exp_f32_e32 v116, v3
	v_sub_f32_e32 v3, v68, v178
	v_mul_f32_e32 v3, 0x3fb8aa3b, v3
	v_sub_f32_e32 v2, v107, v178
	v_exp_f32_e32 v118, v3
	v_sub_f32_e32 v3, v71, v178
	v_mul_f32_e32 v2, 0x3fb8aa3b, v2
	v_mul_f32_e32 v3, 0x3fb8aa3b, v3
	v_exp_f32_e32 v50, v2
	v_sub_f32_e32 v2, v106, v178
	v_exp_f32_e32 v117, v3
	v_sub_f32_e32 v3, v70, v178
	v_mul_f32_e32 v2, 0x3fb8aa3b, v2
	v_mul_f32_e32 v3, 0x3fb8aa3b, v3
	v_exp_f32_e32 v52, v2
	v_sub_f32_e32 v2, v83, v178
	v_exp_f32_e32 v119, v3
	v_sub_f32_e32 v3, v73, v178
	v_mul_f32_e32 v2, 0x3fb8aa3b, v2
	v_mul_f32_e32 v3, 0x3fb8aa3b, v3
	v_exp_f32_e32 v51, v2
	v_sub_f32_e32 v2, v82, v178
	v_exp_f32_e32 v26, v3
	v_sub_f32_e32 v3, v72, v178
	v_mul_f32_e32 v2, 0x3fb8aa3b, v2
	v_mul_f32_e32 v3, 0x3fb8aa3b, v3
	v_exp_f32_e32 v53, v2
	v_exp_f32_e32 v28, v3
	v_sub_f32_e32 v3, v75, v178
	v_add_f32_e32 v2, 0, v50
	v_mul_f32_e32 v3, 0x3fb8aa3b, v3
	v_add_f32_e32 v2, v52, v2
	v_exp_f32_e32 v27, v3
	v_sub_f32_e32 v3, v74, v178
	v_add_f32_e32 v2, v51, v2
	v_mul_f32_e32 v3, 0x3fb8aa3b, v3
	v_add_f32_e32 v2, v53, v2
	v_exp_f32_e32 v29, v3
	v_sub_f32_e32 v3, v77, v178
	v_add_f32_e32 v2, v54, v2
	v_mul_f32_e32 v3, 0x3fb8aa3b, v3
	v_add_f32_e32 v2, v56, v2
	v_exp_f32_e32 v30, v3
	v_sub_f32_e32 v3, v76, v178
	v_add_f32_e32 v2, v55, v2
	v_mul_f32_e32 v3, 0x3fb8aa3b, v3
	v_add_f32_e32 v2, v57, v2
	v_exp_f32_e32 v32, v3
	v_sub_f32_e32 v3, v79, v178
	v_add_f32_e32 v2, v120, v2
	v_mul_f32_e32 v3, 0x3fb8aa3b, v3
	v_add_f32_e32 v2, v122, v2
	v_exp_f32_e32 v31, v3
	v_sub_f32_e32 v3, v78, v178
	v_add_f32_e32 v2, v121, v2
	v_mul_f32_e32 v3, 0x3fb8aa3b, v3
	v_add_f32_e32 v2, v123, v2
	v_exp_f32_e32 v33, v3
	v_sub_f32_e32 v3, v81, v178
	v_add_f32_e32 v2, v124, v2
	v_mul_f32_e32 v3, 0x3fb8aa3b, v3
	v_add_f32_e32 v2, v126, v2
	v_exp_f32_e32 v18, v3
	v_sub_f32_e32 v3, v80, v178
	v_add_f32_e32 v2, v125, v2
	v_mul_f32_e32 v3, 0x3fb8aa3b, v3
	v_add_f32_e32 v2, v127, v2
	v_exp_f32_e32 v20, v3
	v_sub_f32_e32 v3, v103, v178
; __device__ __forceinline__ void attn_unit(const Args& A, const Ctx& C0, int l, int u_qrow0, int u_nq, int u_krow0, int u_krow1, int u_krow2, int u_g, const float* u_ck, const float* u_cv, unsigned u_vmask) {
;     ...
;         float sum = 0.f;
; #pragma unroll
;         for (int kt = 0; kt < 6; ++kt)
; #pragma unroll
;             for (int r = 0; r < 16; ++r) { const float e = __expf(sacc[kt][r] - mx); sacc[kt][r] = e; sum += e; }
	v_add_f32_e32 v2, v112, v2
	v_mul_f32_e32 v3, 0x3fb8aa3b, v3
	v_add_f32_e32 v2, v114, v2
	v_exp_f32_e32 v19, v3
	v_sub_f32_e32 v3, v102, v178
	v_add_f32_e32 v2, v113, v2
	v_mul_f32_e32 v3, 0x3fb8aa3b, v3
	v_add_f32_e32 v2, v115, v2
	v_exp_f32_e32 v21, v3
	v_sub_f32_e32 v3, v105, v178
	v_add_f32_e32 v2, v116, v2
	v_mul_f32_e32 v3, 0x3fb8aa3b, v3
	v_add_f32_e32 v2, v118, v2
	v_exp_f32_e32 v22, v3
	v_sub_f32_e32 v3, v104, v178
	v_add_f32_e32 v2, v117, v2
	v_mul_f32_e32 v3, 0x3fb8aa3b, v3
	v_add_f32_e32 v2, v119, v2
	v_exp_f32_e32 v24, v3
	v_sub_f32_e32 v3, v109, v178
	v_add_f32_e32 v2, v26, v2
	v_mul_f32_e32 v3, 0x3fb8aa3b, v3
	v_add_f32_e32 v2, v28, v2
	v_exp_f32_e32 v23, v3
	v_sub_f32_e32 v3, v108, v178
	v_add_f32_e32 v2, v27, v2
	v_mul_f32_e32 v3, 0x3fb8aa3b, v3
	v_add_f32_e32 v2, v29, v2
	v_exp_f32_e32 v25, v3
	v_sub_f32_e32 v3, v111, v178
	v_add_f32_e32 v2, v30, v2
	v_mul_f32_e32 v3, 0x3fb8aa3b, v3
	v_add_f32_e32 v2, v32, v2
	v_exp_f32_e32 v10, v3
	v_sub_f32_e32 v3, v110, v178
	v_add_f32_e32 v2, v31, v2
	v_mul_f32_e32 v3, 0x3fb8aa3b, v3
	v_add_f32_e32 v2, v33, v2
	v_exp_f32_e32 v12, v3
	v_sub_f32_e32 v3, v59, v178
	v_add_f32_e32 v2, v18, v2
	v_mul_f32_e32 v3, 0x3fb8aa3b, v3
	v_add_f32_e32 v2, v20, v2
	v_exp_f32_e32 v11, v3
	v_sub_f32_e32 v3, v58, v178
	v_add_f32_e32 v2, v19, v2
	v_mul_f32_e32 v3, 0x3fb8aa3b, v3
	v_add_f32_e32 v2, v21, v2
	v_exp_f32_e32 v13, v3
	v_sub_f32_e32 v3, v61, v178
	v_add_f32_e32 v2, v22, v2
	v_mul_f32_e32 v3, 0x3fb8aa3b, v3
	v_add_f32_e32 v2, v24, v2
	v_exp_f32_e32 v14, v3
	v_sub_f32_e32 v3, v60, v178
	v_add_f32_e32 v2, v23, v2
	v_mul_f32_e32 v3, 0x3fb8aa3b, v3
	v_add_f32_e32 v2, v25, v2
	v_exp_f32_e32 v16, v3
	v_sub_f32_e32 v3, v63, v178
	v_add_f32_e32 v2, v10, v2
	v_mul_f32_e32 v3, 0x3fb8aa3b, v3
	v_add_f32_e32 v2, v12, v2
	v_exp_f32_e32 v15, v3
	v_sub_f32_e32 v3, v62, v178
	v_add_f32_e32 v2, v11, v2
	v_mul_f32_e32 v3, 0x3fb8aa3b, v3
	v_add_f32_e32 v2, v13, v2
	v_exp_f32_e32 v17, v3
	v_add_f32_e32 v2, v14, v2
	v_add_f32_e32 v2, v16, v2
	v_add_f32_e32 v2, v15, v2
	v_add_f32_e32 v6, v17, v2
	v_sub_f32_e32 v2, v65, v178
	v_sub_f32_e32 v3, v64, v178
	v_mul_f32_e32 v2, 0x3fb8aa3b, v2
	v_mul_f32_e32 v3, 0x3fb8aa3b, v3
	v_exp_f32_e32 v2, v2
	v_exp_f32_e32 v4, v3
	v_sub_f32_e32 v3, v149, v178
	v_mul_f32_e32 v3, 0x3fb8aa3b, v3
	v_sub_f32_e32 v5, v148, v178
	v_exp_f32_e32 v3, v3
	v_mul_f32_e32 v5, 0x3fb8aa3b, v5
	v_exp_f32_e32 v5, v5
	v_add_f32_e32 v6, v2, v6
	v_sub_f32_e32 v59, v156, v178
	v_add_f32_e32 v6, v4, v6
	v_mul_f32_e32 v59, 0x3fb8aa3b, v59
	v_add_f32_e32 v6, v3, v6
	v_exp_f32_e32 v104, v59
	v_sub_f32_e32 v59, v154, v178
	v_add_f32_e32 v58, v5, v6
	v_sub_f32_e32 v6, v151, v178
	v_sub_f32_e32 v7, v150, v178
	v_mul_f32_e32 v59, 0x3fb8aa3b, v59
	v_mul_f32_e32 v6, 0x3fb8aa3b, v6
	v_mul_f32_e32 v7, 0x3fb8aa3b, v7
	v_exp_f32_e32 v106, v59
	v_sub_f32_e32 v59, v160, v178
	v_exp_f32_e32 v6, v6
	v_exp_f32_e32 v8, v7
	v_sub_f32_e32 v7, v153, v178
	v_mul_f32_e32 v59, 0x3fb8aa3b, v59
	v_mul_f32_e32 v7, 0x3fb8aa3b, v7
	v_sub_f32_e32 v9, v152, v178
	v_exp_f32_e32 v105, v59
	v_sub_f32_e32 v59, v158, v178
	v_exp_f32_e32 v7, v7
	v_mul_f32_e32 v9, 0x3fb8aa3b, v9
	v_mul_f32_e32 v59, 0x3fb8aa3b, v59
	v_exp_f32_e32 v9, v9
	v_exp_f32_e32 v107, v59
	v_sub_f32_e32 v59, v164, v178
	v_add_f32_e32 v58, v6, v58
	v_mul_f32_e32 v59, 0x3fb8aa3b, v59
	v_add_f32_e32 v58, v8, v58
	v_exp_f32_e32 v108, v59
	v_sub_f32_e32 v59, v162, v178
	v_add_f32_e32 v58, v7, v58
	v_mul_f32_e32 v59, 0x3fb8aa3b, v59
	v_add_f32_e32 v58, v9, v58
	v_exp_f32_e32 v110, v59
	v_sub_f32_e32 v59, v168, v178
	v_add_f32_e32 v58, v104, v58
	v_mul_f32_e32 v59, 0x3fb8aa3b, v59
	v_add_f32_e32 v58, v106, v58
	v_exp_f32_e32 v109, v59
	v_sub_f32_e32 v59, v166, v178
	v_sub_f32_e32 v48, v48, v178
	v_sub_f32_e32 v34, v34, v178
	v_add_f32_e32 v58, v105, v58
	v_mul_f32_e32 v59, 0x3fb8aa3b, v59
	v_mul_f32_e32 v48, 0x3fb8aa3b, v48
	v_mul_f32_e32 v34, 0x3fb8aa3b, v34
	v_add_f32_e32 v58, v107, v58
	v_exp_f32_e32 v111, v59
	v_exp_f32_e32 v92, v48
	v_sub_f32_e32 v48, v49, v178
	v_sub_f32_e32 v46, v46, v178
	v_exp_f32_e32 v89, v34
	v_sub_f32_e32 v34, v35, v178
	v_sub_f32_e32 v35, v157, v178
	v_add_f32_e32 v58, v108, v58
	v_mul_f32_e32 v48, 0x3fb8aa3b, v48
	v_mul_f32_e32 v46, 0x3fb8aa3b, v46
	v_mul_f32_e32 v35, 0x3fb8aa3b, v35
	v_add_f32_e32 v58, v110, v58
	v_exp_f32_e32 v94, v48
	v_exp_f32_e32 v93, v46
	v_sub_f32_e32 v46, v47, v178
	v_sub_f32_e32 v44, v44, v178
	v_exp_f32_e32 v74, v35
	v_sub_f32_e32 v35, v155, v178
	v_add_f32_e32 v58, v109, v58
	v_mul_f32_e32 v46, 0x3fb8aa3b, v46
	v_mul_f32_e32 v44, 0x3fb8aa3b, v44
	v_mul_f32_e32 v35, 0x3fb8aa3b, v35
	v_add_f32_e32 v58, v111, v58
	v_exp_f32_e32 v95, v46
	v_exp_f32_e32 v96, v44
	v_sub_f32_e32 v44, v45, v178
	v_sub_f32_e32 v42, v42, v178
	v_exp_f32_e32 v76, v35
	v_sub_f32_e32 v35, v161, v178
	v_add_f32_e32 v46, v92, v58
	v_mul_f32_e32 v44, 0x3fb8aa3b, v44
	v_mul_f32_e32 v42, 0x3fb8aa3b, v42
	v_mul_f32_e32 v35, 0x3fb8aa3b, v35
	v_add_f32_e32 v46, v94, v46
	v_exp_f32_e32 v102, v44
	v_exp_f32_e32 v97, v42
; #define LAS __attribute__((address_space(3)))
; __device__ __forceinline__ unsigned pk2(float lo, float hi) { return f2bf(lo) | (f2bf(hi) << 16); }
; __device__ __forceinline__ float shflx(float v, int mask, int lane) { return __int_as_float(__builtin_amdgcn_ds_bpermute((lane ^ mask) << 2, __float_as_int(v))); }
; __device__ __forceinline__ void attn_unit(const Args& A, const Ctx& C0, int l, int u_qrow0, int u_nq, int u_krow0, int u_krow1, int u_krow2, int u_g, const float* u_ck, const float* u_cv, unsigned u_vmask) {
;     ...
;         for (int kt = 0; kt < 6; ++kt)
; #pragma unroll
;             for (int r = 0; r < 16; ++r) { const float e = __expf(sacc[kt][r] - mx); sacc[kt][r] = e; sum += e; }
;         sum += shflx(sum, 32, C.lane); sum += __expf(sink - mx);
;         const float inv = 1.f / sum;
;         f32x16 oacc[2];
; #pragma unroll
;         for (int dt = 0; dt < 2; ++dt)
; #pragma unroll
;             for (int r = 0; r < 16; ++r) oacc[dt][r] = 0.f;
; #pragma unroll
;         for (int kt = 0; kt < 6; ++kt) {
;             if ((u.vmask >> kt) & 1u) {
; #pragma unroll
;                 for (int s = 0; s < 2; ++s) {
;                     union { bf16x8 v; unsigned w[4]; } pf;
; #pragma unroll
;                     for (int e = 0; e < 4; ++e) pf.w[e] = pk2(sacc[kt][8 * s + 2 * e] * inv, sacc[kt][8 * s + 2 * e + 1] * inv);
; #pragma unroll
;                     for (int dt = 0; dt < 2; ++dt) { const LAS bf16* vp = Vt + (dt * 32 + li) * VP + kt * 32 + 16 * s + 4 * h;
;                         union { bf16x8 v; v2u w[2]; } vf; vf.w[0] = *(const LAS v2u*)vp; vf.w[1] = *(const LAS v2u*)(vp + 8);
;                         oacc[dt] = __builtin_amdgcn_mfma_f32_32x32x16_bf16(vf.v, pf.v, oacc[dt], 0, 0, 0); }
	v_sub_f32_e32 v42, v43, v178
	v_sub_f32_e32 v40, v40, v178
	v_exp_f32_e32 v75, v35
	v_sub_f32_e32 v35, v159, v178
	v_add_f32_e32 v46, v93, v46
	v_mul_f32_e32 v42, 0x3fb8aa3b, v42
	v_mul_f32_e32 v40, 0x3fb8aa3b, v40
	v_mul_f32_e32 v35, 0x3fb8aa3b, v35
	v_add_f32_e32 v46, v95, v46
	v_exp_f32_e32 v103, v42
	v_exp_f32_e32 v84, v40
	v_sub_f32_e32 v40, v41, v178
	v_sub_f32_e32 v38, v38, v178
	v_exp_f32_e32 v77, v35
	v_sub_f32_e32 v35, v165, v178
	v_add_f32_e32 v42, v96, v46
	v_mul_f32_e32 v40, 0x3fb8aa3b, v40
	v_mul_f32_e32 v38, 0x3fb8aa3b, v38
	v_mul_f32_e32 v35, 0x3fb8aa3b, v35
	v_add_f32_e32 v42, v102, v42
	v_exp_f32_e32 v86, v40
	v_exp_f32_e32 v85, v38
	v_sub_f32_e32 v38, v39, v178
	v_sub_f32_e32 v36, v36, v178
	v_exp_f32_e32 v78, v35
	v_sub_f32_e32 v35, v163, v178
	v_add_f32_e32 v42, v97, v42
	v_mul_f32_e32 v38, 0x3fb8aa3b, v38
	v_mul_f32_e32 v36, 0x3fb8aa3b, v36
	v_mul_f32_e32 v35, 0x3fb8aa3b, v35
	v_add_f32_e32 v42, v103, v42
	v_exp_f32_e32 v87, v38
	v_exp_f32_e32 v88, v36
	v_sub_f32_e32 v36, v37, v178
	v_exp_f32_e32 v80, v35
	v_sub_f32_e32 v35, v169, v178
	v_add_f32_e32 v38, v84, v42
	v_mul_f32_e32 v36, 0x3fb8aa3b, v36
	v_mul_f32_e32 v35, 0x3fb8aa3b, v35
	v_add_f32_e32 v38, v86, v38
	v_exp_f32_e32 v90, v36
	v_exp_f32_e32 v79, v35
	v_sub_f32_e32 v35, v167, v178
	v_add_f32_e32 v38, v85, v38
	v_mul_f32_e32 v34, 0x3fb8aa3b, v34
	v_mul_f32_e32 v35, 0x3fb8aa3b, v35
	v_add_f32_e32 v38, v87, v38
	v_exp_f32_e32 v91, v34
	v_exp_f32_e32 v81, v35
	v_sub_f32_e32 v35, v171, v178
	v_add_f32_e32 v34, v88, v38
	v_mul_f32_e32 v35, 0x3fb8aa3b, v35
	v_add_f32_e32 v34, v90, v34
	v_exp_f32_e32 v66, v35
	v_sub_f32_e32 v35, v170, v178
	v_add_f32_e32 v34, v89, v34
	v_mul_f32_e32 v35, 0x3fb8aa3b, v35
	v_add_f32_e32 v34, v91, v34
	v_exp_f32_e32 v68, v35
	v_sub_f32_e32 v35, v173, v178
	v_add_f32_e32 v34, v74, v34
	v_mul_f32_e32 v35, 0x3fb8aa3b, v35
	v_add_f32_e32 v34, v76, v34
	v_exp_f32_e32 v67, v35
	v_sub_f32_e32 v35, v172, v178
	v_add_f32_e32 v34, v75, v34
	v_mul_f32_e32 v35, 0x3fb8aa3b, v35
	v_add_f32_e32 v34, v77, v34
	v_exp_f32_e32 v69, v35
	v_sub_f32_e32 v35, v175, v178
	v_add_f32_e32 v34, v78, v34
	v_mul_f32_e32 v35, 0x3fb8aa3b, v35
	v_add_f32_e32 v34, v80, v34
	v_exp_f32_e32 v70, v35
	v_sub_f32_e32 v35, v174, v178
	v_add_f32_e32 v34, v79, v34
	v_mul_f32_e32 v35, 0x3fb8aa3b, v35
	v_add_f32_e32 v34, v81, v34
	v_exp_f32_e32 v72, v35
	v_sub_f32_e32 v35, v177, v178
	v_add_f32_e32 v34, v66, v34
	v_mul_f32_e32 v35, 0x3fb8aa3b, v35
	v_add_f32_e32 v34, v68, v34
	v_exp_f32_e32 v71, v35
	v_sub_f32_e32 v35, v176, v178
	v_add_f32_e32 v34, v67, v34
	v_mul_f32_e32 v35, 0x3fb8aa3b, v35
	v_add_f32_e32 v34, v69, v34
	v_exp_f32_e32 v73, v35
	v_add_f32_e32 v34, v70, v34
	v_add_f32_e32 v34, v72, v34
	v_add_f32_e32 v34, v71, v34
	v_add_f32_e32 v34, v73, v34
	ds_bpermute_b32 v35, v189, v34
	v_sub_f32_e32 v36, v186, v178
	v_mul_f32_e32 v36, 0x3fb8aa3b, v36
	v_exp_f32_e32 v36, v36
	s_waitcnt lgkmcnt(0)
	v_add_f32_e32 v34, v34, v35
	v_add_f32_e32 v34, v36, v34
	v_div_scale_f32 v35, s[2:3], v34, v34, 1.0
	v_rcp_f32_e32 v36, v35
	s_nop 0
	v_fma_f32 v37, -v35, v36, 1.0
	v_fmac_f32_e32 v36, v37, v36
	v_div_scale_f32 v37, vcc, 1.0, v34, 1.0
	v_mul_f32_e32 v38, v37, v36
	v_fma_f32 v39, -v35, v38, v37
	v_fmac_f32_e32 v38, v39, v36
	v_fma_f32 v35, -v35, v38, v37
	v_div_fmas_f32 v35, v35, v36, v38
	s_and_b64 vcc, exec, s[38:39]
	v_div_fixup_f32 v82, v35, v34, 1.0
	s_cbranch_vccnz .LBB0_1143
	v_pk_mul_f32 v[36:37], v[52:53], v[82:83] op_sel_hi:[1,0]
	v_pk_mul_f32 v[40:41], v[56:57], v[82:83] op_sel_hi:[1,0]
	v_pk_mul_f32 v[34:35], v[50:51], v[82:83] op_sel_hi:[1,0]
	v_pk_mul_f32 v[38:39], v[54:55], v[82:83] op_sel_hi:[1,0]
	s_nop 0
	s_nop 0
	v_cvt_pk_bf16_f32 v241, v35, v37
	v_cvt_pk_bf16_f32 v242, v34, v36
	ds_read2_b64 v[34:37], v129 offset0:128 offset1:130
	v_pk_mul_f32 v[126:127], v[126:127], v[82:83] op_sel_hi:[1,0]
	v_cvt_pk_bf16_f32 v41, v39, v41
	v_cvt_pk_bf16_f32 v40, v38, v40
	v_mov_b32_e32 v39, v241
	v_mov_b32_e32 v38, v242
	v_pk_mul_f32 v[120:121], v[120:121], v[82:83] op_sel_hi:[1,0]
	v_pk_mul_f32 v[122:123], v[122:123], v[82:83] op_sel_hi:[1,0]
	v_pk_mul_f32 v[124:125], v[124:125], v[82:83] op_sel_hi:[1,0]
	s_nop 0
	s_waitcnt lgkmcnt(0)
	v_mfma_f32_32x32x16_bf16 v[50:65], v[34:37], v[38:41], 0
	ds_read2_b64 v[34:37], v128 offset0:128 offset1:130
	ds_read2_b64 v[148:151], v129 offset0:132 offset1:134
	s_nop 0
	s_nop 0
	s_nop 0
	s_nop 0
	s_nop 0
	s_nop 0
	s_nop 0
	s_nop 0
	s_nop 0
	s_nop 0
	s_nop 0
	v_cvt_pk_bf16_f32 v120, v120, v122
	v_cvt_pk_bf16_f32 v122, v124, v126
	s_nop 0
	s_nop 0
	s_nop 0
	s_nop 0
	s_nop 0
	s_nop 0
	s_nop 0
	v_cvt_pk_bf16_f32 v121, v121, v123
	v_cvt_pk_bf16_f32 v123, v125, v127
	ds_read2_b64 v[124:127], v128 offset0:132 offset1:134
	s_waitcnt lgkmcnt(0)
	v_mfma_f32_32x32x16_bf16 v[34:49], v[34:37], v[38:41], 0
	s_nop 0
	s_nop 0
	s_nop 0
	s_nop 0
	s_nop 0
	s_nop 1
	v_mfma_f32_32x32x16_bf16 v[50:65], v[148:151], v[120:123], v[50:65]
	v_mfma_f32_32x32x16_bf16 v[34:49], v[124:127], v[120:123], v[34:49]
	s_branch .LBB0_1144

; #define LAS __attribute__((address_space(3)))
; __device__ __forceinline__ unsigned pk2(float lo, float hi) { return f2bf(lo) | (f2bf(hi) << 16); }
; __device__ __forceinline__ void attn_unit(const Args& A, const Ctx& C0, int l, int u_qrow0, int u_nq, int u_krow0, int u_krow1, int u_krow2, int u_g, const float* u_ck, const float* u_cv, unsigned u_vmask) {
;     ...
;         for (int kt = 0; kt < 6; ++kt) {
;             if ((u.vmask >> kt) & 1u) {
; #pragma unroll
;                 for (int s = 0; s < 2; ++s) {
;                     union { bf16x8 v; unsigned w[4]; } pf;
; #pragma unroll
;                     for (int e = 0; e < 4; ++e) pf.w[e] = pk2(sacc[kt][8 * s + 2 * e] * inv, sacc[kt][8 * s + 2 * e + 1] * inv);
; #pragma unroll
;                     for (int dt = 0; dt < 2; ++dt) { const LAS bf16* vp = Vt + (dt * 32 + li) * VP + kt * 32 + 16 * s + 4 * h;
;                         union { bf16x8 v; v2u w[2]; } vf; vf.w[0] = *(const LAS v2u*)vp; vf.w[1] = *(const LAS v2u*)(vp + 8);
;                         oacc[dt] = __builtin_amdgcn_mfma_f32_32x32x16_bf16(vf.v, pf.v, oacc[dt], 0, 0, 0); }
;                 }
;             }
.LBB0_1144:
	s_and_b64 vcc, exec, s[40:41]
	s_cbranch_vccnz .LBB0_1146
	v_pk_mul_f32 v[114:115], v[114:115], v[82:83] op_sel_hi:[1,0]
	v_pk_mul_f32 v[118:119], v[118:119], v[82:83] op_sel_hi:[1,0]
	v_pk_mul_f32 v[112:113], v[112:113], v[82:83] op_sel_hi:[1,0]
	v_pk_mul_f32 v[116:117], v[116:117], v[82:83] op_sel_hi:[1,0]
	v_bfe_u32 v83, v119, 16, 1
	s_nop 0
	s_nop 0
	s_nop 0
	s_nop 0
	s_nop 0
	s_nop 0
	v_add3_u32 v83, v119, v83, s33
	s_nop 0
	s_nop 0
	s_nop 0
	v_bfe_u32 v120, v117, 16, 1
	v_add3_u32 v117, v117, v120, s33
	s_nop 0
	v_cvt_pk_bf16_f32 v241, v113, v115
	v_cvt_pk_bf16_f32 v242, v112, v114
	ds_read2_b64 v[112:115], v129 offset0:136 offset1:138
	v_lshrrev_b32_e32 v117, 16, v117
	v_and_or_b32 v119, v83, s96, v117
	v_cvt_pk_bf16_f32 v118, v116, v118
	v_mov_b32_e32 v117, v241
	v_mov_b32_e32 v116, v242
	v_pk_mul_f32 v[28:29], v[28:29], v[82:83] op_sel_hi:[1,0]
	v_pk_mul_f32 v[32:33], v[32:33], v[82:83] op_sel_hi:[1,0]
	s_waitcnt lgkmcnt(0)
	v_mfma_f32_32x32x16_bf16 v[50:65], v[112:115], v[116:119], v[50:65]
	ds_read2_b64 v[112:115], v128 offset0:136 offset1:138
	ds_read2_b64 v[120:123], v129 offset0:140 offset1:142
	v_mul_f32_e64 v26, v26, v82
	v_mul_f32_e64 v27, v27, v82
	v_mul_f32_e64 v30, v30, v82
	v_mul_f32_e64 v31, v31, v82
	s_nop 0
	s_waitcnt lgkmcnt(0)
	v_mfma_f32_32x32x16_bf16 v[34:49], v[112:115], v[116:119], v[34:49]
	s_nop 0
	v_bfe_u32 v113, v29, 16, 1
	v_bfe_u32 v114, v28, 16, 1
	v_add3_u32 v114, v28, v114, s33
	v_add3_u32 v113, v29, v113, s33
	s_nop 0
	s_nop 0
	s_nop 0
	s_nop 0
	s_nop 0
	s_nop 0
	v_cvt_pk_bf16_f32 v28, v30, v32
	v_bfe_u32 v32, v26, 16, 1
	v_cvt_pk_bf16_f32 v29, v31, v33
	v_bfe_u32 v33, v27, 16, 1
	s_nop 0
	s_nop 0
	v_add3_u32 v27, v27, v33, s33
	v_add3_u32 v26, v26, v32, s33
	s_nop 0
	ds_read2_b64 v[30:33], v128 offset0:140 offset1:142
	v_lshrrev_b32_e32 v26, 16, v26
	v_lshrrev_b32_e32 v27, 16, v27
	v_and_or_b32 v27, v113, s96, v27
	v_and_or_b32 v26, v114, s96, v26
	s_nop 1
	v_mfma_f32_32x32x16_bf16 v[50:65], v[120:123], v[26:29], v[50:65]
	s_waitcnt lgkmcnt(0)
	v_mfma_f32_32x32x16_bf16 v[34:49], v[30:33], v[26:29], v[34:49]
.LBB0_1146:
	s_and_b64 vcc, exec, s[44:45]
	s_cbranch_vccnz .LBB0_1148
	v_pk_mul_f32 v[20:21], v[20:21], v[82:83] op_sel_hi:[1,0]
	v_pk_mul_f32 v[24:25], v[24:25], v[82:83] op_sel_hi:[1,0]
	v_pk_mul_f32 v[18:19], v[18:19], v[82:83] op_sel_hi:[1,0]
	v_pk_mul_f32 v[22:23], v[22:23], v[82:83] op_sel_hi:[1,0]
	s_nop 0
	s_nop 0
	s_nop 0
	s_nop 0
	s_nop 0
	s_nop 0
	s_nop 0
	s_nop 0
	s_nop 0
	s_nop 0
	s_nop 0
	s_nop 0
	s_nop 0
	s_nop 0
	v_cvt_pk_bf16_f32 v241, v19, v21
	v_cvt_pk_bf16_f32 v242, v18, v20
	ds_read2_b64 v[18:21], v129 offset0:144 offset1:146
	v_cvt_pk_bf16_f32 v25, v23, v25
	v_cvt_pk_bf16_f32 v24, v22, v24
	v_mov_b32_e32 v23, v241
	v_mov_b32_e32 v22, v242
	v_pk_mul_f32 v[12:13], v[12:13], v[82:83] op_sel_hi:[1,0]
	v_pk_mul_f32 v[16:17], v[16:17], v[82:83] op_sel_hi:[1,0]
	s_waitcnt lgkmcnt(0)
	v_mfma_f32_32x32x16_bf16 v[50:65], v[18:21], v[22:25], v[50:65]
	ds_read2_b64 v[18:21], v128 offset0:144 offset1:146
	ds_read2_b64 v[26:29], v129 offset0:148 offset1:150
	v_mul_f32_e64 v14, v14, v82
	v_mul_f32_e64 v15, v15, v82
	v_mul_f32_e64 v10, v10, v82
	v_mul_f32_e64 v11, v11, v82
	s_waitcnt lgkmcnt(0)
	v_mfma_f32_32x32x16_bf16 v[34:49], v[18:21], v[22:25], v[34:49]
	s_nop 0
	s_nop 0
	v_bfe_u32 v20, v13, 16, 1
	v_bfe_u32 v21, v12, 16, 1
	v_add3_u32 v21, v12, v21, s33
	v_add3_u32 v20, v13, v20, s33
	s_nop 0
	s_nop 0
	s_nop 0
	s_nop 0
	s_nop 0
	s_nop 0
	v_cvt_pk_bf16_f32 v12, v14, v16
	v_bfe_u32 v16, v10, 16, 1
	v_cvt_pk_bf16_f32 v13, v15, v17
	v_bfe_u32 v17, v11, 16, 1
	s_nop 0
	s_nop 0
	v_add3_u32 v11, v11, v17, s33
	v_add3_u32 v10, v10, v16, s33
	ds_read2_b64 v[14:17], v128 offset0:148 offset1:150
	v_lshrrev_b32_e32 v10, 16, v10
	v_lshrrev_b32_e32 v11, 16, v11
	v_and_or_b32 v11, v20, s96, v11
	v_and_or_b32 v10, v21, s96, v10
	s_nop 1
	v_mfma_f32_32x32x16_bf16 v[50:65], v[26:29], v[10:13], v[50:65]
	s_waitcnt lgkmcnt(0)
	v_mfma_f32_32x32x16_bf16 v[34:49], v[14:17], v[10:13], v[34:49]
.LBB0_1148:
	s_and_b64 vcc, exec, s[62:63]
	s_cbranch_vccz .LBB0_1150
	v_pk_mul_f32 v[4:5], v[4:5], v[82:83] op_sel_hi:[1,0]
	v_pk_mul_f32 v[8:9], v[8:9], v[82:83] op_sel_hi:[1,0]
	v_pk_mul_f32 v[2:3], v[2:3], v[82:83] op_sel_hi:[1,0]
	v_pk_mul_f32 v[6:7], v[6:7], v[82:83] op_sel_hi:[1,0]
	s_nop 0
	s_nop 0
	s_nop 0
	s_nop 0
	s_nop 0
	s_nop 0
	s_nop 0
	s_nop 0
	s_nop 0
	s_nop 0
	s_nop 0
	s_nop 0
	s_nop 0
	s_nop 0
	v_cvt_pk_bf16_f32 v113, v3, v5
	v_cvt_pk_bf16_f32 v112, v2, v4
	ds_read2_b64 v[2:5], v129 offset0:152 offset1:154
	ds_read2_b64 v[116:119], v128 offset0:152 offset1:154
	ds_read2_b64 v[120:123], v129 offset0:156 offset1:158
	v_pk_mul_f32 v[110:111], v[110:111], v[82:83] op_sel_hi:[1,0]
	v_cvt_pk_bf16_f32 v115, v7, v9
	v_cvt_pk_bf16_f32 v114, v6, v8
	v_pk_mul_f32 v[104:105], v[104:105], v[82:83] op_sel_hi:[1,0]
	v_pk_mul_f32 v[106:107], v[106:107], v[82:83] op_sel_hi:[1,0]
	v_pk_mul_f32 v[108:109], v[108:109], v[82:83] op_sel_hi:[1,0]
	s_nop 0
	s_waitcnt lgkmcnt(0)
	v_mfma_f32_32x32x16_bf16 v[18:33], v[2:5], v[112:115], v[50:65]
	s_nop 0
	s_nop 0
	s_nop 0
	s_nop 0
	v_mfma_f32_32x32x16_bf16 v[2:17], v[116:119], v[112:115], v[34:49]
	s_nop 0
	s_nop 0
	s_nop 0
	s_nop 0
	s_nop 0
	s_nop 0
	s_nop 0
	s_nop 0
	v_cvt_pk_bf16_f32 v104, v104, v106
	v_cvt_pk_bf16_f32 v106, v108, v110
	s_nop 0
	s_nop 0
	s_nop 0
	s_nop 0
	s_nop 0
	s_nop 0
	v_cvt_pk_bf16_f32 v105, v105, v107
	v_cvt_pk_bf16_f32 v107, v109, v111
	ds_read2_b64 v[108:111], v128 offset0:156 offset1:158
	s_nop 0
	s_nop 0
	s_nop 0
	s_nop 0
	s_nop 0
	s_nop 1
	v_mfma_f32_32x32x16_bf16 v[18:33], v[120:123], v[104:107], v[18:33]
	s_waitcnt lgkmcnt(0)
	v_mfma_f32_32x32x16_bf16 v[2:17], v[108:111], v[104:107], v[2:17]
	s_cbranch_execz .LBB0_1151
	s_branch .LBB0_1152

; #define LAS __attribute__((address_space(3)))
; __device__ __forceinline__ unsigned pk2(float lo, float hi) { return f2bf(lo) | (f2bf(hi) << 16); }
; __device__ __forceinline__ void attn_unit(const Args& A, const Ctx& C0, int l, int u_qrow0, int u_nq, int u_krow0, int u_krow1, int u_krow2, int u_g, const float* u_ck, const float* u_cv, unsigned u_vmask) {
;     ...
;         for (int kt = 0; kt < 6; ++kt) {
;             if ((u.vmask >> kt) & 1u) {
; #pragma unroll
;                 for (int s = 0; s < 2; ++s) {
;                     union { bf16x8 v; unsigned w[4]; } pf;
; #pragma unroll
;                     for (int e = 0; e < 4; ++e) pf.w[e] = pk2(sacc[kt][8 * s + 2 * e] * inv, sacc[kt][8 * s + 2 * e + 1] * inv);
; #pragma unroll
;                     for (int dt = 0; dt < 2; ++dt) { const LAS bf16* vp = Vt + (dt * 32 + li) * VP + kt * 32 + 16 * s + 4 * h;
;                         union { bf16x8 v; v2u w[2]; } vf; vf.w[0] = *(const LAS v2u*)vp; vf.w[1] = *(const LAS v2u*)(vp + 8);
;                         oacc[dt] = __builtin_amdgcn_mfma_f32_32x32x16_bf16(vf.v, pf.v, oacc[dt], 0, 0, 0); }
;                 }
;             }
.LBB0_1152:
	v_mov_b32_e32 v83, v82
	v_pk_mul_f32 v[36:37], v[94:95], v[82:83]
	v_pk_mul_f32 v[40:41], v[102:103], v[82:83]
	v_pk_mul_f32 v[34:35], v[92:93], v[82:83]
	v_pk_mul_f32 v[38:39], v[96:97], v[82:83]
	s_nop 0
	s_nop 0
	s_nop 0
	s_nop 0
	s_nop 0
	s_nop 0
	s_nop 0
	s_nop 0
	s_nop 0
	s_nop 0
	s_nop 0
	s_nop 0
	s_nop 0
	s_nop 0
	s_nop 0
	v_cvt_pk_bf16_f32 v241, v35, v37
	v_cvt_pk_bf16_f32 v242, v34, v36
	ds_read2_b64 v[34:37], v129 offset0:160 offset1:162
	v_cvt_pk_bf16_f32 v41, v39, v41
	v_cvt_pk_bf16_f32 v40, v38, v40
	v_mov_b32_e32 v39, v241
	v_mov_b32_e32 v38, v242
	s_and_b64 vcc, exec, s[42:43]
	s_waitcnt lgkmcnt(0)
	v_mfma_f32_32x32x16_bf16 v[18:33], v[34:37], v[38:41], v[18:33]
	ds_read2_b64 v[34:37], v128 offset0:160 offset1:162
	ds_read2_b64 v[42:45], v129 offset0:164 offset1:166
	s_waitcnt lgkmcnt(0)
	v_mfma_f32_32x32x16_bf16 v[2:17], v[34:37], v[38:41], v[2:17]
	v_mul_f32_e64 v36, v86, v82
	v_mul_f32_e64 v37, v87, v83
	v_mul_f32_e64 v40, v90, v82
	v_mul_f32_e64 v41, v91, v83
	v_mul_f32_e64 v38, v88, v82
	v_mul_f32_e64 v39, v89, v83
	s_nop 0
	s_nop 0
	v_bfe_u32 v48, v37, 16, 1
	v_bfe_u32 v49, v36, 16, 1
	v_add3_u32 v49, v36, v49, s33
	v_add3_u32 v48, v37, v48, s33
	s_nop 0
	s_nop 0
	s_nop 0
	s_nop 0
	v_pk_mul_f32 v[34:35], v[84:85], v[82:83]
	s_nop 0
	s_nop 0
	v_cvt_pk_bf16_f32 v36, v38, v40
	v_bfe_u32 v40, v34, 16, 1
	v_cvt_pk_bf16_f32 v37, v39, v41
	v_bfe_u32 v41, v35, 16, 1
	v_add3_u32 v35, v35, v41, s33
	v_add3_u32 v34, v34, v40, s33
	ds_read2_b64 v[38:41], v128 offset0:164 offset1:166
	v_lshrrev_b32_e32 v34, 16, v34
	v_lshrrev_b32_e32 v35, 16, v35
	v_and_or_b32 v35, v48, s96, v35
	v_and_or_b32 v34, v49, s96, v34
	s_nop 1
	v_mfma_f32_32x32x16_bf16 v[18:33], v[42:45], v[34:37], v[18:33]
	s_waitcnt lgkmcnt(0)
	v_mfma_f32_32x32x16_bf16 v[2:17], v[38:41], v[34:37], v[2:17]
	s_cbranch_vccnz .LBB0_1154
	v_pk_mul_f32 v[36:37], v[76:77], v[82:83]
	v_pk_mul_f32 v[40:41], v[80:81], v[82:83]
	v_pk_mul_f32 v[34:35], v[74:75], v[82:83]
	v_pk_mul_f32 v[38:39], v[78:79], v[82:83]
	s_nop 0
	s_nop 0
	s_nop 0
	s_nop 0
	s_nop 0
	s_nop 0
	s_nop 0
	s_nop 0
	s_nop 0
	s_nop 0
	s_nop 0
	s_nop 0
	s_nop 0
	s_nop 0
	s_nop 0
	v_cvt_pk_bf16_f32 v241, v35, v37
	v_cvt_pk_bf16_f32 v242, v34, v36
	ds_read2_b64 v[34:37], v129 offset0:168 offset1:170
	v_cvt_pk_bf16_f32 v41, v39, v41
	v_cvt_pk_bf16_f32 v40, v38, v40
	v_mov_b32_e32 v39, v241
	v_mov_b32_e32 v38, v242
	s_waitcnt lgkmcnt(0)
	s_nop 0
	v_mfma_f32_32x32x16_bf16 v[18:33], v[34:37], v[38:41], v[18:33]
	ds_read2_b64 v[34:37], v128 offset0:168 offset1:170
	ds_read2_b64 v[42:45], v129 offset0:172 offset1:174
	s_waitcnt lgkmcnt(0)
	v_mfma_f32_32x32x16_bf16 v[2:17], v[34:37], v[38:41], v[2:17]
	v_mul_f32_e64 v36, v68, v82
	v_mul_f32_e64 v37, v69, v83
	v_mul_f32_e64 v40, v72, v82
	v_mul_f32_e64 v41, v73, v83
	v_mul_f32_e64 v38, v70, v82
	v_mul_f32_e64 v39, v71, v83
	s_nop 0
	s_nop 0
	v_bfe_u32 v48, v37, 16, 1
	v_bfe_u32 v49, v36, 16, 1
	v_add3_u32 v49, v36, v49, s33
	v_add3_u32 v48, v37, v48, s33
	s_nop 0
	s_nop 0
	s_nop 0
	s_nop 0
	v_pk_mul_f32 v[34:35], v[66:67], v[82:83]
	s_nop 0
	s_nop 0
	v_cvt_pk_bf16_f32 v36, v38, v40
	v_bfe_u32 v40, v34, 16, 1
	v_cvt_pk_bf16_f32 v37, v39, v41
	v_bfe_u32 v41, v35, 16, 1
	v_add3_u32 v35, v35, v41, s33
	v_add3_u32 v34, v34, v40, s33
	ds_read2_b64 v[38:41], v128 offset0:172 offset1:174
	v_lshrrev_b32_e32 v34, 16, v34
	v_lshrrev_b32_e32 v35, 16, v35
	v_and_or_b32 v35, v48, s96, v35
	v_and_or_b32 v34, v49, s96, v34
	s_nop 1
	v_mfma_f32_32x32x16_bf16 v[18:33], v[42:45], v[34:37], v[18:33]
	s_waitcnt lgkmcnt(0)
	v_mfma_f32_32x32x16_bf16 v[2:17], v[38:41], v[34:37], v[2:17]

; #define LAS __attribute__((address_space(3)))
; #define LDS_WAIT() asm volatile("s_waitcnt lgkmcnt(0)" ::: "memory")
; __device__ __forceinline__ unsigned pk2(float lo, float hi) { return f2bf(lo) | (f2bf(hi) << 16); }
; __device__ __forceinline__ void transpose_item(const float* W, int K, int N, bf16* WT, LAS float* scr, int item, int lane, const float* kscale = nullptr) {
;     const int nblk = N / 32, kb = item / nblk, nb = item % nblk, k0 = 64 * kb, n0 = 32 * nb;
;     { f32x4 t[8]; float sc[8];
; #pragma unroll
;       for (int i = 0; i < 8; ++i) { const int kk = 8 * i + (lane >> 3); t[i] = *(const f32x4*)(W + (size_t)(k0 + kk) * N + n0 + 4 * (lane & 7)); sc[i] = kscale ? kscale[k0 + kk] : 1.0f; }
; #pragma unroll
;       for (int i = 0; i < 8; ++i) { const int kk = 8 * i + (lane >> 3); LAS float* d = scr + kk * 33 + 4 * (lane & 7); d[0] = t[i].x * sc[i]; d[1] = t[i].y * sc[i]; d[2] = t[i].z * sc[i]; d[3] = t[i].w * sc[i]; } }
;     LDS_WAIT(); asm volatile("" ::: "memory");
;     const int c = lane & 7;
; #pragma unroll
;     for (int j = 0; j < 4; ++j) { const int n = (lane >> 3) + 8 * j; const LAS float* s = scr + (8 * c) * 33 + n;
;         v4u o; o.x = pk2(s[0 * 33], s[1 * 33]); o.y = pk2(s[2 * 33], s[3 * 33]); o.z = pk2(s[4 * 33], s[5 * 33]); o.w = pk2(s[6 * 33], s[7 * 33]);
;         *(v4u*)(WT + (size_t)(n0 + n) * K + k0 + 8 * c) = o; }
;     LDS_WAIT(); asm volatile("" ::: "memory");
; __device__ __forceinline__ void phase_prologue(const Args& A, const Ctx& C0) {
;     ...
;         if (r < I_IN) { transpose_item(A.in[I_WIN] + (size_t)l * D * DIN, D, DIN, WS_PTR(bf16, WS_WINT) + (size_t)l * DINP * D, scr, r, C.lane, A.in[I_NORMW] + (size_t)l * D); continue; } r -= I_IN;
.LBB0_1314:
	s_waitcnt vmcnt(0)
	v_pk_mul_f32 v[2:3], v[2:3], v[44:45] op_sel_hi:[1,0]
	v_add_u32_e32 v48, v37, v39
	ds_write2_b32 v48, v2, v3 offset1:1
	v_pk_mul_f32 v[2:3], v[4:5], v[44:45] op_sel_hi:[1,0]
	ds_write2_b32 v48, v2, v3 offset0:2 offset1:3
	v_pk_mul_f32 v[2:3], v[6:7], v[0:1] op_sel_hi:[1,0]
	v_add_u32_e32 v4, 0x420, v48
	ds_write2_b32 v4, v2, v3 offset1:1
	v_pk_mul_f32 v[2:3], v[8:9], v[0:1] op_sel_hi:[1,0]
	v_add_u32_e32 v0, 0x428, v48
	ds_write2_b32 v0, v2, v3 offset1:1
	v_pk_mul_f32 v[2:3], v[10:11], v[50:51] op_sel_hi:[1,0]
	v_add_u32_e32 v0, 0x840, v48
	ds_write2_b32 v0, v2, v3 offset1:1
	v_pk_mul_f32 v[2:3], v[12:13], v[50:51] op_sel_hi:[1,0]
	v_add_u32_e32 v0, 0x848, v48
	ds_write2_b32 v0, v2, v3 offset1:1
	v_pk_mul_f32 v[2:3], v[14:15], v[46:47] op_sel_hi:[1,0]
	v_add_u32_e32 v0, 0xc60, v48
	ds_write2_b32 v0, v2, v3 offset1:1
	v_pk_mul_f32 v[2:3], v[16:17], v[46:47] op_sel_hi:[1,0]
	v_add_u32_e32 v0, 0xc68, v48
	ds_write2_b32 v0, v2, v3 offset1:1
	v_pk_mul_f32 v[2:3], v[18:19], v[54:55] op_sel_hi:[1,0]
	v_add_u32_e32 v0, 0x1080, v48
	ds_write2_b32 v0, v2, v3 offset1:1
	v_pk_mul_f32 v[2:3], v[20:21], v[54:55] op_sel_hi:[1,0]
	v_add_u32_e32 v0, 0x1088, v48
	ds_write2_b32 v0, v2, v3 offset1:1
	v_pk_mul_f32 v[2:3], v[22:23], v[52:53] op_sel_hi:[1,0]
	v_add_u32_e32 v0, 0x14a0, v48
	ds_write2_b32 v0, v2, v3 offset1:1
	v_pk_mul_f32 v[2:3], v[24:25], v[52:53] op_sel_hi:[1,0]
	v_add_u32_e32 v0, 0x14a8, v48
	ds_write2_b32 v0, v2, v3 offset1:1
	v_pk_mul_f32 v[2:3], v[26:27], v[58:59] op_sel_hi:[1,0]
	v_add_u32_e32 v0, 0x18c0, v48
	s_mul_i32 s1, s36, 0x1600000
	ds_write2_b32 v0, v2, v3 offset1:1
	v_pk_mul_f32 v[2:3], v[28:29], v[58:59] op_sel_hi:[1,0]
	v_add_u32_e32 v0, 0x18c8, v48
	s_mul_hi_i32 s0, s36, 0x1600000
	s_add_u32 s18, s13, s1
	ds_write2_b32 v0, v2, v3 offset1:1
	v_pk_mul_f32 v[2:3], v[30:31], v[56:57] op_sel_hi:[1,0]
	v_add_u32_e32 v0, 0x1ce0, v48
	s_addc_u32 s19, s14, s0
	ds_write2_b32 v0, v2, v3 offset1:1
	v_pk_mul_f32 v[2:3], v[32:33], v[56:57] op_sel_hi:[1,0]
	v_add_u32_e32 v0, 0x1ce8, v48
	s_ashr_i32 s41, s40, 31
	ds_write2_b32 v0, v2, v3 offset1:1
	s_lshl_b64 s[0:1], s[40:41], 1
	s_waitcnt lgkmcnt(0)
	s_add_u32 s0, s18, s0
	s_addc_u32 s1, s19, s1
	v_lshlrev_b32_e32 v0, 1, v42
	v_lshl_add_u64 v[6:7], s[0:1], 0, v[0:1]
	ds_read_b32 v0, v47
	ds_read_b32 v2, v47 offset:132
	ds_read_b32 v3, v47 offset:264
	ds_read_b32 v4, v47 offset:396
	ds_read_b32 v5, v47 offset:528
	ds_read_b32 v8, v47 offset:660
	ds_read_b32 v9, v47 offset:792
	ds_read_b32 v10, v47 offset:924
	s_waitcnt lgkmcnt(7)
	s_waitcnt lgkmcnt(6)
	v_cvt_pk_bf16_f32 v2, v0, v2
	s_waitcnt lgkmcnt(5)
	s_waitcnt lgkmcnt(4)
	v_cvt_pk_bf16_f32 v3, v3, v4
	s_waitcnt lgkmcnt(3)
	s_waitcnt lgkmcnt(2)
	v_cvt_pk_bf16_f32 v4, v5, v8
	s_waitcnt lgkmcnt(1)
	v_or_b32_e32 v8, s38, v35
	s_waitcnt lgkmcnt(0)
	v_cvt_pk_bf16_f32 v5, v9, v10
	v_ashrrev_i32_e32 v9, 31, v8
	v_lshlrev_b64 v[8:9], 12, v[8:9]
	v_lshl_add_u64 v[8:9], v[6:7], 0, v[8:9]
	flat_store_dwordx4 v[8:9], v[2:5]
	ds_read_b32 v0, v47 offset:32
	ds_read_b32 v2, v47 offset:164
	ds_read_b32 v3, v47 offset:296
	ds_read_b32 v4, v47 offset:428
	ds_read_b32 v5, v47 offset:560
	ds_read_b32 v8, v47 offset:692
	ds_read_b32 v9, v47 offset:824
	ds_read_b32 v10, v47 offset:956
	s_waitcnt lgkmcnt(0)
	v_cvt_pk_bf16_f32 v2, v0, v2
	v_cvt_pk_bf16_f32 v3, v3, v4
	v_cvt_pk_bf16_f32 v4, v5, v8
	v_or_b32_e32 v8, s38, v41
	v_cvt_pk_bf16_f32 v5, v9, v10
	v_ashrrev_i32_e32 v9, 31, v8
	v_lshlrev_b64 v[8:9], 12, v[8:9]
	v_lshl_add_u64 v[8:9], v[6:7], 0, v[8:9]
	flat_store_dwordx4 v[8:9], v[2:5]
	ds_read_b32 v0, v47 offset:64
	ds_read_b32 v2, v47 offset:196
	ds_read_b32 v3, v47 offset:328
	ds_read_b32 v4, v47 offset:460
	ds_read_b32 v5, v47 offset:592
	ds_read_b32 v8, v47 offset:724
	ds_read_b32 v9, v47 offset:856
	ds_read_b32 v10, v47 offset:988
	s_waitcnt lgkmcnt(0)
	v_cvt_pk_bf16_f32 v2, v0, v2
	v_cvt_pk_bf16_f32 v3, v3, v4
	v_cvt_pk_bf16_f32 v4, v5, v8
	v_or_b32_e32 v8, s38, v43
	v_cvt_pk_bf16_f32 v5, v9, v10
	v_ashrrev_i32_e32 v9, 31, v8
	v_lshlrev_b64 v[8:9], 12, v[8:9]
	v_lshl_add_u64 v[8:9], v[6:7], 0, v[8:9]
	flat_store_dwordx4 v[8:9], v[2:5]
	ds_read_b32 v0, v47 offset:96
	ds_read_b32 v2, v47 offset:228
	ds_read_b32 v3, v47 offset:360
	ds_read_b32 v4, v47 offset:492
	ds_read_b32 v5, v47 offset:624
	ds_read_b32 v8, v47 offset:756
	ds_read_b32 v9, v47 offset:888
	ds_read_b32 v10, v47 offset:1020
	s_waitcnt lgkmcnt(0)
	v_cvt_pk_bf16_f32 v2, v0, v2
	v_cvt_pk_bf16_f32 v3, v3, v4
	v_cvt_pk_bf16_f32 v4, v5, v8
	v_or_b32_e32 v8, s38, v45
	v_cvt_pk_bf16_f32 v5, v9, v10
	v_ashrrev_i32_e32 v9, 31, v8
	v_lshlrev_b64 v[8:9], 12, v[8:9]
	s_nop 0
	v_lshl_add_u64 v[6:7], v[6:7], 0, v[8:9]
	flat_store_dwordx4 v[6:7], v[2:5]
	s_waitcnt lgkmcnt(0)

; #define LAS __attribute__((address_space(3)))
; #define LDS_WAIT() asm volatile("s_waitcnt lgkmcnt(0)" ::: "memory")
; __device__ __forceinline__ unsigned pk2(float lo, float hi) { return f2bf(lo) | (f2bf(hi) << 16); }
; __device__ __forceinline__ void transpose_item(const float* W, int K, int N, bf16* WT, LAS float* scr, int item, int lane, const float* kscale = nullptr) {
;     const int nblk = N / 32, kb = item / nblk, nb = item % nblk, k0 = 64 * kb, n0 = 32 * nb;
;     { f32x4 t[8]; float sc[8];
; #pragma unroll
;       for (int i = 0; i < 8; ++i) { const int kk = 8 * i + (lane >> 3); t[i] = *(const f32x4*)(W + (size_t)(k0 + kk) * N + n0 + 4 * (lane & 7)); sc[i] = kscale ? kscale[k0 + kk] : 1.0f; }
; #pragma unroll
;       for (int i = 0; i < 8; ++i) { const int kk = 8 * i + (lane >> 3); LAS float* d = scr + kk * 33 + 4 * (lane & 7); d[0] = t[i].x * sc[i]; d[1] = t[i].y * sc[i]; d[2] = t[i].z * sc[i]; d[3] = t[i].w * sc[i]; } }
;     LDS_WAIT(); asm volatile("" ::: "memory");
;     const int c = lane & 7;
; #pragma unroll
;     for (int j = 0; j < 4; ++j) { const int n = (lane >> 3) + 8 * j; const LAS float* s = scr + (8 * c) * 33 + n;
;         v4u o; o.x = pk2(s[0 * 33], s[1 * 33]); o.y = pk2(s[2 * 33], s[3 * 33]); o.z = pk2(s[4 * 33], s[5 * 33]); o.w = pk2(s[6 * 33], s[7 * 33]);
;         *(v4u*)(WT + (size_t)(n0 + n) * K + k0 + 8 * c) = o; }
;     LDS_WAIT(); asm volatile("" ::: "memory");
; __device__ __forceinline__ void phase_prologue(const Args& A, const Ctx& C0) {
;     ...
;         { const int g = r >> 3; transpose_item(A.in[I_POOLW] + (size_t)(l * 4 + g) * 128 * 128, 128, 128, WS_PTR(bf16, WS_PWT) + (size_t)(l * 4 + g) * 128 * 128, scr, r & 7, C.lane); }
.LBB0_1318:
	s_cmpk_gt_u32 s18, 0x1d7f
	s_cbranch_scc0 .LBB0_1320
	s_add_i32 s0, s18, 0xffffe280
	s_lshr_b32 s0, s0, 3
	s_lshl_b32 s1, s36, 2
	s_add_i32 s0, s0, s1
	s_ashr_i32 s1, s0, 31
	v_readlane_b32 s40, v255, 4
	s_lshl_b64 s[30:31], s[0:1], 16
	v_readlane_b32 s44, v255, 8
	v_readlane_b32 s45, v255, 9
	s_add_u32 s19, s44, s30
	s_addc_u32 s27, s45, s31
	s_lshl_b64 s[0:1], s[0:1], 15
	s_add_u32 s37, s2, s0
	s_addc_u32 s1, s3, s1
	s_and_b32 s0, s18, 7
	s_add_i32 s30, s0, 0xfffc
	s_and_b32 s30, s30, 0xffff
	s_min_u32 s30, s0, s30
	s_cmp_gt_u32 s0, 3
	s_cselect_b32 s38, 64, 0
	s_lshl_b32 s0, s30, 5
	s_lshl_b32 s30, s30, 7
	s_add_u32 s30, s19, s30
	v_or_b32_e32 v4, s38, v35
	s_addc_u32 s31, s27, 0
	v_lshlrev_b32_e32 v0, 2, v40
	s_waitcnt lgkmcnt(0)
	v_lshl_add_u64 v[2:3], s[30:31], 0, v[0:1]
	v_lshlrev_b32_e32 v0, 9, v4
	v_lshl_add_u64 v[2:3], v[2:3], 0, v[0:1]
	s_movk_i32 s19, 0x2000
	v_add_co_u32_e32 v12, vcc, s19, v2
	s_movk_i32 s19, 0x4000
	s_nop 0
	v_addc_co_u32_e32 v13, vcc, 0, v3, vcc
	v_add_co_u32_e32 v20, vcc, s19, v2
	s_movk_i32 s19, 0x6000
	s_nop 0
	v_addc_co_u32_e32 v21, vcc, 0, v3, vcc
	v_add_co_u32_e32 v28, vcc, s19, v2
	global_load_dwordx4 v[4:7], v[2:3], off
	s_nop 0
	v_addc_co_u32_e32 v29, vcc, 0, v3, vcc
	global_load_dwordx4 v[8:11], v[12:13], off offset:-4096
	s_nop 0
	global_load_dwordx4 v[12:15], v[12:13], off
	s_nop 0
	global_load_dwordx4 v[16:19], v[20:21], off offset:-4096
	s_nop 0
	global_load_dwordx4 v[20:23], v[20:21], off
	s_nop 0
	global_load_dwordx4 v[24:27], v[28:29], off offset:-4096
	s_nop 0
	global_load_dwordx4 v[28:31], v[28:29], off
	s_movk_i32 s19, 0x7000
	v_add_co_u32_e32 v2, vcc, s19, v2
	v_add_u32_e32 v32, v37, v39
	s_nop 0
	v_addc_co_u32_e32 v3, vcc, 0, v3, vcc
	global_load_dwordx4 v[48:51], v[2:3], off
	v_add_u32_e32 v33, 0x420, v32
	v_add_u32_e32 v44, 0x428, v32
	v_add_u32_e32 v46, 0x840, v32
	v_add_u32_e32 v52, 0x848, v32
	v_add_u32_e32 v53, 0xc60, v32
	v_add_u32_e32 v54, 0xc68, v32
	v_add_u32_e32 v55, 0x1080, v32
	v_add_u32_e32 v56, 0x1088, v32
	v_add_u32_e32 v57, 0x14a0, v32
	v_add_u32_e32 v58, 0x14a8, v32
	v_add_u32_e32 v59, 0x18c0, v32
	v_add_u32_e32 v60, 0x18c8, v32
	v_add_u32_e32 v61, 0x1ce0, v32
	v_add_u32_e32 v62, 0x1ce8, v32
	s_lshl_b32 s19, s38, 1
	s_add_u32 s30, s37, s19
	s_addc_u32 s31, s1, 0
	v_lshlrev_b32_e32 v0, 1, v42
	v_lshl_add_u64 v[2:3], s[30:31], 0, v[0:1]
	v_readlane_b32 s41, v255, 5
	v_readlane_b32 s42, v255, 6
	v_readlane_b32 s43, v255, 7
	v_readlane_b32 s46, v255, 10
	v_readlane_b32 s47, v255, 11
	v_readlane_b32 s48, v255, 12
	v_readlane_b32 s49, v255, 13
	v_readlane_b32 s50, v255, 14
	v_readlane_b32 s51, v255, 15
	v_readlane_b32 s52, v255, 16
	v_readlane_b32 s53, v255, 17
	v_readlane_b32 s54, v255, 18
	v_readlane_b32 s55, v255, 19
	s_waitcnt vmcnt(0)
	ds_write2_b32 v32, v4, v5 offset1:1
	ds_write2_b32 v32, v6, v7 offset0:2 offset1:3
	ds_write2_b32 v33, v8, v9 offset1:1
	ds_write2_b32 v44, v10, v11 offset1:1
	ds_write2_b32 v46, v12, v13 offset1:1
	ds_write2_b32 v52, v14, v15 offset1:1
	ds_write2_b32 v53, v16, v17 offset1:1
	ds_write2_b32 v54, v18, v19 offset1:1
	ds_write2_b32 v55, v20, v21 offset1:1
	ds_write2_b32 v56, v22, v23 offset1:1
	ds_write2_b32 v57, v24, v25 offset1:1
	ds_write2_b32 v58, v26, v27 offset1:1
	ds_write2_b32 v59, v28, v29 offset1:1
	ds_write2_b32 v60, v30, v31 offset1:1
	ds_write2_b32 v61, v48, v49 offset1:1
	ds_write2_b32 v62, v50, v51 offset1:1
	s_waitcnt lgkmcnt(0)
	ds_read_b32 v0, v47
	ds_read_b32 v4, v47 offset:132
	ds_read_b32 v5, v47 offset:264
	ds_read_b32 v6, v47 offset:396
	ds_read_b32 v7, v47 offset:528
	ds_read_b32 v8, v47 offset:660
	ds_read_b32 v9, v47 offset:792
	ds_read_b32 v10, v47 offset:924
	s_waitcnt lgkmcnt(7)
	s_waitcnt lgkmcnt(6)
	s_waitcnt lgkmcnt(5)
	s_waitcnt lgkmcnt(3)
	s_waitcnt lgkmcnt(2)
	v_cvt_pk_bf16_f32 v4, v0, v4
	v_cvt_pk_bf16_f32 v5, v5, v6
	v_cvt_pk_bf16_f32 v6, v7, v8
	s_waitcnt lgkmcnt(1)
	s_waitcnt lgkmcnt(0)
	v_cvt_pk_bf16_f32 v7, v9, v10
	v_or_b32_e32 v0, s0, v35
	v_lshlrev_b32_e32 v0, 8, v0
	v_lshl_add_u64 v[8:9], v[2:3], 0, v[0:1]
	flat_store_dwordx4 v[8:9], v[4:7]
	ds_read_b32 v0, v47 offset:32
	ds_read_b32 v4, v47 offset:164
	ds_read_b32 v5, v47 offset:296
	ds_read_b32 v6, v47 offset:428
	ds_read_b32 v7, v47 offset:560
	ds_read_b32 v8, v47 offset:692
	ds_read_b32 v9, v47 offset:824
	ds_read_b32 v10, v47 offset:956
	s_waitcnt lgkmcnt(0)
	v_cvt_pk_bf16_f32 v4, v0, v4
	v_cvt_pk_bf16_f32 v5, v5, v6
	v_cvt_pk_bf16_f32 v6, v7, v8
	v_cvt_pk_bf16_f32 v7, v9, v10
	v_or_b32_e32 v0, s0, v41
	v_lshlrev_b32_e32 v0, 8, v0
	v_lshl_add_u64 v[8:9], v[2:3], 0, v[0:1]
	flat_store_dwordx4 v[8:9], v[4:7]
	ds_read_b32 v0, v47 offset:64
	ds_read_b32 v4, v47 offset:196
	ds_read_b32 v5, v47 offset:328
	ds_read_b32 v6, v47 offset:460
	ds_read_b32 v7, v47 offset:592
	ds_read_b32 v8, v47 offset:724
	ds_read_b32 v9, v47 offset:856
	ds_read_b32 v10, v47 offset:988
	s_waitcnt lgkmcnt(0)
	v_cvt_pk_bf16_f32 v4, v0, v4
	v_cvt_pk_bf16_f32 v5, v5, v6
	v_cvt_pk_bf16_f32 v6, v7, v8
	v_cvt_pk_bf16_f32 v7, v9, v10
	v_or_b32_e32 v0, s0, v43
	v_lshlrev_b32_e32 v0, 8, v0
	v_lshl_add_u64 v[8:9], v[2:3], 0, v[0:1]
	flat_store_dwordx4 v[8:9], v[4:7]
	ds_read_b32 v0, v47 offset:96
	ds_read_b32 v4, v47 offset:228
	ds_read_b32 v5, v47 offset:360
	ds_read_b32 v6, v47 offset:492
	ds_read_b32 v7, v47 offset:624
	ds_read_b32 v8, v47 offset:756
	ds_read_b32 v9, v47 offset:888
	ds_read_b32 v10, v47 offset:1020
	s_waitcnt lgkmcnt(0)
	v_cvt_pk_bf16_f32 v4, v0, v4
	v_cvt_pk_bf16_f32 v5, v5, v6
	v_cvt_pk_bf16_f32 v6, v7, v8
	v_cvt_pk_bf16_f32 v7, v9, v10
	v_or_b32_e32 v0, s0, v45
	v_lshlrev_b32_e32 v0, 8, v0
	v_lshl_add_u64 v[2:3], v[2:3], 0, v[0:1]
	flat_store_dwordx4 v[2:3], v[4:7]
	s_waitcnt lgkmcnt(0)
	s_mov_b64 s[0:1], 0
; #define LAS __attribute__((address_space(3)))
; #define LDS_WAIT() asm volatile("s_waitcnt lgkmcnt(0)" ::: "memory")
; __device__ __forceinline__ unsigned pk2(float lo, float hi) { return f2bf(lo) | (f2bf(hi) << 16); }
; __device__ __forceinline__ void transpose_item(const float* W, int K, int N, bf16* WT, LAS float* scr, int item, int lane, const float* kscale = nullptr) {
;     const int nblk = N / 32, kb = item / nblk, nb = item % nblk, k0 = 64 * kb, n0 = 32 * nb;
;     { f32x4 t[8]; float sc[8];
; #pragma unroll
;       for (int i = 0; i < 8; ++i) { const int kk = 8 * i + (lane >> 3); t[i] = *(const f32x4*)(W + (size_t)(k0 + kk) * N + n0 + 4 * (lane & 7)); sc[i] = kscale ? kscale[k0 + kk] : 1.0f; }
; #pragma unroll
;       for (int i = 0; i < 8; ++i) { const int kk = 8 * i + (lane >> 3); LAS float* d = scr + kk * 33 + 4 * (lane & 7); d[0] = t[i].x * sc[i]; d[1] = t[i].y * sc[i]; d[2] = t[i].z * sc[i]; d[3] = t[i].w * sc[i]; } }
;     LDS_WAIT(); asm volatile("" ::: "memory");
;     const int c = lane & 7;
; #pragma unroll
;     for (int j = 0; j < 4; ++j) { const int n = (lane >> 3) + 8 * j; const LAS float* s = scr + (8 * c) * 33 + n;
;         v4u o; o.x = pk2(s[0 * 33], s[1 * 33]); o.y = pk2(s[2 * 33], s[3 * 33]); o.z = pk2(s[4 * 33], s[5 * 33]); o.w = pk2(s[6 * 33], s[7 * 33]);
;         *(v4u*)(WT + (size_t)(n0 + n) * K + k0 + 8 * c) = o; }
;     LDS_WAIT(); asm volatile("" ::: "memory");
; __device__ __forceinline__ void phase_prologue(const Args& A, const Ctx& C0) {
;     ...
;         if (r < I_OUT) { transpose_item(A.in[I_WOUT] + (size_t)l * D * D, D, D, WS_PTR(bf16, WS_WOUTT) + (size_t)l * D * D, scr, r, C.lane); continue; } r -= I_OUT;
.LBB0_1320:
	s_andn2_b64 vcc, exec, s[0:1]
	s_cbranch_vccnz .LBB0_1322
	s_ashr_i32 s37, s36, 31
	v_readlane_b32 s40, v255, 4
	s_lshl_b64 s[0:1], s[36:37], 24
	v_readlane_b32 s42, v255, 6
	v_readlane_b32 s43, v255, 7
	s_add_u32 s19, s42, s0
	s_addc_u32 s27, s43, s1
	s_lshl_b64 s[0:1], s[36:37], 23
	s_add_u32 s37, s11, s0
	s_addc_u32 s1, s12, s1
	s_add_i32 s0, s18, 0xea80
	s_and_b32 s38, s0, 0xffc0
	s_lshl_b32 s0, s36, 10
	s_sub_i32 s0, s15, s0
	s_and_b32 s0, s0, 0x7e0
	s_lshl_b32 s30, s0, 2
	s_add_u32 s30, s19, s30
	v_or_b32_e32 v4, s38, v35
	s_addc_u32 s31, s27, 0
	v_lshlrev_b32_e32 v0, 2, v40
	s_waitcnt lgkmcnt(0)
	v_lshl_add_u64 v[2:3], s[30:31], 0, v[0:1]
	v_lshlrev_b32_e32 v0, 13, v4
	v_lshl_add_u64 v[2:3], v[2:3], 0, v[0:1]
	s_mov_b32 s19, 0x10000
	v_add_co_u32_e32 v8, vcc, s19, v2
	s_mov_b32 s19, 0x20000
	s_nop 0
	v_addc_co_u32_e32 v9, vcc, 0, v3, vcc
	v_add_co_u32_e32 v12, vcc, s19, v2
	s_mov_b32 s19, 0x30000
	s_nop 0
	v_addc_co_u32_e32 v13, vcc, 0, v3, vcc
	v_add_co_u32_e32 v16, vcc, s19, v2
	s_mov_b32 s19, 0x40000
	s_nop 0
	v_addc_co_u32_e32 v17, vcc, 0, v3, vcc
	v_add_co_u32_e32 v20, vcc, s19, v2
	s_mov_b32 s19, 0x50000
	s_nop 0
	v_addc_co_u32_e32 v21, vcc, 0, v3, vcc
	v_add_co_u32_e32 v24, vcc, s19, v2
	global_load_dwordx4 v[4:7], v[2:3], off
	s_nop 0
	global_load_dwordx4 v[8:11], v[8:9], off
	v_addc_co_u32_e32 v25, vcc, 0, v3, vcc
	global_load_dwordx4 v[12:15], v[12:13], off
	s_nop 0
	global_load_dwordx4 v[16:19], v[16:17], off
	s_nop 0
	global_load_dwordx4 v[20:23], v[20:21], off
	s_nop 0
	global_load_dwordx4 v[24:27], v[24:25], off
	s_mov_b32 s19, 0x60000
	v_add_co_u32_e32 v28, vcc, s19, v2
	s_mov_b32 s19, 0x70000
	s_nop 0
	v_addc_co_u32_e32 v29, vcc, 0, v3, vcc
	global_load_dwordx4 v[28:31], v[28:29], off
	v_add_co_u32_e32 v2, vcc, s19, v2
	v_add_u32_e32 v32, v37, v39
	s_nop 0
	v_addc_co_u32_e32 v3, vcc, 0, v3, vcc
	global_load_dwordx4 v[48:51], v[2:3], off
	v_add_u32_e32 v33, 0x420, v32
	v_add_u32_e32 v44, 0x428, v32
	v_add_u32_e32 v46, 0x840, v32
	v_add_u32_e32 v52, 0x848, v32
	v_add_u32_e32 v53, 0xc60, v32
	v_add_u32_e32 v54, 0xc68, v32
	v_add_u32_e32 v55, 0x1080, v32
	v_add_u32_e32 v56, 0x1088, v32
	v_add_u32_e32 v57, 0x14a0, v32
	v_add_u32_e32 v58, 0x14a8, v32
	v_add_u32_e32 v59, 0x18c0, v32
	v_add_u32_e32 v60, 0x18c8, v32
	v_add_u32_e32 v61, 0x1ce0, v32
	v_add_u32_e32 v62, 0x1ce8, v32
	s_lshl_b32 s19, s38, 1
	s_add_u32 s30, s37, s19
	s_addc_u32 s31, s1, 0
	v_lshlrev_b32_e32 v0, 1, v42
	v_lshl_add_u64 v[2:3], s[30:31], 0, v[0:1]
	v_readlane_b32 s41, v255, 5
	v_readlane_b32 s44, v255, 8
	v_readlane_b32 s45, v255, 9
	v_readlane_b32 s46, v255, 10
	v_readlane_b32 s47, v255, 11
	v_readlane_b32 s48, v255, 12
	v_readlane_b32 s49, v255, 13
	v_readlane_b32 s50, v255, 14
	v_readlane_b32 s51, v255, 15
	v_readlane_b32 s52, v255, 16
	v_readlane_b32 s53, v255, 17
	v_readlane_b32 s54, v255, 18
	v_readlane_b32 s55, v255, 19
	s_waitcnt vmcnt(0)
	ds_write2_b32 v32, v4, v5 offset1:1
	ds_write2_b32 v32, v6, v7 offset0:2 offset1:3
	ds_write2_b32 v33, v8, v9 offset1:1
	ds_write2_b32 v44, v10, v11 offset1:1
	ds_write2_b32 v46, v12, v13 offset1:1
	ds_write2_b32 v52, v14, v15 offset1:1
	ds_write2_b32 v53, v16, v17 offset1:1
	ds_write2_b32 v54, v18, v19 offset1:1
	ds_write2_b32 v55, v20, v21 offset1:1
	ds_write2_b32 v56, v22, v23 offset1:1
	ds_write2_b32 v57, v24, v25 offset1:1
	ds_write2_b32 v58, v26, v27 offset1:1
	ds_write2_b32 v59, v28, v29 offset1:1
	ds_write2_b32 v60, v30, v31 offset1:1
	ds_write2_b32 v61, v48, v49 offset1:1
	ds_write2_b32 v62, v50, v51 offset1:1
	s_waitcnt lgkmcnt(0)
	ds_read_b32 v0, v47
	ds_read_b32 v4, v47 offset:132
	ds_read_b32 v5, v47 offset:264
	ds_read_b32 v6, v47 offset:396
	ds_read_b32 v7, v47 offset:528
	ds_read_b32 v8, v47 offset:660
	ds_read_b32 v9, v47 offset:792
	ds_read_b32 v10, v47 offset:924
	s_waitcnt lgkmcnt(7)
	s_waitcnt lgkmcnt(6)
	v_cvt_pk_bf16_f32 v4, v0, v4
	s_waitcnt lgkmcnt(5)
	s_waitcnt lgkmcnt(4)
	v_cvt_pk_bf16_f32 v5, v5, v6
	s_waitcnt lgkmcnt(3)
	s_waitcnt lgkmcnt(2)
	v_cvt_pk_bf16_f32 v6, v7, v8
	s_waitcnt lgkmcnt(1)
	s_waitcnt lgkmcnt(0)
	v_cvt_pk_bf16_f32 v7, v9, v10
	v_or_b32_e32 v0, s0, v35
	v_lshlrev_b32_e32 v0, 12, v0
	v_lshl_add_u64 v[8:9], v[2:3], 0, v[0:1]
	flat_store_dwordx4 v[8:9], v[4:7]
	ds_read_b32 v0, v47 offset:32
	ds_read_b32 v4, v47 offset:164
	ds_read_b32 v5, v47 offset:296
	ds_read_b32 v6, v47 offset:428
	ds_read_b32 v7, v47 offset:560
	ds_read_b32 v8, v47 offset:692
	ds_read_b32 v9, v47 offset:824
	ds_read_b32 v10, v47 offset:956
	s_waitcnt lgkmcnt(0)
	v_cvt_pk_bf16_f32 v4, v0, v4
	v_cvt_pk_bf16_f32 v5, v5, v6
	v_cvt_pk_bf16_f32 v6, v7, v8
	v_cvt_pk_bf16_f32 v7, v9, v10
	v_or_b32_e32 v0, s0, v41
	v_lshlrev_b32_e32 v0, 12, v0
	v_lshl_add_u64 v[8:9], v[2:3], 0, v[0:1]
	flat_store_dwordx4 v[8:9], v[4:7]
	ds_read_b32 v0, v47 offset:64
	ds_read_b32 v4, v47 offset:196
	ds_read_b32 v5, v47 offset:328
	ds_read_b32 v6, v47 offset:460
	ds_read_b32 v7, v47 offset:592
	ds_read_b32 v8, v47 offset:724
	ds_read_b32 v9, v47 offset:856
	ds_read_b32 v10, v47 offset:988
	s_waitcnt lgkmcnt(0)
	v_cvt_pk_bf16_f32 v4, v0, v4
	v_cvt_pk_bf16_f32 v5, v5, v6
	v_cvt_pk_bf16_f32 v6, v7, v8
	v_cvt_pk_bf16_f32 v7, v9, v10
	v_or_b32_e32 v0, s0, v43
	v_lshlrev_b32_e32 v0, 12, v0
	v_lshl_add_u64 v[8:9], v[2:3], 0, v[0:1]
	flat_store_dwordx4 v[8:9], v[4:7]
	ds_read_b32 v0, v47 offset:96
	ds_read_b32 v4, v47 offset:228
	ds_read_b32 v5, v47 offset:360
	ds_read_b32 v6, v47 offset:492
	ds_read_b32 v7, v47 offset:624
	ds_read_b32 v8, v47 offset:756
	ds_read_b32 v9, v47 offset:888
	ds_read_b32 v10, v47 offset:1020
	s_waitcnt lgkmcnt(0)
	v_cvt_pk_bf16_f32 v4, v0, v4
	v_cvt_pk_bf16_f32 v5, v5, v6
	v_cvt_pk_bf16_f32 v6, v7, v8
	v_cvt_pk_bf16_f32 v7, v9, v10
	v_or_b32_e32 v0, s0, v45
	v_lshlrev_b32_e32 v0, 12, v0
	v_lshl_add_u64 v[2:3], v[2:3], 0, v[0:1]
	flat_store_dwordx4 v[2:3], v[4:7]
	s_waitcnt lgkmcnt(0)
